# previous + non-temporal (nt) hint on the once-read f32 weight loads and bf16 stores of the weight-conversion loops
# speedup vs baseline: 1.0222x; 1.0051x over previous
; DI int otid() { int t = threadIdx.x; asm volatile("" : "+v"(t)); return t; }
; DI int obid() { int t = blockIdx.x; asm volatile("" : "+s"(t)); return t; }
; DI int ogrid() { int t = gridDim.x; asm volatile("" : "+s"(t)); return t; }
; DI CvTile cv_tile(const Job* jobs, int t, int c0, int c1) {
;   CvTile r; r.valid = t < c1; r.pad = 0;
;   int j = 0, tt = r.valid ? t : c0;
;   while (tt >= jobs[j].tiles) { tt -= jobs[j].tiles; ++j; }
;   const Job jb = jobs[j];
;   const int tk = jb.K >> 6, tn = jb.N >> 6, per = tk * tn;
;   const int bi = tt / per, rr = tt % per, kt = rr % tk, nt = rr / tk;
;   r.src = jb.src + (size_t)bi * jb.ss + (size_t)(kt * 64) * jb.N + nt * 64;
;   r.dst = jb.dst + (size_t)bi * jb.ds + (size_t)(nt * 64) * jb.K + kt * 64;
;   r.N = jb.N; r.K = jb.K;
;   return r;
; }
;   if (c0 >= c1) return;
;   const int tid = otid(), G = widx < 0 ? ogrid() : wn, b = widx < 0 ? obid() : widx;
;   float* smf = (float*)smraw;
;   const int half = tid >> 8, vt = tid & 255;
;   float* smh = smf + half * (64 * 65);
;   const int kr = vt >> 4, nc = (vt & 15) * 4;
;   int t0 = c0 + b * 2;
;   if (t0 >= c1) { __syncthreads(); return; }
;   CvTile cur = cv_tile(g_jobs, t0 + half, c0, c1);
;   float4 v[4];
; #pragma unroll
;   for (int i = 0; i < 4; ++i) v[i] = *(const float4*)(cur.src + (size_t)(kr + 16 * i) * cur.N + nc);
.LBB0_45:
	s_or_b64 exec, exec, s[6:7]
	ds_read2_b64 v[18:21], v1 offset1:1
	ds_read_b64 v[42:43], v1 offset:16
	v_lshlrev_b32_e32 v2, 2, v16
	v_and_b32_e32 v26, 60, v2
	v_sub_u32_e32 v6, 0, v0
	v_max_i32_e32 v6, v0, v6
	s_waitcnt lgkmcnt(0)
	v_ashrrev_i32_e32 v2, 6, v43
	v_ashrrev_i32_e32 v3, 6, v42
	v_mul_lo_u32 v2, v3, v2
	v_sub_u32_e32 v4, 0, v2
	v_max_i32_e32 v4, v2, v4
	v_cvt_f32_u32_e32 v5, v4
	v_sub_u32_e32 v7, 0, v4
	ds_read2_b64 v[22:25], v1 offset0:4 offset1:5
	v_xor_b32_e32 v1, v0, v2
	v_rcp_iflag_f32_e32 v5, v5
	v_ashrrev_i32_e32 v1, 31, v1
	v_bfe_u32 v32, v16, 4, 4
	v_mov_b32_e32 v35, 0
	v_mul_f32_e32 v5, 0x4f7ffffe, v5
	v_cvt_u32_f32_e32 v5, v5
	v_or_b32_e32 v40, 48, v32
	v_lshlrev_b32_e32 v34, 2, v26
	v_or_b32_e32 v38, 32, v32
	v_mul_lo_u32 v7, v7, v5
	v_mul_hi_u32 v7, v5, v7
	v_add_u32_e32 v5, v5, v7
	v_mul_hi_u32 v5, v6, v5
	v_mul_lo_u32 v7, v5, v4
	v_sub_u32_e32 v6, v6, v7
	v_add_u32_e32 v7, 1, v5
	v_cmp_ge_u32_e64 s[4:5], v6, v4
	v_or_b32_e32 v36, 16, v32
	v_bfe_u32 v44, v16, 2, 6
	v_cndmask_b32_e64 v5, v5, v7, s[4:5]
	v_sub_u32_e32 v7, v6, v4
	v_cndmask_b32_e64 v6, v6, v7, s[4:5]
	v_add_u32_e32 v7, 1, v5
	v_cmp_ge_u32_e64 s[4:5], v6, v4
	v_cndmask_b32_e64 v45, 0, 1, vcc
	s_lshl_b32 s13, s10, 1
	v_cndmask_b32_e64 v4, v5, v7, s[4:5]
	v_sub_u32_e32 v5, 0, v3
	v_max_i32_e32 v5, v3, v5
	v_cvt_f32_u32_e32 v6, v5
	v_xor_b32_e32 v4, v4, v1
	v_sub_u32_e32 v17, v4, v1
	v_mul_lo_u32 v1, v17, v2
	v_rcp_iflag_f32_e32 v2, v6
	v_sub_u32_e32 v6, 0, v5
	v_sub_u32_e32 v0, v0, v1
	v_sub_u32_e32 v4, 0, v0
	v_mul_f32_e32 v2, 0x4f7ffffe, v2
	v_cvt_u32_f32_e32 v2, v2
	v_max_i32_e32 v4, v0, v4
	v_xor_b32_e32 v1, v0, v3
	v_ashrrev_i32_e32 v1, 31, v1
	v_mul_lo_u32 v6, v6, v2
	v_mul_hi_u32 v6, v2, v6
	v_add_u32_e32 v2, v2, v6
	v_mul_hi_u32 v2, v4, v2
	v_mul_lo_u32 v6, v2, v5
	v_sub_u32_e32 v4, v4, v6
	v_add_u32_e32 v6, 1, v2
	v_cmp_ge_u32_e64 s[4:5], v4, v5
	v_ashrrev_i32_e32 v27, 31, v17
	s_waitcnt lgkmcnt(0)
	v_mul_lo_u32 v25, v25, v17
	v_cndmask_b32_e64 v2, v2, v6, s[4:5]
	v_sub_u32_e32 v6, v4, v5
	v_cndmask_b32_e64 v4, v4, v6, s[4:5]
	v_add_u32_e32 v6, 1, v2
	v_cmp_ge_u32_e64 s[4:5], v4, v5
	s_movk_i32 s14, 0x400
	v_mov_b32_e32 v41, 0x2401c
	v_cndmask_b32_e64 v2, v2, v6, s[4:5]
	v_xor_b32_e32 v2, v2, v1
	v_sub_u32_e32 v1, v2, v1
	v_lshlrev_b32_e32 v28, 6, v1
	v_mul_lo_u32 v1, v1, v3
	v_sub_u32_e32 v0, v0, v1
	v_lshlrev_b32_e32 v30, 6, v0
	v_mul_lo_u32 v2, v22, v27
	v_mul_lo_u32 v3, v23, v17
	v_mad_u64_u32 v[0:1], s[4:5], v22, v17, 0
	v_add3_u32 v1, v1, v2, v3
	v_lshl_add_u64 v[0:1], v[0:1], 2, v[18:19]
	v_mad_i64_i32 v[2:3], s[4:5], v30, v43, 0
	v_ashrrev_i32_e32 v29, 31, v28
	v_lshl_add_u64 v[0:1], v[2:3], 2, v[0:1]
	v_lshl_add_u64 v[0:1], v[28:29], 2, v[0:1]
	v_lshl_add_u64 v[8:9], v[0:1], 0, v[34:35]
	v_mad_i64_i32 v[0:1], s[4:5], v43, v40, 0
	v_lshl_add_u64 v[10:11], v[0:1], 2, v[8:9]
	v_mad_i64_i32 v[0:1], s[4:5], v43, v38, 0
	v_lshl_add_u64 v[12:13], v[0:1], 2, v[8:9]
	flat_load_dwordx4 v[0:3], v[10:11] nt
	flat_load_dwordx4 v[4:7], v[12:13] nt
	v_mad_i64_i32 v[10:11], s[4:5], v43, v36, 0
	v_lshl_add_u64 v[18:19], v[10:11], 2, v[8:9]
	v_mad_i64_i32 v[10:11], s[4:5], v43, v32, 0
	v_lshl_add_u64 v[22:23], v[10:11], 2, v[8:9]
	flat_load_dwordx4 v[8:11], v[18:19] nt
	flat_load_dwordx4 v[12:15], v[22:23] nt
	v_mul_lo_u32 v23, v24, v27
	v_mad_u64_u32 v[18:19], s[4:5], v24, v17, 0
	v_add3_u32 v19, v19, v23, v25
	v_lshl_add_u64 v[18:19], v[18:19], 1, v[20:21]
	v_mad_i64_i32 v[20:21], s[4:5], v28, v42, 0
	v_lshl_add_u64 v[18:19], v[20:21], 1, v[18:19]
	v_ashrrev_i32_e32 v31, 31, v30
	v_lshl_add_u64 v[46:47], v[30:31], 1, v[18:19]
	v_lshlrev_b32_e32 v18, 4, v16
	v_and_b32_e32 v18, 48, v18
	v_mul_i32_i24_e32 v22, 0x4100, v33
	v_and_b32_e32 v16, 0xfc, v16
	v_mul_u32_u24_e32 v21, 0x41, v18
	v_or_b32_e32 v17, v22, v34
	v_or_b32_e32 v19, v22, v16
	v_mul_u32_u24_e32 v20, 0x104, v32
	v_lshlrev_b32_e32 v21, 2, v21
	v_add_u32_e32 v37, v19, v21
	v_add3_u32 v39, v22, v21, v16
	v_lshlrev_b32_e32 v34, 2, v26
	v_add_u32_e32 v43, v17, v20
	v_lshlrev_b32_e32 v48, 1, v18
	v_mov_b32_e32 v51, v45
	v_mov_b64_e32 v[52:53], v[46:47]
	s_branch .LBB0_47

; DI int otid() { int t = threadIdx.x; asm volatile("" : "+v"(t)); return t; }
; DI int obid() { int t = blockIdx.x; asm volatile("" : "+s"(t)); return t; }
; DI int ogrid() { int t = gridDim.x; asm volatile("" : "+s"(t)); return t; }
; DI unsigned pack2(float a, float b) { unsigned r; asm("v_cvt_pk_bf16_f32 %0, %1, %2" : "=v"(r) : "v"(a), "v"(b)); return r; }
; DI CvTile cv_tile(const Job* jobs, int t, int c0, int c1) {
;   CvTile r; r.valid = t < c1; r.pad = 0;
;   int j = 0, tt = r.valid ? t : c0;
;   while (tt >= jobs[j].tiles) { tt -= jobs[j].tiles; ++j; }
;   const Job jb = jobs[j];
;   const int tk = jb.K >> 6, tn = jb.N >> 6, per = tk * tn;
;   const int bi = tt / per, rr = tt % per, kt = rr % tk, nt = rr / tk;
;   r.src = jb.src + (size_t)bi * jb.ss + (size_t)(kt * 64) * jb.N + nt * 64;
;   r.dst = jb.dst + (size_t)bi * jb.ds + (size_t)(nt * 64) * jb.K + kt * 64;
;   r.N = jb.N; r.K = jb.K;
;   return r;
; }
;   if (c0 >= c1) return;
;   const int tid = otid(), G = widx < 0 ? ogrid() : wn, b = widx < 0 ? obid() : widx;
;   float* smf = (float*)smraw;
;   const int half = tid >> 8, vt = tid & 255;
;   float* smh = smf + half * (64 * 65);
;   const int kr = vt >> 4, nc = (vt & 15) * 4;
;   int t0 = c0 + b * 2;
;   if (t0 >= c1) { __syncthreads(); return; }
;   CvTile cur = cv_tile(g_jobs, t0 + half, c0, c1);
;   float4 v[4];
; #pragma unroll
;   for (int i = 0; i < 4; ++i) v[i] = *(const float4*)(cur.src + (size_t)(kr + 16 * i) * cur.N + nc);
;   for (; t0 < c1; t0 += 2 * G) {
;     const bool more = t0 + 2 * G < c1;
;     CvTile nx = cur; float4 vn[4];
;     if (more) {
;       nx = cv_tile(g_jobs, t0 + 2 * G + half, c0, c1);
; #pragma unroll
;       for (int i = 0; i < 4; ++i) vn[i] = *(const float4*)(nx.src + (size_t)(kr + 16 * i) * nx.N + nc);
;     }
;     __syncthreads();
; #pragma unroll
;     for (int i = 0; i < 4; ++i) { float* d = smh + (kr + 16 * i) * 65 + nc; d[0] = v[i].x; d[1] = v[i].y; d[2] = v[i].z; d[3] = v[i].w; }
;     __syncthreads();
;     if (cur.valid) {
;       const int n = vt >> 2, kp = (vt & 3) * 16;
;       unsigned o[8];
; #pragma unroll
;       for (int q = 0; q < 8; ++q) o[q] = pack2(smh[(kp + 2 * q) * 65 + n], smh[(kp + 2 * q + 1) * 65 + n]);
;       uint4* d4 = (uint4*)(cur.dst + (size_t)n * cur.K + kp);
;       d4[0] = make_uint4(o[0], o[1], o[2], o[3]); d4[1] = make_uint4(o[4], o[5], o[6], o[7]);
.LBB0_52:
	s_or_b64 exec, exec, s[8:9]
	ds_read_b64 v[50:51], v18 offset:16
	ds_read2_b64 v[52:55], v18 offset1:1
	ds_read2_b64 v[56:59], v18 offset0:4 offset1:5
	v_sub_u32_e32 v18, 0, v16
	v_max_i32_e32 v18, v16, v18
	s_waitcnt lgkmcnt(0)
	v_ashrrev_i32_e32 v17, 6, v50
	v_ashrrev_i32_e32 v19, 6, v51
	v_mul_lo_u32 v19, v19, v17
	v_sub_u32_e32 v20, 0, v19
	v_max_i32_e32 v20, v19, v20
	v_cvt_f32_u32_e32 v21, v20
	v_sub_u32_e32 v23, 0, v20
	v_xor_b32_e32 v22, v16, v19
	v_ashrrev_i32_e32 v22, 31, v22
	v_rcp_iflag_f32_e32 v21, v21
	s_nop 0
	v_mul_f32_e32 v21, 0x4f7ffffe, v21
	v_cvt_u32_f32_e32 v21, v21
	v_mul_lo_u32 v23, v23, v21
	v_mul_hi_u32 v23, v21, v23
	v_add_u32_e32 v21, v21, v23
	v_mul_hi_u32 v21, v18, v21
	v_mul_lo_u32 v23, v21, v20
	v_sub_u32_e32 v18, v18, v23
	v_cmp_ge_u32_e64 s[4:5], v18, v20
	v_sub_u32_e32 v23, v18, v20
	v_add_u32_e32 v24, 1, v21
	v_cndmask_b32_e64 v18, v18, v23, s[4:5]
	v_cndmask_b32_e64 v21, v21, v24, s[4:5]
	v_cmp_ge_u32_e64 s[4:5], v18, v20
	v_sub_u32_e32 v20, 0, v17
	v_add_u32_e32 v23, 1, v21
	v_max_i32_e32 v20, v17, v20
	v_cndmask_b32_e64 v18, v21, v23, s[4:5]
	v_cvt_f32_u32_e32 v21, v20
	v_xor_b32_e32 v18, v18, v22
	v_sub_u32_e32 v49, v18, v22
	v_mul_lo_u32 v18, v49, v19
	v_rcp_iflag_f32_e32 v19, v21
	v_sub_u32_e32 v22, 0, v20
	v_sub_u32_e32 v16, v16, v18
	v_sub_u32_e32 v21, 0, v16
	v_mul_f32_e32 v19, 0x4f7ffffe, v19
	v_cvt_u32_f32_e32 v19, v19
	v_max_i32_e32 v21, v16, v21
	v_xor_b32_e32 v18, v16, v17
	v_ashrrev_i32_e32 v18, 31, v18
	v_mul_lo_u32 v22, v22, v19
	v_mul_hi_u32 v22, v19, v22
	v_add_u32_e32 v19, v19, v22
	v_mul_hi_u32 v19, v21, v19
	v_mul_lo_u32 v22, v19, v20
	v_sub_u32_e32 v21, v21, v22
	v_add_u32_e32 v22, 1, v19
	v_cmp_ge_u32_e64 s[4:5], v21, v20
	v_ashrrev_i32_e32 v64, 31, v49
	s_nop 0
	v_cndmask_b32_e64 v19, v19, v22, s[4:5]
	v_sub_u32_e32 v22, v21, v20
	v_cndmask_b32_e64 v21, v21, v22, s[4:5]
	v_add_u32_e32 v22, 1, v19
	v_cmp_ge_u32_e64 s[4:5], v21, v20
	v_mul_lo_u32 v21, v57, v49
	s_nop 0
	v_cndmask_b32_e64 v19, v19, v22, s[4:5]
	v_xor_b32_e32 v19, v19, v18
	v_sub_u32_e32 v20, v19, v18
	v_mul_lo_u32 v17, v20, v17
	v_sub_u32_e32 v18, v16, v17
	v_mul_lo_u32 v19, v56, v64
	v_mad_u64_u32 v[16:17], s[4:5], v56, v49, 0
	v_add3_u32 v17, v17, v19, v21
	v_lshl_add_u64 v[16:17], v[16:17], 2, v[52:53]
	v_lshlrev_b32_e32 v52, 6, v18
	v_mad_i64_i32 v[18:19], s[4:5], v52, v51, 0
	v_lshlrev_b32_e32 v56, 6, v20
	v_lshl_add_u64 v[16:17], v[18:19], 2, v[16:17]
	v_ashrrev_i32_e32 v57, 31, v56
	v_lshl_add_u64 v[16:17], v[56:57], 2, v[16:17]
	v_lshl_add_u64 v[24:25], v[16:17], 0, v[34:35]
	v_mad_i64_i32 v[16:17], s[4:5], v51, v32, 0
	v_lshl_add_u64 v[26:27], v[16:17], 2, v[24:25]
	v_mad_i64_i32 v[16:17], s[4:5], v51, v36, 0
	v_lshl_add_u64 v[28:29], v[16:17], 2, v[24:25]
	flat_load_dwordx4 v[16:19], v[26:27] nt
	flat_load_dwordx4 v[20:23], v[28:29] nt
	v_mad_i64_i32 v[26:27], s[4:5], v51, v38, 0
	v_lshl_add_u64 v[60:61], v[26:27], 2, v[24:25]
	v_mad_i64_i32 v[26:27], s[4:5], v51, v40, 0
	v_lshl_add_u64 v[62:63], v[26:27], 2, v[24:25]
	flat_load_dwordx4 v[24:27], v[60:61] nt
	flat_load_dwordx4 v[28:31], v[62:63] nt
	v_mul_lo_u32 v51, v58, v64
	v_mul_lo_u32 v57, v59, v49
	v_mad_u64_u32 v[58:59], s[4:5], v58, v49, 0
	v_add3_u32 v59, v59, v51, v57
	v_lshl_add_u64 v[54:55], v[58:59], 1, v[54:55]
	v_mad_i64_i32 v[56:57], s[4:5], v56, v50, 0
	v_ashrrev_i32_e32 v53, 31, v52
	v_lshl_add_u64 v[54:55], v[56:57], 1, v[54:55]
	v_cndmask_b32_e64 v51, 0, 1, vcc
	v_lshl_add_u64 v[52:53], v[52:53], 1, v[54:55]
.LBB0_53:
	s_waitcnt lgkmcnt(0)
	s_barrier
	s_waitcnt vmcnt(0)
	ds_write2_b32 v43, v12, v13 offset1:1
	ds_write2_b32 v43, v14, v15 offset0:2 offset1:3
	v_add_u32_e32 v12, 0x1040, v43
	ds_write2_b32 v12, v8, v9 offset1:1
	v_add_u32_e32 v8, 0x1048, v43
	ds_write2_b32 v8, v10, v11 offset1:1
	v_add_u32_e32 v8, 0x2080, v43
	ds_write2_b32 v8, v4, v5 offset1:1
	v_add_u32_e32 v4, 0x2088, v43
	ds_write2_b32 v4, v6, v7 offset1:1
	v_add_u32_e32 v4, 0x30c0, v43
	ds_write2_b32 v4, v0, v1 offset1:1
	v_add_u32_e32 v0, 0x30c8, v43
	v_cmp_ne_u32_e32 vcc, 0, v45
	ds_write2_b32 v0, v2, v3 offset1:1
	s_waitcnt lgkmcnt(0)
	s_barrier
	s_and_saveexec_b64 s[4:5], vcc
	s_cbranch_execz .LBB0_46
	ds_read2_b32 v[0:1], v37 offset1:130
	ds_read2_b32 v[2:3], v39 offset0:65 offset1:195
	v_add_u32_e32 v4, 0x400, v37
	v_add_u32_e32 v8, 0x800, v39
	ds_read2_b32 v[4:5], v4 offset0:4 offset1:134
	v_add_u32_e32 v6, 0x800, v37
	s_waitcnt lgkmcnt(1)
	v_cvt_pk_bf16_f32 v0, v0, v2
	v_add_u32_e32 v2, 0x400, v39
	v_cvt_pk_bf16_f32 v1, v1, v3
	ds_read2_b32 v[2:3], v2 offset0:69 offset1:199
	ds_read2_b32 v[8:9], v8 offset0:73 offset1:203
	ds_read2_b32 v[6:7], v6 offset0:8 offset1:138
	s_waitcnt lgkmcnt(2)
	v_cvt_pk_bf16_f32 v2, v4, v2
	v_cvt_pk_bf16_f32 v3, v5, v3
	s_waitcnt lgkmcnt(0)
	v_cvt_pk_bf16_f32 v4, v6, v8
	v_cvt_pk_bf16_f32 v5, v7, v9
	v_mad_i64_i32 v[8:9], s[8:9], v42, v44, 0
	v_lshl_add_u64 v[8:9], v[8:9], 1, v[46:47]
	v_mov_b32_e32 v49, v35
	v_add_u32_e32 v10, 0xc00, v37
	v_add_u32_e32 v12, 0xc00, v39
	v_lshl_add_u64 v[8:9], v[8:9], 0, v[48:49]
	ds_read2_b32 v[10:11], v10 offset0:12 offset1:142
	ds_read2_b32 v[12:13], v12 offset0:77 offset1:207
	s_waitcnt lgkmcnt(0)
	v_cvt_pk_bf16_f32 v6, v10, v12
	v_cvt_pk_bf16_f32 v7, v11, v13
	flat_store_dwordx4 v[8:9], v[0:3] nt
	flat_store_dwordx4 v[8:9], v[4:7] offset:16 nt
	s_branch .LBB0_46

; DI int otid() { int t = threadIdx.x; asm volatile("" : "+v"(t)); return t; }
; DI int obid() { int t = blockIdx.x; asm volatile("" : "+s"(t)); return t; }
; DI int ogrid() { int t = gridDim.x; asm volatile("" : "+s"(t)); return t; }
; DI CvTile cv_tile(const Job* jobs, int t, int c0, int c1) {
;   CvTile r; r.valid = t < c1; r.pad = 0;
;   int j = 0, tt = r.valid ? t : c0;
;   while (tt >= jobs[j].tiles) { tt -= jobs[j].tiles; ++j; }
;   const Job jb = jobs[j];
;   const int tk = jb.K >> 6, tn = jb.N >> 6, per = tk * tn;
;   const int bi = tt / per, rr = tt % per, kt = rr % tk, nt = rr / tk;
;   r.src = jb.src + (size_t)bi * jb.ss + (size_t)(kt * 64) * jb.N + nt * 64;
;   r.dst = jb.dst + (size_t)bi * jb.ds + (size_t)(nt * 64) * jb.K + kt * 64;
;   r.N = jb.N; r.K = jb.K;
;   return r;
; }
;   if (c0 >= c1) return;
;   const int tid = otid(), G = widx < 0 ? ogrid() : wn, b = widx < 0 ? obid() : widx;
;   float* smf = (float*)smraw;
;   const int half = tid >> 8, vt = tid & 255;
;   float* smh = smf + half * (64 * 65);
;   const int kr = vt >> 4, nc = (vt & 15) * 4;
;   int t0 = c0 + b * 2;
;   if (t0 >= c1) { __syncthreads(); return; }
;   CvTile cur = cv_tile(g_jobs, t0 + half, c0, c1);
;   float4 v[4];
; #pragma unroll
;   for (int i = 0; i < 4; ++i) v[i] = *(const float4*)(cur.src + (size_t)(kr + 16 * i) * cur.N + nc);
.LBB0_548:
	s_or_b64 exec, exec, s[14:15]
	ds_read_b64 v[40:41], v1 offset:16
	ds_read2_b64 v[18:21], v1 offset1:1
	v_lshlrev_b32_e32 v2, 2, v16
	v_and_b32_e32 v26, 60, v2
	v_sub_u32_e32 v6, 0, v0
	s_waitcnt lgkmcnt(1)
	v_ashrrev_i32_e32 v2, 6, v41
	v_ashrrev_i32_e32 v3, 6, v40
	v_mul_lo_u32 v2, v3, v2
	v_sub_u32_e32 v4, 0, v2
	v_max_i32_e32 v4, v2, v4
	v_cvt_f32_u32_e32 v5, v4
	v_sub_u32_e32 v7, 0, v4
	v_max_i32_e32 v6, v0, v6
	ds_read2_b64 v[22:25], v1 offset0:4 offset1:5
	v_rcp_iflag_f32_e32 v5, v5
	v_xor_b32_e32 v1, v0, v2
	v_ashrrev_i32_e32 v1, 31, v1
	v_bfe_u32 v32, v16, 4, 4
	v_mul_f32_e32 v5, 0x4f7ffffe, v5
	v_cvt_u32_f32_e32 v5, v5
	v_or_b32_e32 v34, 16, v32
	v_or_b32_e32 v36, 32, v32
	v_or_b32_e32 v38, 48, v32
	v_mul_lo_u32 v7, v7, v5
	v_mul_hi_u32 v7, v5, v7
	v_add_u32_e32 v5, v5, v7
	v_mul_hi_u32 v5, v6, v5
	v_mul_lo_u32 v7, v5, v4
	v_sub_u32_e32 v6, v6, v7
	v_add_u32_e32 v7, 1, v5
	v_cmp_ge_u32_e64 s[38:39], v6, v4
	v_lshlrev_b32_e32 v192, 2, v26
	v_mad_i64_i32 v[10:11], s[14:15], v41, v34, 0
	v_cndmask_b32_e64 v5, v5, v7, s[38:39]
	v_sub_u32_e32 v7, v6, v4
	v_cndmask_b32_e64 v6, v6, v7, s[38:39]
	v_add_u32_e32 v7, 1, v5
	v_cmp_ge_u32_e64 s[38:39], v6, v4
	v_mad_i64_i32 v[12:13], s[14:15], v41, v32, 0
	s_nop 0
	v_cndmask_b32_e64 v4, v5, v7, s[38:39]
	v_sub_u32_e32 v5, 0, v3
	v_max_i32_e32 v5, v3, v5
	v_cvt_f32_u32_e32 v6, v5
	v_xor_b32_e32 v4, v4, v1
	v_sub_u32_e32 v17, v4, v1
	v_mul_lo_u32 v1, v17, v2
	v_rcp_iflag_f32_e32 v2, v6
	v_sub_u32_e32 v6, 0, v5
	v_sub_u32_e32 v0, v0, v1
	v_sub_u32_e32 v4, 0, v0
	v_mul_f32_e32 v2, 0x4f7ffffe, v2
	v_cvt_u32_f32_e32 v2, v2
	v_max_i32_e32 v4, v0, v4
	v_xor_b32_e32 v1, v0, v3
	v_ashrrev_i32_e32 v1, 31, v1
	v_mul_lo_u32 v6, v6, v2
	v_mul_hi_u32 v6, v2, v6
	v_add_u32_e32 v2, v2, v6
	v_mul_hi_u32 v2, v4, v2
	v_mul_lo_u32 v6, v2, v5
	v_sub_u32_e32 v4, v4, v6
	v_add_u32_e32 v6, 1, v2
	v_cmp_ge_u32_e64 s[38:39], v4, v5
	v_ashrrev_i32_e32 v27, 31, v17
	s_waitcnt lgkmcnt(0)
	v_mul_lo_u32 v25, v25, v17
	v_cndmask_b32_e64 v2, v2, v6, s[38:39]
	v_sub_u32_e32 v6, v4, v5
	v_cndmask_b32_e64 v4, v4, v6, s[38:39]
	v_add_u32_e32 v6, 1, v2
	v_cmp_ge_u32_e64 s[38:39], v4, v5
	v_bfe_u32 v42, v16, 2, 6
	s_lshl_b32 s18, s18, 4
	v_cndmask_b32_e64 v2, v2, v6, s[38:39]
	v_xor_b32_e32 v2, v2, v1
	v_sub_u32_e32 v1, v2, v1
	v_lshlrev_b32_e32 v28, 6, v1
	v_mul_lo_u32 v1, v1, v3
	v_sub_u32_e32 v0, v0, v1
	v_lshlrev_b32_e32 v30, 6, v0
	v_mul_lo_u32 v2, v22, v27
	v_mul_lo_u32 v3, v23, v17
	v_mad_u64_u32 v[0:1], s[14:15], v22, v17, 0
	v_add3_u32 v1, v1, v2, v3
	v_lshl_add_u64 v[0:1], v[0:1], 2, v[18:19]
	v_mad_i64_i32 v[2:3], s[14:15], v30, v41, 0
	v_ashrrev_i32_e32 v29, 31, v28
	v_lshl_add_u64 v[0:1], v[2:3], 2, v[0:1]
	v_lshl_add_u64 v[0:1], v[28:29], 2, v[0:1]
	v_lshl_add_u64 v[8:9], v[0:1], 0, v[192:193]
	v_mad_i64_i32 v[0:1], s[14:15], v41, v38, 0
	v_mad_i64_i32 v[2:3], s[14:15], v41, v36, 0
	v_lshl_add_u64 v[0:1], v[0:1], 2, v[8:9]
	v_lshl_add_u64 v[4:5], v[2:3], 2, v[8:9]
	v_lshl_add_u64 v[10:11], v[10:11], 2, v[8:9]
	v_lshl_add_u64 v[12:13], v[12:13], 2, v[8:9]
	flat_load_dwordx4 v[0:3], v[0:1] nt
	s_nop 0
	flat_load_dwordx4 v[4:7], v[4:5] nt
	s_nop 0
	flat_load_dwordx4 v[8:11], v[10:11] nt
	s_nop 0
	flat_load_dwordx4 v[12:15], v[12:13] nt
	v_mul_lo_u32 v23, v24, v27
	v_mad_u64_u32 v[18:19], s[14:15], v24, v17, 0
	v_add3_u32 v19, v19, v23, v25
	v_lshl_add_u64 v[18:19], v[18:19], 1, v[20:21]
	v_mad_i64_i32 v[20:21], s[14:15], v28, v40, 0
	v_lshl_add_u64 v[18:19], v[20:21], 1, v[18:19]
	v_ashrrev_i32_e32 v31, 31, v30
	v_lshl_add_u64 v[44:45], v[30:31], 1, v[18:19]
	v_lshlrev_b32_e32 v18, 4, v16
	v_and_b32_e32 v18, 48, v18
	v_mul_i32_i24_e32 v22, 0x4100, v33
	v_and_b32_e32 v16, 0xfc, v16
	v_mul_u32_u24_e32 v21, 0x41, v18
	v_cndmask_b32_e64 v41, 0, 1, vcc
	v_or_b32_e32 v17, v22, v192
	v_or_b32_e32 v19, v22, v16
	v_mul_u32_u24_e32 v20, 0x104, v32
	v_lshlrev_b32_e32 v21, 2, v21
	v_add_u32_e32 v35, v19, v21
	v_add3_u32 v37, v22, v21, v16
	v_lshlrev_b32_e32 v192, 2, v26
	v_add_u32_e32 v39, v17, v20
	v_lshlrev_b32_e32 v46, 1, v18
	v_mov_b32_e32 v43, v41
	v_mov_b64_e32 v[50:51], v[44:45]
	s_branch .LBB0_550

; DI int otid() { int t = threadIdx.x; asm volatile("" : "+v"(t)); return t; }
; DI int obid() { int t = blockIdx.x; asm volatile("" : "+s"(t)); return t; }
; DI int ogrid() { int t = gridDim.x; asm volatile("" : "+s"(t)); return t; }
; DI unsigned pack2(float a, float b) { unsigned r; asm("v_cvt_pk_bf16_f32 %0, %1, %2" : "=v"(r) : "v"(a), "v"(b)); return r; }
; DI CvTile cv_tile(const Job* jobs, int t, int c0, int c1) {
;   CvTile r; r.valid = t < c1; r.pad = 0;
;   int j = 0, tt = r.valid ? t : c0;
;   while (tt >= jobs[j].tiles) { tt -= jobs[j].tiles; ++j; }
;   const Job jb = jobs[j];
;   const int tk = jb.K >> 6, tn = jb.N >> 6, per = tk * tn;
;   const int bi = tt / per, rr = tt % per, kt = rr % tk, nt = rr / tk;
;   r.src = jb.src + (size_t)bi * jb.ss + (size_t)(kt * 64) * jb.N + nt * 64;
;   r.dst = jb.dst + (size_t)bi * jb.ds + (size_t)(nt * 64) * jb.K + kt * 64;
;   r.N = jb.N; r.K = jb.K;
;   return r;
; }
;   if (c0 >= c1) return;
;   const int tid = otid(), G = widx < 0 ? ogrid() : wn, b = widx < 0 ? obid() : widx;
;   float* smf = (float*)smraw;
;   const int half = tid >> 8, vt = tid & 255;
;   float* smh = smf + half * (64 * 65);
;   const int kr = vt >> 4, nc = (vt & 15) * 4;
;   int t0 = c0 + b * 2;
;   if (t0 >= c1) { __syncthreads(); return; }
;   CvTile cur = cv_tile(g_jobs, t0 + half, c0, c1);
;   float4 v[4];
; #pragma unroll
;   for (int i = 0; i < 4; ++i) v[i] = *(const float4*)(cur.src + (size_t)(kr + 16 * i) * cur.N + nc);
;   for (; t0 < c1; t0 += 2 * G) {
;     const bool more = t0 + 2 * G < c1;
;     CvTile nx = cur; float4 vn[4];
;     if (more) {
;       nx = cv_tile(g_jobs, t0 + 2 * G + half, c0, c1);
; #pragma unroll
;       for (int i = 0; i < 4; ++i) vn[i] = *(const float4*)(nx.src + (size_t)(kr + 16 * i) * nx.N + nc);
;     }
;     __syncthreads();
; #pragma unroll
;     for (int i = 0; i < 4; ++i) { float* d = smh + (kr + 16 * i) * 65 + nc; d[0] = v[i].x; d[1] = v[i].y; d[2] = v[i].z; d[3] = v[i].w; }
;     __syncthreads();
;     if (cur.valid) {
;       const int n = vt >> 2, kp = (vt & 3) * 16;
;       unsigned o[8];
; #pragma unroll
;       for (int q = 0; q < 8; ++q) o[q] = pack2(smh[(kp + 2 * q) * 65 + n], smh[(kp + 2 * q + 1) * 65 + n]);
;       uint4* d4 = (uint4*)(cur.dst + (size_t)n * cur.K + kp);
;       d4[0] = make_uint4(o[0], o[1], o[2], o[3]); d4[1] = make_uint4(o[4], o[5], o[6], o[7]);
.LBB0_555:
	s_or_b64 exec, exec, s[16:17]
	ds_read2_b64 v[16:19], v20 offset1:1
	ds_read_b64 v[48:49], v20 offset:16
	ds_read2_b64 v[20:23], v20 offset0:4 offset1:5
	v_sub_u32_e32 v28, 0, v24
	v_max_i32_e32 v28, v24, v28
	v_cndmask_b32_e64 v43, 0, 1, vcc
	s_waitcnt lgkmcnt(0)
	v_ashrrev_i32_e32 v25, 6, v48
	v_ashrrev_i32_e32 v26, 6, v49
	v_mul_lo_u32 v26, v26, v25
	v_sub_u32_e32 v29, 0, v26
	v_max_i32_e32 v29, v26, v29
	v_cvt_f32_u32_e32 v30, v29
	v_sub_u32_e32 v31, 0, v29
	v_xor_b32_e32 v27, v24, v26
	v_ashrrev_i32_e32 v27, 31, v27
	v_rcp_iflag_f32_e32 v30, v30
	s_nop 0
	v_mul_f32_e32 v30, 0x4f7ffffe, v30
	v_cvt_u32_f32_e32 v30, v30
	v_mul_lo_u32 v31, v31, v30
	v_mul_hi_u32 v31, v30, v31
	v_add_u32_e32 v30, v30, v31
	v_mul_hi_u32 v30, v28, v30
	v_mul_lo_u32 v31, v30, v29
	v_sub_u32_e32 v28, v28, v31
	v_cmp_ge_u32_e64 s[38:39], v28, v29
	v_add_u32_e32 v31, 1, v30
	s_nop 0
	v_cndmask_b32_e64 v30, v30, v31, s[38:39]
	v_sub_u32_e32 v31, v28, v29
	v_cndmask_b32_e64 v28, v28, v31, s[38:39]
	v_cmp_ge_u32_e64 s[38:39], v28, v29
	v_sub_u32_e32 v29, 0, v25
	v_add_u32_e32 v28, 1, v30
	v_max_i32_e32 v29, v25, v29
	v_cndmask_b32_e64 v28, v30, v28, s[38:39]
	v_cvt_f32_u32_e32 v30, v29
	v_xor_b32_e32 v28, v28, v27
	v_sub_u32_e32 v27, v28, v27
	v_mul_lo_u32 v26, v27, v26
	v_rcp_iflag_f32_e32 v30, v30
	v_sub_u32_e32 v31, 0, v29
	v_sub_u32_e32 v24, v24, v26
	v_sub_u32_e32 v28, 0, v24
	v_mul_f32_e32 v30, 0x4f7ffffe, v30
	v_cvt_u32_f32_e32 v30, v30
	v_max_i32_e32 v28, v24, v28
	v_xor_b32_e32 v26, v24, v25
	v_ashrrev_i32_e32 v26, 31, v26
	v_mul_lo_u32 v31, v31, v30
	v_mul_hi_u32 v31, v30, v31
	v_add_u32_e32 v30, v30, v31
	v_mul_hi_u32 v30, v28, v30
	v_mul_lo_u32 v31, v30, v29
	v_sub_u32_e32 v28, v28, v31
	v_cmp_ge_u32_e64 s[38:39], v28, v29
	v_add_u32_e32 v31, 1, v30
	s_nop 0
	v_cndmask_b32_e64 v30, v30, v31, s[38:39]
	v_sub_u32_e32 v31, v28, v29
	v_cndmask_b32_e64 v28, v28, v31, s[38:39]
	v_cmp_ge_u32_e64 s[38:39], v28, v29
	v_add_u32_e32 v28, 1, v30
	v_mul_lo_u32 v29, v21, v27
	v_cndmask_b32_e64 v28, v30, v28, s[38:39]
	v_xor_b32_e32 v28, v28, v26
	v_sub_u32_e32 v26, v28, v26
	v_mul_lo_u32 v25, v26, v25
	v_sub_u32_e32 v24, v24, v25
	v_ashrrev_i32_e32 v25, 31, v27
	v_mul_lo_u32 v28, v20, v25
	v_mad_u64_u32 v[20:21], s[16:17], v20, v27, 0
	v_add3_u32 v21, v21, v28, v29
	v_lshlrev_b32_e32 v50, 6, v24
	v_lshl_add_u64 v[16:17], v[20:21], 2, v[16:17]
	v_mad_i64_i32 v[20:21], s[16:17], v50, v49, 0
	v_lshl_add_u64 v[16:17], v[20:21], 2, v[16:17]
	v_lshlrev_b32_e32 v20, 6, v26
	v_ashrrev_i32_e32 v21, 31, v20
	v_lshl_add_u64 v[16:17], v[20:21], 2, v[16:17]
	v_mul_lo_u32 v21, v22, v25
	v_mul_lo_u32 v24, v23, v27
	v_mad_u64_u32 v[22:23], s[16:17], v22, v27, 0
	v_add3_u32 v23, v23, v21, v24
	v_lshl_add_u64 v[18:19], v[22:23], 1, v[18:19]
	v_mad_i64_i32 v[20:21], s[16:17], v20, v48, 0
	v_lshl_add_u64 v[52:53], v[20:21], 1, v[18:19]
	v_lshl_add_u64 v[28:29], v[16:17], 0, v[192:193]
	v_mad_i64_i32 v[16:17], s[16:17], v49, v32, 0
	v_mad_i64_i32 v[20:21], s[16:17], v49, v34, 0
	v_mad_i64_i32 v[24:25], s[16:17], v49, v36, 0
	v_mad_i64_i32 v[30:31], s[16:17], v49, v38, 0
	v_lshl_add_u64 v[16:17], v[16:17], 2, v[28:29]
	v_lshl_add_u64 v[20:21], v[20:21], 2, v[28:29]
	v_lshl_add_u64 v[24:25], v[24:25], 2, v[28:29]
	v_lshl_add_u64 v[28:29], v[30:31], 2, v[28:29]
	flat_load_dwordx4 v[16:19], v[16:17] nt
	v_ashrrev_i32_e32 v51, 31, v50
	flat_load_dwordx4 v[20:23], v[20:21] nt
	v_lshl_add_u64 v[50:51], v[50:51], 1, v[52:53]
	flat_load_dwordx4 v[24:27], v[24:25] nt
	s_nop 0
	flat_load_dwordx4 v[28:31], v[28:29] nt
.LBB0_556:
	s_waitcnt lgkmcnt(0)
	s_barrier
	s_waitcnt vmcnt(0)
	ds_write2_b32 v39, v12, v13 offset1:1
	ds_write2_b32 v39, v14, v15 offset0:2 offset1:3
	v_add_u32_e32 v12, 0x1040, v39
	ds_write2_b32 v12, v8, v9 offset1:1
	v_add_u32_e32 v8, 0x1048, v39
	ds_write2_b32 v8, v10, v11 offset1:1
	v_add_u32_e32 v8, 0x2080, v39
	ds_write2_b32 v8, v4, v5 offset1:1
	v_add_u32_e32 v4, 0x2088, v39
	ds_write2_b32 v4, v6, v7 offset1:1
	v_add_u32_e32 v4, 0x30c0, v39
	ds_write2_b32 v4, v0, v1 offset1:1
	v_add_u32_e32 v0, 0x30c8, v39
	v_cmp_ne_u32_e32 vcc, 0, v41
	ds_write2_b32 v0, v2, v3 offset1:1
	s_waitcnt lgkmcnt(0)
	s_barrier
	s_and_saveexec_b64 s[16:17], vcc
	s_cbranch_execz .LBB0_549
	ds_read2_b32 v[0:1], v35 offset1:130
	ds_read2_b32 v[2:3], v37 offset0:65 offset1:195
	v_add_u32_e32 v4, 0x400, v37
	ds_read2_b32 v[4:5], v4 offset0:69 offset1:199
	v_add_u32_e32 v6, 0x800, v37
	ds_read2_b32 v[6:7], v6 offset0:73 offset1:203
	s_waitcnt lgkmcnt(2)
	v_cvt_pk_bf16_f32 v0, v0, v2
	v_add_u32_e32 v2, 0x400, v35
	v_cvt_pk_bf16_f32 v1, v1, v3
	ds_read2_b32 v[2:3], v2 offset0:4 offset1:134
	s_waitcnt lgkmcnt(0)
	v_cvt_pk_bf16_f32 v2, v2, v4
	v_add_u32_e32 v4, 0x800, v35
	v_cvt_pk_bf16_f32 v3, v3, v5
	ds_read2_b32 v[4:5], v4 offset0:8 offset1:138
	s_waitcnt lgkmcnt(0)
	v_cvt_pk_bf16_f32 v4, v4, v6
	v_add_u32_e32 v6, 0xc00, v35
	v_add_u32_e32 v8, 0xc00, v37
	v_cvt_pk_bf16_f32 v5, v5, v7
	ds_read2_b32 v[6:7], v6 offset0:12 offset1:142
	ds_read2_b32 v[8:9], v8 offset0:77 offset1:207
	s_waitcnt lgkmcnt(0)
	v_cvt_pk_bf16_f32 v6, v6, v8
	v_cvt_pk_bf16_f32 v7, v7, v9
	v_mad_i64_i32 v[8:9], s[24:25], v40, v42, 0
	v_lshl_add_u64 v[8:9], v[8:9], 1, v[44:45]
	v_mov_b32_e32 v47, v193
	v_lshl_add_u64 v[8:9], v[8:9], 0, v[46:47]
	flat_store_dwordx4 v[8:9], v[0:3] nt
	flat_store_dwordx4 v[8:9], v[4:7] offset:16 nt
	s_branch .LBB0_549

; DI int otid() { int t = threadIdx.x; asm volatile("" : "+v"(t)); return t; }
; DI int obid() { int t = blockIdx.x; asm volatile("" : "+s"(t)); return t; }
; DI int ogrid() { int t = gridDim.x; asm volatile("" : "+s"(t)); return t; }
; DI CvTile cv_tile(const Job* jobs, int t, int c0, int c1) {
;   CvTile r; r.valid = t < c1; r.pad = 0;
;   int j = 0, tt = r.valid ? t : c0;
;   while (tt >= jobs[j].tiles) { tt -= jobs[j].tiles; ++j; }
;   const Job jb = jobs[j];
;   const int tk = jb.K >> 6, tn = jb.N >> 6, per = tk * tn;
;   const int bi = tt / per, rr = tt % per, kt = rr % tk, nt = rr / tk;
;   r.src = jb.src + (size_t)bi * jb.ss + (size_t)(kt * 64) * jb.N + nt * 64;
;   r.dst = jb.dst + (size_t)bi * jb.ds + (size_t)(nt * 64) * jb.K + kt * 64;
;   r.N = jb.N; r.K = jb.K;
;   return r;
; }
;   if (c0 >= c1) return;
;   const int tid = otid(), G = widx < 0 ? ogrid() : wn, b = widx < 0 ? obid() : widx;
;   float* smf = (float*)smraw;
;   const int half = tid >> 8, vt = tid & 255;
;   float* smh = smf + half * (64 * 65);
;   const int kr = vt >> 4, nc = (vt & 15) * 4;
;   int t0 = c0 + b * 2;
;   if (t0 >= c1) { __syncthreads(); return; }
;   CvTile cur = cv_tile(g_jobs, t0 + half, c0, c1);
;   float4 v[4];
; #pragma unroll
;   for (int i = 0; i < 4; ++i) v[i] = *(const float4*)(cur.src + (size_t)(kr + 16 * i) * cur.N + nc);
.LBB0_567:
	s_or_b64 exec, exec, s[0:1]
	ds_read_b64 v[40:41], v1 offset:16
	ds_read2_b64 v[18:21], v1 offset1:1
	v_lshlrev_b32_e32 v2, 2, v16
	v_and_b32_e32 v26, 60, v2
	v_sub_u32_e32 v6, 0, v0
	s_waitcnt lgkmcnt(0)
	v_ashrrev_i32_e32 v2, 6, v41
	v_ashrrev_i32_e32 v3, 6, v40
	v_mul_lo_u32 v2, v3, v2
	v_sub_u32_e32 v4, 0, v2
	v_max_i32_e32 v4, v2, v4
	v_cvt_f32_u32_e32 v5, v4
	v_sub_u32_e32 v7, 0, v4
	v_max_i32_e32 v6, v0, v6
	ds_read2_b64 v[22:25], v1 offset0:4 offset1:5
	v_rcp_iflag_f32_e32 v5, v5
	v_xor_b32_e32 v1, v0, v2
	v_ashrrev_i32_e32 v1, 31, v1
	v_bfe_u32 v32, v16, 4, 4
	v_mul_f32_e32 v5, 0x4f7ffffe, v5
	v_cvt_u32_f32_e32 v5, v5
	v_or_b32_e32 v34, 16, v32
	v_or_b32_e32 v36, 32, v32
	v_or_b32_e32 v38, 48, v32
	v_mul_lo_u32 v7, v7, v5
	v_mul_hi_u32 v7, v5, v7
	v_add_u32_e32 v5, v5, v7
	v_mul_hi_u32 v5, v6, v5
	v_mul_lo_u32 v7, v5, v4
	v_sub_u32_e32 v6, v6, v7
	v_add_u32_e32 v7, 1, v5
	v_cmp_ge_u32_e64 s[38:39], v6, v4
	v_lshlrev_b32_e32 v192, 2, v26
	v_mad_i64_i32 v[10:11], s[0:1], v41, v34, 0
	v_cndmask_b32_e64 v5, v5, v7, s[38:39]
	v_sub_u32_e32 v7, v6, v4
	v_cndmask_b32_e64 v6, v6, v7, s[38:39]
	v_add_u32_e32 v7, 1, v5
	v_cmp_ge_u32_e64 s[38:39], v6, v4
	v_mad_i64_i32 v[12:13], s[0:1], v41, v32, 0
	s_nop 0
	v_cndmask_b32_e64 v4, v5, v7, s[38:39]
	v_sub_u32_e32 v5, 0, v3
	v_max_i32_e32 v5, v3, v5
	v_cvt_f32_u32_e32 v6, v5
	v_xor_b32_e32 v4, v4, v1
	v_sub_u32_e32 v17, v4, v1
	v_mul_lo_u32 v1, v17, v2
	v_rcp_iflag_f32_e32 v2, v6
	v_sub_u32_e32 v6, 0, v5
	v_sub_u32_e32 v0, v0, v1
	v_sub_u32_e32 v4, 0, v0
	v_mul_f32_e32 v2, 0x4f7ffffe, v2
	v_cvt_u32_f32_e32 v2, v2
	v_max_i32_e32 v4, v0, v4
	v_xor_b32_e32 v1, v0, v3
	v_ashrrev_i32_e32 v1, 31, v1
	v_mul_lo_u32 v6, v6, v2
	v_mul_hi_u32 v6, v2, v6
	v_add_u32_e32 v2, v2, v6
	v_mul_hi_u32 v2, v4, v2
	v_mul_lo_u32 v6, v2, v5
	v_sub_u32_e32 v4, v4, v6
	v_add_u32_e32 v6, 1, v2
	v_cmp_ge_u32_e64 s[38:39], v4, v5
	v_ashrrev_i32_e32 v27, 31, v17
	s_waitcnt lgkmcnt(0)
	v_mul_lo_u32 v25, v25, v17
	v_cndmask_b32_e64 v2, v2, v6, s[38:39]
	v_sub_u32_e32 v6, v4, v5
	v_cndmask_b32_e64 v4, v4, v6, s[38:39]
	v_add_u32_e32 v6, 1, v2
	v_cmp_ge_u32_e64 s[38:39], v4, v5
	v_bfe_u32 v42, v16, 2, 6
	s_lshl_b32 s18, s16, 1
	v_cndmask_b32_e64 v2, v2, v6, s[38:39]
	v_xor_b32_e32 v2, v2, v1
	v_sub_u32_e32 v1, v2, v1
	v_lshlrev_b32_e32 v28, 6, v1
	v_mul_lo_u32 v1, v1, v3
	v_sub_u32_e32 v0, v0, v1
	v_lshlrev_b32_e32 v30, 6, v0
	v_mul_lo_u32 v2, v22, v27
	v_mul_lo_u32 v3, v23, v17
	v_mad_u64_u32 v[0:1], s[0:1], v22, v17, 0
	v_add3_u32 v1, v1, v2, v3
	v_lshl_add_u64 v[0:1], v[0:1], 2, v[18:19]
	v_mad_i64_i32 v[2:3], s[0:1], v30, v41, 0
	v_ashrrev_i32_e32 v29, 31, v28
	v_lshl_add_u64 v[0:1], v[2:3], 2, v[0:1]
	v_lshl_add_u64 v[0:1], v[28:29], 2, v[0:1]
	v_lshl_add_u64 v[8:9], v[0:1], 0, v[192:193]
	v_mad_i64_i32 v[0:1], s[0:1], v41, v38, 0
	v_mad_i64_i32 v[2:3], s[0:1], v41, v36, 0
	v_lshl_add_u64 v[0:1], v[0:1], 2, v[8:9]
	v_lshl_add_u64 v[4:5], v[2:3], 2, v[8:9]
	v_lshl_add_u64 v[10:11], v[10:11], 2, v[8:9]
	v_lshl_add_u64 v[12:13], v[12:13], 2, v[8:9]
	flat_load_dwordx4 v[0:3], v[0:1] nt
	s_nop 0
	flat_load_dwordx4 v[4:7], v[4:5] nt
	s_nop 0
	flat_load_dwordx4 v[8:11], v[10:11] nt
	s_nop 0
	flat_load_dwordx4 v[12:15], v[12:13] nt
	v_mul_lo_u32 v23, v24, v27
	v_mad_u64_u32 v[18:19], s[0:1], v24, v17, 0
	v_add3_u32 v19, v19, v23, v25
	v_lshl_add_u64 v[18:19], v[18:19], 1, v[20:21]
	v_mad_i64_i32 v[20:21], s[0:1], v28, v40, 0
	v_lshl_add_u64 v[18:19], v[20:21], 1, v[18:19]
	v_ashrrev_i32_e32 v31, 31, v30
	v_lshl_add_u64 v[44:45], v[30:31], 1, v[18:19]
	v_lshlrev_b32_e32 v18, 4, v16
	v_and_b32_e32 v18, 48, v18
	v_mul_i32_i24_e32 v22, 0x4100, v33
	v_and_b32_e32 v16, 0xfc, v16
	v_mul_u32_u24_e32 v21, 0x41, v18
	v_cndmask_b32_e64 v41, 0, 1, vcc
	v_or_b32_e32 v17, v22, v192
	v_or_b32_e32 v19, v22, v16
	v_mul_u32_u24_e32 v20, 0x104, v32
	v_lshlrev_b32_e32 v21, 2, v21
	v_add_u32_e32 v35, v19, v21
	v_add3_u32 v37, v22, v21, v16
	v_lshlrev_b32_e32 v192, 2, v26
	v_add_u32_e32 v39, v17, v20
	v_lshlrev_b32_e32 v46, 1, v18
	v_mov_b32_e32 v43, v41
	v_mov_b64_e32 v[50:51], v[44:45]
	s_branch .LBB0_569

; DI int otid() { int t = threadIdx.x; asm volatile("" : "+v"(t)); return t; }
; DI int obid() { int t = blockIdx.x; asm volatile("" : "+s"(t)); return t; }
; DI int ogrid() { int t = gridDim.x; asm volatile("" : "+s"(t)); return t; }
; DI unsigned pack2(float a, float b) { unsigned r; asm("v_cvt_pk_bf16_f32 %0, %1, %2" : "=v"(r) : "v"(a), "v"(b)); return r; }
; DI CvTile cv_tile(const Job* jobs, int t, int c0, int c1) {
;   CvTile r; r.valid = t < c1; r.pad = 0;
;   int j = 0, tt = r.valid ? t : c0;
;   while (tt >= jobs[j].tiles) { tt -= jobs[j].tiles; ++j; }
;   const Job jb = jobs[j];
;   const int tk = jb.K >> 6, tn = jb.N >> 6, per = tk * tn;
;   const int bi = tt / per, rr = tt % per, kt = rr % tk, nt = rr / tk;
;   r.src = jb.src + (size_t)bi * jb.ss + (size_t)(kt * 64) * jb.N + nt * 64;
;   r.dst = jb.dst + (size_t)bi * jb.ds + (size_t)(nt * 64) * jb.K + kt * 64;
;   r.N = jb.N; r.K = jb.K;
;   return r;
; }
;   if (c0 >= c1) return;
;   const int tid = otid(), G = widx < 0 ? ogrid() : wn, b = widx < 0 ? obid() : widx;
;   float* smf = (float*)smraw;
;   const int half = tid >> 8, vt = tid & 255;
;   float* smh = smf + half * (64 * 65);
;   const int kr = vt >> 4, nc = (vt & 15) * 4;
;   int t0 = c0 + b * 2;
;   if (t0 >= c1) { __syncthreads(); return; }
;   CvTile cur = cv_tile(g_jobs, t0 + half, c0, c1);
;   float4 v[4];
; #pragma unroll
;   for (int i = 0; i < 4; ++i) v[i] = *(const float4*)(cur.src + (size_t)(kr + 16 * i) * cur.N + nc);
;   for (; t0 < c1; t0 += 2 * G) {
;     const bool more = t0 + 2 * G < c1;
;     CvTile nx = cur; float4 vn[4];
;     if (more) {
;       nx = cv_tile(g_jobs, t0 + 2 * G + half, c0, c1);
; #pragma unroll
;       for (int i = 0; i < 4; ++i) vn[i] = *(const float4*)(nx.src + (size_t)(kr + 16 * i) * nx.N + nc);
;     }
;     __syncthreads();
; #pragma unroll
;     for (int i = 0; i < 4; ++i) { float* d = smh + (kr + 16 * i) * 65 + nc; d[0] = v[i].x; d[1] = v[i].y; d[2] = v[i].z; d[3] = v[i].w; }
;     __syncthreads();
;     if (cur.valid) {
;       const int n = vt >> 2, kp = (vt & 3) * 16;
;       unsigned o[8];
; #pragma unroll
;       for (int q = 0; q < 8; ++q) o[q] = pack2(smh[(kp + 2 * q) * 65 + n], smh[(kp + 2 * q + 1) * 65 + n]);
;       uint4* d4 = (uint4*)(cur.dst + (size_t)n * cur.K + kp);
;       d4[0] = make_uint4(o[0], o[1], o[2], o[3]); d4[1] = make_uint4(o[4], o[5], o[6], o[7]);
.LBB0_574:
	s_or_b64 exec, exec, s[14:15]
	ds_read2_b64 v[16:19], v20 offset1:1
	ds_read_b64 v[48:49], v20 offset:16
	ds_read2_b64 v[20:23], v20 offset0:4 offset1:5
	v_sub_u32_e32 v28, 0, v24
	v_max_i32_e32 v28, v24, v28
	v_cndmask_b32_e64 v43, 0, 1, vcc
	s_waitcnt lgkmcnt(0)
	v_ashrrev_i32_e32 v25, 6, v48
	v_ashrrev_i32_e32 v26, 6, v49
	v_mul_lo_u32 v26, v26, v25
	v_sub_u32_e32 v29, 0, v26
	v_max_i32_e32 v29, v26, v29
	v_cvt_f32_u32_e32 v30, v29
	v_sub_u32_e32 v31, 0, v29
	v_xor_b32_e32 v27, v24, v26
	v_ashrrev_i32_e32 v27, 31, v27
	v_rcp_iflag_f32_e32 v30, v30
	s_nop 0
	v_mul_f32_e32 v30, 0x4f7ffffe, v30
	v_cvt_u32_f32_e32 v30, v30
	v_mul_lo_u32 v31, v31, v30
	v_mul_hi_u32 v31, v30, v31
	v_add_u32_e32 v30, v30, v31
	v_mul_hi_u32 v30, v28, v30
	v_mul_lo_u32 v31, v30, v29
	v_sub_u32_e32 v28, v28, v31
	v_cmp_ge_u32_e64 s[38:39], v28, v29
	v_add_u32_e32 v31, 1, v30
	s_nop 0
	v_cndmask_b32_e64 v30, v30, v31, s[38:39]
	v_sub_u32_e32 v31, v28, v29
	v_cndmask_b32_e64 v28, v28, v31, s[38:39]
	v_cmp_ge_u32_e64 s[38:39], v28, v29
	v_sub_u32_e32 v29, 0, v25
	v_add_u32_e32 v28, 1, v30
	v_max_i32_e32 v29, v25, v29
	v_cndmask_b32_e64 v28, v30, v28, s[38:39]
	v_cvt_f32_u32_e32 v30, v29
	v_xor_b32_e32 v28, v28, v27
	v_sub_u32_e32 v27, v28, v27
	v_mul_lo_u32 v26, v27, v26
	v_rcp_iflag_f32_e32 v30, v30
	v_sub_u32_e32 v31, 0, v29
	v_sub_u32_e32 v24, v24, v26
	v_sub_u32_e32 v28, 0, v24
	v_mul_f32_e32 v30, 0x4f7ffffe, v30
	v_cvt_u32_f32_e32 v30, v30
	v_max_i32_e32 v28, v24, v28
	v_xor_b32_e32 v26, v24, v25
	v_ashrrev_i32_e32 v26, 31, v26
	v_mul_lo_u32 v31, v31, v30
	v_mul_hi_u32 v31, v30, v31
	v_add_u32_e32 v30, v30, v31
	v_mul_hi_u32 v30, v28, v30
	v_mul_lo_u32 v31, v30, v29
	v_sub_u32_e32 v28, v28, v31
	v_cmp_ge_u32_e64 s[38:39], v28, v29
	v_add_u32_e32 v31, 1, v30
	s_nop 0
	v_cndmask_b32_e64 v30, v30, v31, s[38:39]
	v_sub_u32_e32 v31, v28, v29
	v_cndmask_b32_e64 v28, v28, v31, s[38:39]
	v_cmp_ge_u32_e64 s[38:39], v28, v29
	v_add_u32_e32 v28, 1, v30
	v_mul_lo_u32 v29, v21, v27
	v_cndmask_b32_e64 v28, v30, v28, s[38:39]
	v_xor_b32_e32 v28, v28, v26
	v_sub_u32_e32 v26, v28, v26
	v_mul_lo_u32 v25, v26, v25
	v_sub_u32_e32 v24, v24, v25
	v_ashrrev_i32_e32 v25, 31, v27
	v_mul_lo_u32 v28, v20, v25
	v_mad_u64_u32 v[20:21], s[14:15], v20, v27, 0
	v_add3_u32 v21, v21, v28, v29
	v_lshlrev_b32_e32 v50, 6, v24
	v_lshl_add_u64 v[16:17], v[20:21], 2, v[16:17]
	v_mad_i64_i32 v[20:21], s[14:15], v50, v49, 0
	v_lshl_add_u64 v[16:17], v[20:21], 2, v[16:17]
	v_lshlrev_b32_e32 v20, 6, v26
	v_ashrrev_i32_e32 v21, 31, v20
	v_lshl_add_u64 v[16:17], v[20:21], 2, v[16:17]
	v_mul_lo_u32 v21, v22, v25
	v_mul_lo_u32 v24, v23, v27
	v_mad_u64_u32 v[22:23], s[14:15], v22, v27, 0
	v_add3_u32 v23, v23, v21, v24
	v_lshl_add_u64 v[18:19], v[22:23], 1, v[18:19]
	v_mad_i64_i32 v[20:21], s[14:15], v20, v48, 0
	v_lshl_add_u64 v[52:53], v[20:21], 1, v[18:19]
	v_lshl_add_u64 v[28:29], v[16:17], 0, v[192:193]
	v_mad_i64_i32 v[16:17], s[14:15], v49, v32, 0
	v_mad_i64_i32 v[20:21], s[14:15], v49, v34, 0
	v_mad_i64_i32 v[24:25], s[14:15], v49, v36, 0
	v_mad_i64_i32 v[30:31], s[14:15], v49, v38, 0
	v_lshl_add_u64 v[16:17], v[16:17], 2, v[28:29]
	v_lshl_add_u64 v[20:21], v[20:21], 2, v[28:29]
	v_lshl_add_u64 v[24:25], v[24:25], 2, v[28:29]
	v_lshl_add_u64 v[28:29], v[30:31], 2, v[28:29]
	flat_load_dwordx4 v[16:19], v[16:17] nt
	v_ashrrev_i32_e32 v51, 31, v50
	flat_load_dwordx4 v[20:23], v[20:21] nt
	v_lshl_add_u64 v[50:51], v[50:51], 1, v[52:53]
	flat_load_dwordx4 v[24:27], v[24:25] nt
	s_nop 0
	flat_load_dwordx4 v[28:31], v[28:29] nt
.LBB0_575:
	s_waitcnt lgkmcnt(0)
	s_barrier
	s_waitcnt vmcnt(0)
	ds_write2_b32 v39, v12, v13 offset1:1
	ds_write2_b32 v39, v14, v15 offset0:2 offset1:3
	v_add_u32_e32 v12, 0x1040, v39
	ds_write2_b32 v12, v8, v9 offset1:1
	v_add_u32_e32 v8, 0x1048, v39
	ds_write2_b32 v8, v10, v11 offset1:1
	v_add_u32_e32 v8, 0x2080, v39
	ds_write2_b32 v8, v4, v5 offset1:1
	v_add_u32_e32 v4, 0x2088, v39
	ds_write2_b32 v4, v6, v7 offset1:1
	v_add_u32_e32 v4, 0x30c0, v39
	ds_write2_b32 v4, v0, v1 offset1:1
	v_add_u32_e32 v0, 0x30c8, v39
	v_cmp_ne_u32_e32 vcc, 0, v41
	ds_write2_b32 v0, v2, v3 offset1:1
	s_waitcnt lgkmcnt(0)
	s_barrier
	s_and_saveexec_b64 s[14:15], vcc
	s_cbranch_execz .LBB0_568
	ds_read2_b32 v[0:1], v35 offset1:130
	ds_read2_b32 v[2:3], v37 offset0:65 offset1:195
	v_add_u32_e32 v4, 0x400, v37
	ds_read2_b32 v[4:5], v4 offset0:69 offset1:199
	v_add_u32_e32 v6, 0x800, v37
	ds_read2_b32 v[6:7], v6 offset0:73 offset1:203
	s_waitcnt lgkmcnt(2)
	v_cvt_pk_bf16_f32 v0, v0, v2
	v_add_u32_e32 v2, 0x400, v35
	v_cvt_pk_bf16_f32 v1, v1, v3
	ds_read2_b32 v[2:3], v2 offset0:4 offset1:134
	s_waitcnt lgkmcnt(0)
	v_cvt_pk_bf16_f32 v2, v2, v4
	v_add_u32_e32 v4, 0x800, v35
	v_cvt_pk_bf16_f32 v3, v3, v5
	ds_read2_b32 v[4:5], v4 offset0:8 offset1:138
	s_waitcnt lgkmcnt(0)
	v_cvt_pk_bf16_f32 v4, v4, v6
	v_add_u32_e32 v6, 0xc00, v35
	v_add_u32_e32 v8, 0xc00, v37
	v_cvt_pk_bf16_f32 v5, v5, v7
	ds_read2_b32 v[6:7], v6 offset0:12 offset1:142
	ds_read2_b32 v[8:9], v8 offset0:77 offset1:207
	s_waitcnt lgkmcnt(0)
	v_cvt_pk_bf16_f32 v6, v6, v8
	v_cvt_pk_bf16_f32 v7, v7, v9
	v_mad_i64_i32 v[8:9], s[16:17], v40, v42, 0
	v_lshl_add_u64 v[8:9], v[8:9], 1, v[44:45]
	v_mov_b32_e32 v47, v193
	v_lshl_add_u64 v[8:9], v[8:9], 0, v[46:47]
	flat_store_dwordx4 v[8:9], v[0:3] nt
	flat_store_dwordx4 v[8:9], v[4:7] offset:16 nt
	s_branch .LBB0_568

; DI int otid() { int t = threadIdx.x; asm volatile("" : "+v"(t)); return t; }
; DI int obid() { int t = blockIdx.x; asm volatile("" : "+s"(t)); return t; }
; DI int ogrid() { int t = gridDim.x; asm volatile("" : "+s"(t)); return t; }
; DI CvTile cv_tile(const Job* jobs, int t, int c0, int c1) {
;   CvTile r; r.valid = t < c1; r.pad = 0;
;   int j = 0, tt = r.valid ? t : c0;
;   while (tt >= jobs[j].tiles) { tt -= jobs[j].tiles; ++j; }
;   const Job jb = jobs[j];
;   const int tk = jb.K >> 6, tn = jb.N >> 6, per = tk * tn;
;   const int bi = tt / per, rr = tt % per, kt = rr % tk, nt = rr / tk;
;   r.src = jb.src + (size_t)bi * jb.ss + (size_t)(kt * 64) * jb.N + nt * 64;
;   r.dst = jb.dst + (size_t)bi * jb.ds + (size_t)(nt * 64) * jb.K + kt * 64;
;   r.N = jb.N; r.K = jb.K;
;   return r;
; }
;   if (c0 >= c1) return;
;   const int tid = otid(), G = widx < 0 ? ogrid() : wn, b = widx < 0 ? obid() : widx;
;   float* smf = (float*)smraw;
;   const int half = tid >> 8, vt = tid & 255;
;   float* smh = smf + half * (64 * 65);
;   const int kr = vt >> 4, nc = (vt & 15) * 4;
;   int t0 = c0 + b * 2;
;   if (t0 >= c1) { __syncthreads(); return; }
;   CvTile cur = cv_tile(g_jobs, t0 + half, c0, c1);
;   float4 v[4];
; #pragma unroll
;   for (int i = 0; i < 4; ++i) v[i] = *(const float4*)(cur.src + (size_t)(kr + 16 * i) * cur.N + nc);
.LBB0_630:
	s_or_b64 exec, exec, s[14:15]
	ds_read_b64 v[40:41], v1 offset:16
	ds_read2_b64 v[18:21], v1 offset1:1
	v_lshlrev_b32_e32 v2, 2, v16
	v_and_b32_e32 v26, 60, v2
	v_sub_u32_e32 v6, 0, v0
	s_waitcnt lgkmcnt(1)
	v_ashrrev_i32_e32 v2, 6, v41
	v_ashrrev_i32_e32 v3, 6, v40
	v_mul_lo_u32 v2, v3, v2
	v_sub_u32_e32 v4, 0, v2
	v_max_i32_e32 v4, v2, v4
	v_cvt_f32_u32_e32 v5, v4
	v_sub_u32_e32 v7, 0, v4
	v_max_i32_e32 v6, v0, v6
	ds_read2_b64 v[22:25], v1 offset0:4 offset1:5
	v_rcp_iflag_f32_e32 v5, v5
	v_xor_b32_e32 v1, v0, v2
	v_ashrrev_i32_e32 v1, 31, v1
	v_bfe_u32 v32, v16, 4, 4
	v_mul_f32_e32 v5, 0x4f7ffffe, v5
	v_cvt_u32_f32_e32 v5, v5
	v_or_b32_e32 v34, 16, v32
	v_or_b32_e32 v36, 32, v32
	v_or_b32_e32 v38, 48, v32
	v_mul_lo_u32 v7, v7, v5
	v_mul_hi_u32 v7, v5, v7
	v_add_u32_e32 v5, v5, v7
	v_mul_hi_u32 v5, v6, v5
	v_mul_lo_u32 v7, v5, v4
	v_sub_u32_e32 v6, v6, v7
	v_add_u32_e32 v7, 1, v5
	v_cmp_ge_u32_e64 s[38:39], v6, v4
	v_lshlrev_b32_e32 v192, 2, v26
	v_mad_i64_i32 v[10:11], s[14:15], v41, v34, 0
	v_cndmask_b32_e64 v5, v5, v7, s[38:39]
	v_sub_u32_e32 v7, v6, v4
	v_cndmask_b32_e64 v6, v6, v7, s[38:39]
	v_add_u32_e32 v7, 1, v5
	v_cmp_ge_u32_e64 s[38:39], v6, v4
	v_mad_i64_i32 v[12:13], s[14:15], v41, v32, 0
	s_nop 0
	v_cndmask_b32_e64 v4, v5, v7, s[38:39]
	v_sub_u32_e32 v5, 0, v3
	v_max_i32_e32 v5, v3, v5
	v_cvt_f32_u32_e32 v6, v5
	v_xor_b32_e32 v4, v4, v1
	v_sub_u32_e32 v17, v4, v1
	v_mul_lo_u32 v1, v17, v2
	v_rcp_iflag_f32_e32 v2, v6
	v_sub_u32_e32 v6, 0, v5
	v_sub_u32_e32 v0, v0, v1
	v_sub_u32_e32 v4, 0, v0
	v_mul_f32_e32 v2, 0x4f7ffffe, v2
	v_cvt_u32_f32_e32 v2, v2
	v_max_i32_e32 v4, v0, v4
	v_xor_b32_e32 v1, v0, v3
	v_ashrrev_i32_e32 v1, 31, v1
	v_mul_lo_u32 v6, v6, v2
	v_mul_hi_u32 v6, v2, v6
	v_add_u32_e32 v2, v2, v6
	v_mul_hi_u32 v2, v4, v2
	v_mul_lo_u32 v6, v2, v5
	v_sub_u32_e32 v4, v4, v6
	v_add_u32_e32 v6, 1, v2
	v_cmp_ge_u32_e64 s[38:39], v4, v5
	v_ashrrev_i32_e32 v27, 31, v17
	s_waitcnt lgkmcnt(0)
	v_mul_lo_u32 v25, v25, v17
	v_cndmask_b32_e64 v2, v2, v6, s[38:39]
	v_sub_u32_e32 v6, v4, v5
	v_cndmask_b32_e64 v4, v4, v6, s[38:39]
	v_add_u32_e32 v6, 1, v2
	v_cmp_ge_u32_e64 s[38:39], v4, v5
	v_bfe_u32 v42, v16, 2, 6
	s_lshl_b32 s18, s25, 1
	v_cndmask_b32_e64 v2, v2, v6, s[38:39]
	v_xor_b32_e32 v2, v2, v1
	v_sub_u32_e32 v1, v2, v1
	v_lshlrev_b32_e32 v28, 6, v1
	v_mul_lo_u32 v1, v1, v3
	v_sub_u32_e32 v0, v0, v1
	v_lshlrev_b32_e32 v30, 6, v0
	v_mul_lo_u32 v2, v22, v27
	v_mul_lo_u32 v3, v23, v17
	v_mad_u64_u32 v[0:1], s[14:15], v22, v17, 0
	v_add3_u32 v1, v1, v2, v3
	v_lshl_add_u64 v[0:1], v[0:1], 2, v[18:19]
	v_mad_i64_i32 v[2:3], s[14:15], v30, v41, 0
	v_ashrrev_i32_e32 v29, 31, v28
	v_lshl_add_u64 v[0:1], v[2:3], 2, v[0:1]
	v_lshl_add_u64 v[0:1], v[28:29], 2, v[0:1]
	v_lshl_add_u64 v[8:9], v[0:1], 0, v[192:193]
	v_mad_i64_i32 v[0:1], s[14:15], v41, v38, 0
	v_mad_i64_i32 v[2:3], s[14:15], v41, v36, 0
	v_lshl_add_u64 v[0:1], v[0:1], 2, v[8:9]
	v_lshl_add_u64 v[4:5], v[2:3], 2, v[8:9]
	v_lshl_add_u64 v[10:11], v[10:11], 2, v[8:9]
	v_lshl_add_u64 v[12:13], v[12:13], 2, v[8:9]
	flat_load_dwordx4 v[0:3], v[0:1] nt
	s_nop 0
	flat_load_dwordx4 v[4:7], v[4:5] nt
	s_nop 0
	flat_load_dwordx4 v[8:11], v[10:11] nt
	s_nop 0
	flat_load_dwordx4 v[12:15], v[12:13] nt
	v_mul_lo_u32 v23, v24, v27
	v_mad_u64_u32 v[18:19], s[14:15], v24, v17, 0
	v_add3_u32 v19, v19, v23, v25
	v_lshl_add_u64 v[18:19], v[18:19], 1, v[20:21]
	v_mad_i64_i32 v[20:21], s[14:15], v28, v40, 0
	v_lshl_add_u64 v[18:19], v[20:21], 1, v[18:19]
	v_ashrrev_i32_e32 v31, 31, v30
	v_lshl_add_u64 v[44:45], v[30:31], 1, v[18:19]
	v_lshlrev_b32_e32 v18, 4, v16
	v_and_b32_e32 v18, 48, v18
	v_mul_i32_i24_e32 v22, 0x4100, v33
	v_and_b32_e32 v16, 0xfc, v16
	v_mul_u32_u24_e32 v21, 0x41, v18
	v_cndmask_b32_e64 v41, 0, 1, vcc
	v_or_b32_e32 v17, v22, v192
	v_or_b32_e32 v19, v22, v16
	v_mul_u32_u24_e32 v20, 0x104, v32
	v_lshlrev_b32_e32 v21, 2, v21
	v_add_u32_e32 v35, v19, v21
	v_add3_u32 v37, v22, v21, v16
	v_lshlrev_b32_e32 v192, 2, v26
	v_add_u32_e32 v39, v17, v20
	v_lshlrev_b32_e32 v46, 1, v18
	v_mov_b32_e32 v43, v41
	v_mov_b64_e32 v[50:51], v[44:45]
	s_branch .LBB0_632

; DI int otid() { int t = threadIdx.x; asm volatile("" : "+v"(t)); return t; }
; DI int obid() { int t = blockIdx.x; asm volatile("" : "+s"(t)); return t; }
; DI int ogrid() { int t = gridDim.x; asm volatile("" : "+s"(t)); return t; }
; DI CvTile cv_tile(const Job* jobs, int t, int c0, int c1) {
;   CvTile r; r.valid = t < c1; r.pad = 0;
;   int j = 0, tt = r.valid ? t : c0;
;   while (tt >= jobs[j].tiles) { tt -= jobs[j].tiles; ++j; }
;   const Job jb = jobs[j];
;   const int tk = jb.K >> 6, tn = jb.N >> 6, per = tk * tn;
;   const int bi = tt / per, rr = tt % per, kt = rr % tk, nt = rr / tk;
;   r.src = jb.src + (size_t)bi * jb.ss + (size_t)(kt * 64) * jb.N + nt * 64;
;   r.dst = jb.dst + (size_t)bi * jb.ds + (size_t)(nt * 64) * jb.K + kt * 64;
;   r.N = jb.N; r.K = jb.K;
;   return r;
; }
;   if (c0 >= c1) return;
;   const int tid = otid(), G = widx < 0 ? ogrid() : wn, b = widx < 0 ? obid() : widx;
;   float* smf = (float*)smraw;
;   const int half = tid >> 8, vt = tid & 255;
;   float* smh = smf + half * (64 * 65);
;   const int kr = vt >> 4, nc = (vt & 15) * 4;
;   int t0 = c0 + b * 2;
;   if (t0 >= c1) { __syncthreads(); return; }
;   CvTile cur = cv_tile(g_jobs, t0 + half, c0, c1);
;   float4 v[4];
; #pragma unroll
;   for (int i = 0; i < 4; ++i) v[i] = *(const float4*)(cur.src + (size_t)(kr + 16 * i) * cur.N + nc);
.LBB0_944:
	s_or_b64 exec, exec, s[0:1]
	ds_read_b64 v[40:41], v1 offset:16
	ds_read2_b64 v[18:21], v1 offset1:1
	v_lshlrev_b32_e32 v2, 2, v16
	v_and_b32_e32 v26, 60, v2
	v_sub_u32_e32 v6, 0, v0
	s_waitcnt lgkmcnt(1)
	v_ashrrev_i32_e32 v2, 6, v41
	v_ashrrev_i32_e32 v3, 6, v40
	v_mul_lo_u32 v2, v3, v2
	v_sub_u32_e32 v4, 0, v2
	v_max_i32_e32 v4, v2, v4
	v_cvt_f32_u32_e32 v5, v4
	v_sub_u32_e32 v7, 0, v4
	v_max_i32_e32 v6, v0, v6
	ds_read2_b64 v[22:25], v1 offset0:4 offset1:5
	v_rcp_iflag_f32_e32 v5, v5
	v_xor_b32_e32 v1, v0, v2
	v_ashrrev_i32_e32 v1, 31, v1
	v_bfe_u32 v32, v16, 4, 4
	v_mul_f32_e32 v5, 0x4f7ffffe, v5
	v_cvt_u32_f32_e32 v5, v5
	v_or_b32_e32 v34, 16, v32
	v_or_b32_e32 v36, 32, v32
	v_or_b32_e32 v38, 48, v32
	v_mul_lo_u32 v7, v7, v5
	v_mul_hi_u32 v7, v5, v7
	v_add_u32_e32 v5, v5, v7
	v_mul_hi_u32 v5, v6, v5
	v_mul_lo_u32 v7, v5, v4
	v_sub_u32_e32 v6, v6, v7
	v_add_u32_e32 v7, 1, v5
	v_cmp_ge_u32_e64 s[38:39], v6, v4
	v_lshlrev_b32_e32 v192, 2, v26
	v_mad_i64_i32 v[10:11], s[0:1], v41, v34, 0
	v_cndmask_b32_e64 v5, v5, v7, s[38:39]
	v_sub_u32_e32 v7, v6, v4
	v_cndmask_b32_e64 v6, v6, v7, s[38:39]
	v_add_u32_e32 v7, 1, v5
	v_cmp_ge_u32_e64 s[38:39], v6, v4
	v_mad_i64_i32 v[12:13], s[0:1], v41, v32, 0
	s_nop 0
	v_cndmask_b32_e64 v4, v5, v7, s[38:39]
	v_sub_u32_e32 v5, 0, v3
	v_max_i32_e32 v5, v3, v5
	v_cvt_f32_u32_e32 v6, v5
	v_xor_b32_e32 v4, v4, v1
	v_sub_u32_e32 v17, v4, v1
	v_mul_lo_u32 v1, v17, v2
	v_rcp_iflag_f32_e32 v2, v6
	v_sub_u32_e32 v6, 0, v5
	v_sub_u32_e32 v0, v0, v1
	v_sub_u32_e32 v4, 0, v0
	v_mul_f32_e32 v2, 0x4f7ffffe, v2
	v_cvt_u32_f32_e32 v2, v2
	v_max_i32_e32 v4, v0, v4
	v_xor_b32_e32 v1, v0, v3
	v_ashrrev_i32_e32 v1, 31, v1
	v_mul_lo_u32 v6, v6, v2
	v_mul_hi_u32 v6, v2, v6
	v_add_u32_e32 v2, v2, v6
	v_mul_hi_u32 v2, v4, v2
	v_mul_lo_u32 v6, v2, v5
	v_sub_u32_e32 v4, v4, v6
	v_add_u32_e32 v6, 1, v2
	v_cmp_ge_u32_e64 s[38:39], v4, v5
	v_ashrrev_i32_e32 v27, 31, v17
	s_waitcnt lgkmcnt(0)
	v_mul_lo_u32 v25, v25, v17
	v_cndmask_b32_e64 v2, v2, v6, s[38:39]
	v_sub_u32_e32 v6, v4, v5
	v_cndmask_b32_e64 v4, v4, v6, s[38:39]
	v_add_u32_e32 v6, 1, v2
	v_cmp_ge_u32_e64 s[38:39], v4, v5
	v_bfe_u32 v42, v16, 2, 6
	s_lshl_b32 s18, s25, 1
	v_cndmask_b32_e64 v2, v2, v6, s[38:39]
	v_xor_b32_e32 v2, v2, v1
	v_sub_u32_e32 v1, v2, v1
	v_lshlrev_b32_e32 v28, 6, v1
	v_mul_lo_u32 v1, v1, v3
	v_sub_u32_e32 v0, v0, v1
	v_lshlrev_b32_e32 v30, 6, v0
	v_mul_lo_u32 v2, v22, v27
	v_mul_lo_u32 v3, v23, v17
	v_mad_u64_u32 v[0:1], s[0:1], v22, v17, 0
	v_add3_u32 v1, v1, v2, v3
	v_lshl_add_u64 v[0:1], v[0:1], 2, v[18:19]
	v_mad_i64_i32 v[2:3], s[0:1], v30, v41, 0
	v_ashrrev_i32_e32 v29, 31, v28
	v_lshl_add_u64 v[0:1], v[2:3], 2, v[0:1]
	v_lshl_add_u64 v[0:1], v[28:29], 2, v[0:1]
	v_lshl_add_u64 v[8:9], v[0:1], 0, v[192:193]
	v_mad_i64_i32 v[0:1], s[0:1], v41, v38, 0
	v_mad_i64_i32 v[2:3], s[0:1], v41, v36, 0
	v_lshl_add_u64 v[0:1], v[0:1], 2, v[8:9]
	v_lshl_add_u64 v[4:5], v[2:3], 2, v[8:9]
	v_lshl_add_u64 v[10:11], v[10:11], 2, v[8:9]
	v_lshl_add_u64 v[12:13], v[12:13], 2, v[8:9]
	flat_load_dwordx4 v[0:3], v[0:1] nt
	s_nop 0
	flat_load_dwordx4 v[4:7], v[4:5] nt
	s_nop 0
	flat_load_dwordx4 v[8:11], v[10:11] nt
	s_nop 0
	flat_load_dwordx4 v[12:15], v[12:13] nt
	v_mul_lo_u32 v23, v24, v27
	v_mad_u64_u32 v[18:19], s[0:1], v24, v17, 0
	v_add3_u32 v19, v19, v23, v25
	v_lshl_add_u64 v[18:19], v[18:19], 1, v[20:21]
	v_mad_i64_i32 v[20:21], s[0:1], v28, v40, 0
	v_lshl_add_u64 v[18:19], v[20:21], 1, v[18:19]
	v_ashrrev_i32_e32 v31, 31, v30
	v_lshl_add_u64 v[44:45], v[30:31], 1, v[18:19]
	v_lshlrev_b32_e32 v18, 4, v16
	v_and_b32_e32 v18, 48, v18
	v_mul_i32_i24_e32 v22, 0x4100, v33
	v_and_b32_e32 v16, 0xfc, v16
	v_mul_u32_u24_e32 v21, 0x41, v18
	v_cndmask_b32_e64 v41, 0, 1, vcc
	v_or_b32_e32 v17, v22, v192
	v_or_b32_e32 v19, v22, v16
	v_mul_u32_u24_e32 v20, 0x104, v32
	v_lshlrev_b32_e32 v21, 2, v21
	v_add_u32_e32 v35, v19, v21
	v_add3_u32 v37, v22, v21, v16
	v_lshlrev_b32_e32 v192, 2, v26
	v_add_u32_e32 v39, v17, v20
	v_lshlrev_b32_e32 v46, 1, v18
	v_mov_b32_e32 v43, v41
	v_mov_b64_e32 v[50:51], v[44:45]
	s_branch .LBB0_946

; DI int otid() { int t = threadIdx.x; asm volatile("" : "+v"(t)); return t; }
; DI int obid() { int t = blockIdx.x; asm volatile("" : "+s"(t)); return t; }
; DI int ogrid() { int t = gridDim.x; asm volatile("" : "+s"(t)); return t; }
; DI CvTile cv_tile(const Job* jobs, int t, int c0, int c1) {
;   CvTile r; r.valid = t < c1; r.pad = 0;
;   int j = 0, tt = r.valid ? t : c0;
;   while (tt >= jobs[j].tiles) { tt -= jobs[j].tiles; ++j; }
;   const Job jb = jobs[j];
;   const int tk = jb.K >> 6, tn = jb.N >> 6, per = tk * tn;
;   const int bi = tt / per, rr = tt % per, kt = rr % tk, nt = rr / tk;
;   r.src = jb.src + (size_t)bi * jb.ss + (size_t)(kt * 64) * jb.N + nt * 64;
;   r.dst = jb.dst + (size_t)bi * jb.ds + (size_t)(nt * 64) * jb.K + kt * 64;
;   r.N = jb.N; r.K = jb.K;
;   return r;
; }
;   if (c0 >= c1) return;
;   const int tid = otid(), G = widx < 0 ? ogrid() : wn, b = widx < 0 ? obid() : widx;
;   float* smf = (float*)smraw;
;   const int half = tid >> 8, vt = tid & 255;
;   float* smh = smf + half * (64 * 65);
;   const int kr = vt >> 4, nc = (vt & 15) * 4;
;   int t0 = c0 + b * 2;
;   if (t0 >= c1) { __syncthreads(); return; }
;   CvTile cur = cv_tile(g_jobs, t0 + half, c0, c1);
;   float4 v[4];
; #pragma unroll
;   for (int i = 0; i < 4; ++i) v[i] = *(const float4*)(cur.src + (size_t)(kr + 16 * i) * cur.N + nc);
.LBB0_961:
	s_or_b64 exec, exec, s[0:1]
	ds_read_b64 v[40:41], v1 offset:16
	ds_read2_b64 v[18:21], v1 offset1:1
	v_lshlrev_b32_e32 v2, 2, v16
	v_and_b32_e32 v26, 60, v2
	v_sub_u32_e32 v6, 0, v0
	s_waitcnt lgkmcnt(1)
	v_ashrrev_i32_e32 v2, 6, v41
	v_ashrrev_i32_e32 v3, 6, v40
	v_mul_lo_u32 v2, v3, v2
	v_sub_u32_e32 v4, 0, v2
	v_max_i32_e32 v4, v2, v4
	v_cvt_f32_u32_e32 v5, v4
	v_sub_u32_e32 v7, 0, v4
	v_max_i32_e32 v6, v0, v6
	ds_read2_b64 v[22:25], v1 offset0:4 offset1:5
	v_rcp_iflag_f32_e32 v5, v5
	v_xor_b32_e32 v1, v0, v2
	v_ashrrev_i32_e32 v1, 31, v1
	v_bfe_u32 v32, v16, 4, 4
	v_mul_f32_e32 v5, 0x4f7ffffe, v5
	v_cvt_u32_f32_e32 v5, v5
	v_or_b32_e32 v34, 16, v32
	v_or_b32_e32 v36, 32, v32
	v_or_b32_e32 v38, 48, v32
	v_mul_lo_u32 v7, v7, v5
	v_mul_hi_u32 v7, v5, v7
	v_add_u32_e32 v5, v5, v7
	v_mul_hi_u32 v5, v6, v5
	v_mul_lo_u32 v7, v5, v4
	v_sub_u32_e32 v6, v6, v7
	v_add_u32_e32 v7, 1, v5
	v_cmp_ge_u32_e64 s[38:39], v6, v4
	v_lshlrev_b32_e32 v192, 2, v26
	v_mad_i64_i32 v[10:11], s[0:1], v41, v34, 0
	v_cndmask_b32_e64 v5, v5, v7, s[38:39]
	v_sub_u32_e32 v7, v6, v4
	v_cndmask_b32_e64 v6, v6, v7, s[38:39]
	v_add_u32_e32 v7, 1, v5
	v_cmp_ge_u32_e64 s[38:39], v6, v4
	v_mad_i64_i32 v[12:13], s[0:1], v41, v32, 0
	s_nop 0
	v_cndmask_b32_e64 v4, v5, v7, s[38:39]
	v_sub_u32_e32 v5, 0, v3
	v_max_i32_e32 v5, v3, v5
	v_cvt_f32_u32_e32 v6, v5
	v_xor_b32_e32 v4, v4, v1
	v_sub_u32_e32 v17, v4, v1
	v_mul_lo_u32 v1, v17, v2
	v_rcp_iflag_f32_e32 v2, v6
	v_sub_u32_e32 v6, 0, v5
	v_sub_u32_e32 v0, v0, v1
	v_sub_u32_e32 v4, 0, v0
	v_mul_f32_e32 v2, 0x4f7ffffe, v2
	v_cvt_u32_f32_e32 v2, v2
	v_max_i32_e32 v4, v0, v4
	v_xor_b32_e32 v1, v0, v3
	v_ashrrev_i32_e32 v1, 31, v1
	v_mul_lo_u32 v6, v6, v2
	v_mul_hi_u32 v6, v2, v6
	v_add_u32_e32 v2, v2, v6
	v_mul_hi_u32 v2, v4, v2
	v_mul_lo_u32 v6, v2, v5
	v_sub_u32_e32 v4, v4, v6
	v_add_u32_e32 v6, 1, v2
	v_cmp_ge_u32_e64 s[38:39], v4, v5
	v_ashrrev_i32_e32 v27, 31, v17
	s_waitcnt lgkmcnt(0)
	v_mul_lo_u32 v25, v25, v17
	v_cndmask_b32_e64 v2, v2, v6, s[38:39]
	v_sub_u32_e32 v6, v4, v5
	v_cndmask_b32_e64 v4, v4, v6, s[38:39]
	v_add_u32_e32 v6, 1, v2
	v_cmp_ge_u32_e64 s[38:39], v4, v5
	v_bfe_u32 v42, v16, 2, 6
	s_lshl_b32 s24, s16, 1
	v_cndmask_b32_e64 v2, v2, v6, s[38:39]
	v_xor_b32_e32 v2, v2, v1
	v_sub_u32_e32 v1, v2, v1
	v_lshlrev_b32_e32 v28, 6, v1
	v_mul_lo_u32 v1, v1, v3
	v_sub_u32_e32 v0, v0, v1
	v_lshlrev_b32_e32 v30, 6, v0
	v_mul_lo_u32 v2, v22, v27
	v_mul_lo_u32 v3, v23, v17
	v_mad_u64_u32 v[0:1], s[0:1], v22, v17, 0
	v_add3_u32 v1, v1, v2, v3
	v_lshl_add_u64 v[0:1], v[0:1], 2, v[18:19]
	v_mad_i64_i32 v[2:3], s[0:1], v30, v41, 0
	v_ashrrev_i32_e32 v29, 31, v28
	v_lshl_add_u64 v[0:1], v[2:3], 2, v[0:1]
	v_lshl_add_u64 v[0:1], v[28:29], 2, v[0:1]
	v_lshl_add_u64 v[8:9], v[0:1], 0, v[192:193]
	v_mad_i64_i32 v[0:1], s[0:1], v41, v38, 0
	v_mad_i64_i32 v[2:3], s[0:1], v41, v36, 0
	v_lshl_add_u64 v[0:1], v[0:1], 2, v[8:9]
	v_lshl_add_u64 v[4:5], v[2:3], 2, v[8:9]
	v_lshl_add_u64 v[10:11], v[10:11], 2, v[8:9]
	v_lshl_add_u64 v[12:13], v[12:13], 2, v[8:9]
	flat_load_dwordx4 v[0:3], v[0:1] nt
	s_nop 0
	flat_load_dwordx4 v[4:7], v[4:5] nt
	s_nop 0
	flat_load_dwordx4 v[8:11], v[10:11] nt
	s_nop 0
	flat_load_dwordx4 v[12:15], v[12:13] nt
	v_mul_lo_u32 v23, v24, v27
	v_mad_u64_u32 v[18:19], s[0:1], v24, v17, 0
	v_add3_u32 v19, v19, v23, v25
	v_lshl_add_u64 v[18:19], v[18:19], 1, v[20:21]
	v_mad_i64_i32 v[20:21], s[0:1], v28, v40, 0
	v_lshl_add_u64 v[18:19], v[20:21], 1, v[18:19]
	v_ashrrev_i32_e32 v31, 31, v30
	v_lshl_add_u64 v[44:45], v[30:31], 1, v[18:19]
	v_lshlrev_b32_e32 v18, 4, v16
	v_and_b32_e32 v18, 48, v18
	v_mul_i32_i24_e32 v22, 0x4100, v33
	v_and_b32_e32 v16, 0xfc, v16
	v_mul_u32_u24_e32 v21, 0x41, v18
	v_cndmask_b32_e64 v41, 0, 1, vcc
	v_or_b32_e32 v17, v22, v192
	v_or_b32_e32 v19, v22, v16
	v_mul_u32_u24_e32 v20, 0x104, v32
	v_lshlrev_b32_e32 v21, 2, v21
	v_add_u32_e32 v35, v19, v21
	v_add3_u32 v37, v22, v21, v16
	v_lshlrev_b32_e32 v192, 2, v26
	v_add_u32_e32 v39, v17, v20
	v_lshlrev_b32_e32 v46, 1, v18
	v_mov_b32_e32 v43, v41
	v_mov_b64_e32 v[50:51], v[44:45]
	s_branch .LBB0_963

; DI int otid() { int t = threadIdx.x; asm volatile("" : "+v"(t)); return t; }
; DI int obid() { int t = blockIdx.x; asm volatile("" : "+s"(t)); return t; }
; DI int ogrid() { int t = gridDim.x; asm volatile("" : "+s"(t)); return t; }
; DI CvTile cv_tile(const Job* jobs, int t, int c0, int c1) {
;   CvTile r; r.valid = t < c1; r.pad = 0;
;   int j = 0, tt = r.valid ? t : c0;
;   while (tt >= jobs[j].tiles) { tt -= jobs[j].tiles; ++j; }
;   const Job jb = jobs[j];
;   const int tk = jb.K >> 6, tn = jb.N >> 6, per = tk * tn;
;   const int bi = tt / per, rr = tt % per, kt = rr % tk, nt = rr / tk;
;   r.src = jb.src + (size_t)bi * jb.ss + (size_t)(kt * 64) * jb.N + nt * 64;
;   r.dst = jb.dst + (size_t)bi * jb.ds + (size_t)(nt * 64) * jb.K + kt * 64;
;   r.N = jb.N; r.K = jb.K;
;   return r;
; }
;   if (c0 >= c1) return;
;   const int tid = otid(), G = widx < 0 ? ogrid() : wn, b = widx < 0 ? obid() : widx;
;   float* smf = (float*)smraw;
;   const int half = tid >> 8, vt = tid & 255;
;   float* smh = smf + half * (64 * 65);
;   const int kr = vt >> 4, nc = (vt & 15) * 4;
;   int t0 = c0 + b * 2;
;   if (t0 >= c1) { __syncthreads(); return; }
;   CvTile cur = cv_tile(g_jobs, t0 + half, c0, c1);
;   float4 v[4];
; #pragma unroll
;   for (int i = 0; i < 4; ++i) v[i] = *(const float4*)(cur.src + (size_t)(kr + 16 * i) * cur.N + nc);
.LBB0_1096:
	s_or_b64 exec, exec, s[14:15]
	ds_read_b64 v[40:41], v1 offset:16
	ds_read2_b64 v[18:21], v1 offset1:1
	v_lshlrev_b32_e32 v2, 2, v16
	v_and_b32_e32 v26, 60, v2
	v_sub_u32_e32 v6, 0, v0
	s_waitcnt lgkmcnt(1)
	v_ashrrev_i32_e32 v2, 6, v41
	v_ashrrev_i32_e32 v3, 6, v40
	v_mul_lo_u32 v2, v3, v2
	v_sub_u32_e32 v4, 0, v2
	v_max_i32_e32 v4, v2, v4
	v_cvt_f32_u32_e32 v5, v4
	v_sub_u32_e32 v7, 0, v4
	v_max_i32_e32 v6, v0, v6
	ds_read2_b64 v[22:25], v1 offset0:4 offset1:5
	v_rcp_iflag_f32_e32 v5, v5
	v_xor_b32_e32 v1, v0, v2
	v_ashrrev_i32_e32 v1, 31, v1
	v_bfe_u32 v32, v16, 4, 4
	v_mul_f32_e32 v5, 0x4f7ffffe, v5
	v_cvt_u32_f32_e32 v5, v5
	v_or_b32_e32 v34, 16, v32
	v_or_b32_e32 v36, 32, v32
	v_or_b32_e32 v38, 48, v32
	v_mul_lo_u32 v7, v7, v5
	v_mul_hi_u32 v7, v5, v7
	v_add_u32_e32 v5, v5, v7
	v_mul_hi_u32 v5, v6, v5
	v_mul_lo_u32 v7, v5, v4
	v_sub_u32_e32 v6, v6, v7
	v_add_u32_e32 v7, 1, v5
	v_cmp_ge_u32_e64 s[40:41], v6, v4
	v_lshlrev_b32_e32 v192, 2, v26
	v_mad_i64_i32 v[10:11], s[14:15], v41, v34, 0
	v_cndmask_b32_e64 v5, v5, v7, s[40:41]
	v_sub_u32_e32 v7, v6, v4
	v_cndmask_b32_e64 v6, v6, v7, s[40:41]
	v_add_u32_e32 v7, 1, v5
	v_cmp_ge_u32_e64 s[40:41], v6, v4
	v_mad_i64_i32 v[12:13], s[14:15], v41, v32, 0
	s_nop 0
	v_cndmask_b32_e64 v4, v5, v7, s[40:41]
	v_sub_u32_e32 v5, 0, v3
	v_max_i32_e32 v5, v3, v5
	v_cvt_f32_u32_e32 v6, v5
	v_xor_b32_e32 v4, v4, v1
	v_sub_u32_e32 v17, v4, v1
	v_mul_lo_u32 v1, v17, v2
	v_rcp_iflag_f32_e32 v2, v6
	v_sub_u32_e32 v6, 0, v5
	v_sub_u32_e32 v0, v0, v1
	v_sub_u32_e32 v4, 0, v0
	v_mul_f32_e32 v2, 0x4f7ffffe, v2
	v_cvt_u32_f32_e32 v2, v2
	v_max_i32_e32 v4, v0, v4
	v_xor_b32_e32 v1, v0, v3
	v_ashrrev_i32_e32 v1, 31, v1
	v_mul_lo_u32 v6, v6, v2
	v_mul_hi_u32 v6, v2, v6
	v_add_u32_e32 v2, v2, v6
	v_mul_hi_u32 v2, v4, v2
	v_mul_lo_u32 v6, v2, v5
	v_sub_u32_e32 v4, v4, v6
	v_add_u32_e32 v6, 1, v2
	v_cmp_ge_u32_e64 s[40:41], v4, v5
	v_ashrrev_i32_e32 v27, 31, v17
	s_waitcnt lgkmcnt(0)
	v_mul_lo_u32 v25, v25, v17
	v_cndmask_b32_e64 v2, v2, v6, s[40:41]
	v_sub_u32_e32 v6, v4, v5
	v_cndmask_b32_e64 v4, v4, v6, s[40:41]
	v_add_u32_e32 v6, 1, v2
	v_cmp_ge_u32_e64 s[40:41], v4, v5
	v_bfe_u32 v42, v16, 2, 6
	s_lshl_b32 s31, s24, 4
	v_cndmask_b32_e64 v2, v2, v6, s[40:41]
	v_xor_b32_e32 v2, v2, v1
	v_sub_u32_e32 v1, v2, v1
	v_lshlrev_b32_e32 v28, 6, v1
	v_mul_lo_u32 v1, v1, v3
	v_sub_u32_e32 v0, v0, v1
	v_lshlrev_b32_e32 v30, 6, v0
	v_mul_lo_u32 v2, v22, v27
	v_mul_lo_u32 v3, v23, v17
	v_mad_u64_u32 v[0:1], s[14:15], v22, v17, 0
	v_add3_u32 v1, v1, v2, v3
	v_lshl_add_u64 v[0:1], v[0:1], 2, v[18:19]
	v_mad_i64_i32 v[2:3], s[14:15], v30, v41, 0
	v_ashrrev_i32_e32 v29, 31, v28
	v_lshl_add_u64 v[0:1], v[2:3], 2, v[0:1]
	v_lshl_add_u64 v[0:1], v[28:29], 2, v[0:1]
	v_lshl_add_u64 v[8:9], v[0:1], 0, v[192:193]
	v_mad_i64_i32 v[0:1], s[14:15], v41, v38, 0
	v_mad_i64_i32 v[2:3], s[14:15], v41, v36, 0
	v_lshl_add_u64 v[0:1], v[0:1], 2, v[8:9]
	v_lshl_add_u64 v[4:5], v[2:3], 2, v[8:9]
	v_lshl_add_u64 v[10:11], v[10:11], 2, v[8:9]
	v_lshl_add_u64 v[12:13], v[12:13], 2, v[8:9]
	flat_load_dwordx4 v[0:3], v[0:1] nt
	s_nop 0
	flat_load_dwordx4 v[4:7], v[4:5] nt
	s_nop 0
	flat_load_dwordx4 v[8:11], v[10:11] nt
	s_nop 0
	flat_load_dwordx4 v[12:15], v[12:13] nt
	v_mul_lo_u32 v23, v24, v27
	v_mad_u64_u32 v[18:19], s[14:15], v24, v17, 0
	v_add3_u32 v19, v19, v23, v25
	v_lshl_add_u64 v[18:19], v[18:19], 1, v[20:21]
	v_mad_i64_i32 v[20:21], s[14:15], v28, v40, 0
	v_lshl_add_u64 v[18:19], v[20:21], 1, v[18:19]
	v_ashrrev_i32_e32 v31, 31, v30
	v_lshl_add_u64 v[44:45], v[30:31], 1, v[18:19]
	v_lshlrev_b32_e32 v18, 4, v16
	v_and_b32_e32 v18, 48, v18
	v_mul_i32_i24_e32 v22, 0x4100, v33
	v_and_b32_e32 v16, 0xfc, v16
	v_mul_u32_u24_e32 v21, 0x41, v18
	v_cndmask_b32_e64 v41, 0, 1, vcc
	v_or_b32_e32 v17, v22, v192
	v_or_b32_e32 v19, v22, v16
	v_mul_u32_u24_e32 v20, 0x104, v32
	v_lshlrev_b32_e32 v21, 2, v21
	v_add_u32_e32 v35, v19, v21
	v_add3_u32 v37, v22, v21, v16
	v_lshlrev_b32_e32 v192, 2, v26
	v_add_u32_e32 v39, v17, v20
	v_lshlrev_b32_e32 v46, 1, v18
	v_mov_b32_e32 v43, v41
	v_mov_b64_e32 v[50:51], v[44:45]
	s_branch .LBB0_1098

; DI int otid() { int t = threadIdx.x; asm volatile("" : "+v"(t)); return t; }
; DI int obid() { int t = blockIdx.x; asm volatile("" : "+s"(t)); return t; }
; DI int ogrid() { int t = gridDim.x; asm volatile("" : "+s"(t)); return t; }
; DI CvTile cv_tile(const Job* jobs, int t, int c0, int c1) {
;   CvTile r; r.valid = t < c1; r.pad = 0;
;   int j = 0, tt = r.valid ? t : c0;
;   while (tt >= jobs[j].tiles) { tt -= jobs[j].tiles; ++j; }
;   const Job jb = jobs[j];
;   const int tk = jb.K >> 6, tn = jb.N >> 6, per = tk * tn;
;   const int bi = tt / per, rr = tt % per, kt = rr % tk, nt = rr / tk;
;   r.src = jb.src + (size_t)bi * jb.ss + (size_t)(kt * 64) * jb.N + nt * 64;
;   r.dst = jb.dst + (size_t)bi * jb.ds + (size_t)(nt * 64) * jb.K + kt * 64;
;   r.N = jb.N; r.K = jb.K;
;   return r;
; }
;   if (c0 >= c1) return;
;   const int tid = otid(), G = widx < 0 ? ogrid() : wn, b = widx < 0 ? obid() : widx;
;   float* smf = (float*)smraw;
;   const int half = tid >> 8, vt = tid & 255;
;   float* smh = smf + half * (64 * 65);
;   const int kr = vt >> 4, nc = (vt & 15) * 4;
;   int t0 = c0 + b * 2;
;   if (t0 >= c1) { __syncthreads(); return; }
;   CvTile cur = cv_tile(g_jobs, t0 + half, c0, c1);
;   float4 v[4];
; #pragma unroll
;   for (int i = 0; i < 4; ++i) v[i] = *(const float4*)(cur.src + (size_t)(kr + 16 * i) * cur.N + nc);
;   for (; t0 < c1; t0 += 2 * G) {
;     const bool more = t0 + 2 * G < c1;
;     CvTile nx = cur; float4 vn[4];
;     if (more) {
;       nx = cv_tile(g_jobs, t0 + 2 * G + half, c0, c1);
; #pragma unroll
;       for (int i = 0; i < 4; ++i) vn[i] = *(const float4*)(nx.src + (size_t)(kr + 16 * i) * nx.N + nc);
.LBB0_1103:
	s_or_b64 exec, exec, s[16:17]
	ds_read2_b64 v[16:19], v20 offset1:1
	ds_read_b64 v[48:49], v20 offset:16
	ds_read2_b64 v[20:23], v20 offset0:4 offset1:5
	v_sub_u32_e32 v28, 0, v24
	v_max_i32_e32 v28, v24, v28
	v_cndmask_b32_e64 v43, 0, 1, vcc
	s_waitcnt lgkmcnt(0)
	v_ashrrev_i32_e32 v25, 6, v48
	v_ashrrev_i32_e32 v26, 6, v49
	v_mul_lo_u32 v26, v26, v25
	v_sub_u32_e32 v29, 0, v26
	v_max_i32_e32 v29, v26, v29
	v_cvt_f32_u32_e32 v30, v29
	v_sub_u32_e32 v31, 0, v29
	v_xor_b32_e32 v27, v24, v26
	v_ashrrev_i32_e32 v27, 31, v27
	v_rcp_iflag_f32_e32 v30, v30
	s_nop 0
	v_mul_f32_e32 v30, 0x4f7ffffe, v30
	v_cvt_u32_f32_e32 v30, v30
	v_mul_lo_u32 v31, v31, v30
	v_mul_hi_u32 v31, v30, v31
	v_add_u32_e32 v30, v30, v31
	v_mul_hi_u32 v30, v28, v30
	v_mul_lo_u32 v31, v30, v29
	v_sub_u32_e32 v28, v28, v31
	v_cmp_ge_u32_e64 s[40:41], v28, v29
	v_add_u32_e32 v31, 1, v30
	s_nop 0
	v_cndmask_b32_e64 v30, v30, v31, s[40:41]
	v_sub_u32_e32 v31, v28, v29
	v_cndmask_b32_e64 v28, v28, v31, s[40:41]
	v_cmp_ge_u32_e64 s[40:41], v28, v29
	v_sub_u32_e32 v29, 0, v25
	v_add_u32_e32 v28, 1, v30
	v_max_i32_e32 v29, v25, v29
	v_cndmask_b32_e64 v28, v30, v28, s[40:41]
	v_cvt_f32_u32_e32 v30, v29
	v_xor_b32_e32 v28, v28, v27
	v_sub_u32_e32 v27, v28, v27
	v_mul_lo_u32 v26, v27, v26
	v_rcp_iflag_f32_e32 v30, v30
	v_sub_u32_e32 v31, 0, v29
	v_sub_u32_e32 v24, v24, v26
	v_sub_u32_e32 v28, 0, v24
	v_mul_f32_e32 v30, 0x4f7ffffe, v30
	v_cvt_u32_f32_e32 v30, v30
	v_max_i32_e32 v28, v24, v28
	v_xor_b32_e32 v26, v24, v25
	v_ashrrev_i32_e32 v26, 31, v26
	v_mul_lo_u32 v31, v31, v30
	v_mul_hi_u32 v31, v30, v31
	v_add_u32_e32 v30, v30, v31
	v_mul_hi_u32 v30, v28, v30
	v_mul_lo_u32 v31, v30, v29
	v_sub_u32_e32 v28, v28, v31
	v_cmp_ge_u32_e64 s[40:41], v28, v29
	v_add_u32_e32 v31, 1, v30
	s_nop 0
	v_cndmask_b32_e64 v30, v30, v31, s[40:41]
	v_sub_u32_e32 v31, v28, v29
	v_cndmask_b32_e64 v28, v28, v31, s[40:41]
	v_cmp_ge_u32_e64 s[40:41], v28, v29
	v_add_u32_e32 v28, 1, v30
	v_mul_lo_u32 v29, v21, v27
	v_cndmask_b32_e64 v28, v30, v28, s[40:41]
	v_xor_b32_e32 v28, v28, v26
	v_sub_u32_e32 v26, v28, v26
	v_mul_lo_u32 v25, v26, v25
	v_sub_u32_e32 v24, v24, v25
	v_ashrrev_i32_e32 v25, 31, v27
	v_mul_lo_u32 v28, v20, v25
	v_mad_u64_u32 v[20:21], s[16:17], v20, v27, 0
	v_add3_u32 v21, v21, v28, v29
	v_lshlrev_b32_e32 v50, 6, v24
	v_lshl_add_u64 v[16:17], v[20:21], 2, v[16:17]
	v_mad_i64_i32 v[20:21], s[16:17], v50, v49, 0
	v_lshl_add_u64 v[16:17], v[20:21], 2, v[16:17]
	v_lshlrev_b32_e32 v20, 6, v26
	v_ashrrev_i32_e32 v21, 31, v20
	v_lshl_add_u64 v[16:17], v[20:21], 2, v[16:17]
	v_mul_lo_u32 v21, v22, v25
	v_mul_lo_u32 v24, v23, v27
	v_mad_u64_u32 v[22:23], s[16:17], v22, v27, 0
	v_add3_u32 v23, v23, v21, v24
	v_lshl_add_u64 v[18:19], v[22:23], 1, v[18:19]
	v_mad_i64_i32 v[20:21], s[16:17], v20, v48, 0
	v_lshl_add_u64 v[52:53], v[20:21], 1, v[18:19]
	v_lshl_add_u64 v[28:29], v[16:17], 0, v[192:193]
	v_mad_i64_i32 v[16:17], s[16:17], v49, v32, 0
	v_mad_i64_i32 v[20:21], s[16:17], v49, v34, 0
	v_mad_i64_i32 v[24:25], s[16:17], v49, v36, 0
	v_mad_i64_i32 v[30:31], s[16:17], v49, v38, 0
	v_lshl_add_u64 v[16:17], v[16:17], 2, v[28:29]
	v_lshl_add_u64 v[20:21], v[20:21], 2, v[28:29]
	v_lshl_add_u64 v[24:25], v[24:25], 2, v[28:29]
	v_lshl_add_u64 v[28:29], v[30:31], 2, v[28:29]
	flat_load_dwordx4 v[16:19], v[16:17] nt
	v_ashrrev_i32_e32 v51, 31, v50
	flat_load_dwordx4 v[20:23], v[20:21] nt
	v_lshl_add_u64 v[50:51], v[50:51], 1, v[52:53]
	flat_load_dwordx4 v[24:27], v[24:25] nt
	s_nop 0
	flat_load_dwordx4 v[28:31], v[28:29] nt

; DI int otid() { int t = threadIdx.x; asm volatile("" : "+v"(t)); return t; }
; DI int obid() { int t = blockIdx.x; asm volatile("" : "+s"(t)); return t; }
; DI int ogrid() { int t = gridDim.x; asm volatile("" : "+s"(t)); return t; }
; DI CvTile cv_tile(const Job* jobs, int t, int c0, int c1) {
;   CvTile r; r.valid = t < c1; r.pad = 0;
;   int j = 0, tt = r.valid ? t : c0;
;   while (tt >= jobs[j].tiles) { tt -= jobs[j].tiles; ++j; }
;   const Job jb = jobs[j];
;   const int tk = jb.K >> 6, tn = jb.N >> 6, per = tk * tn;
;   const int bi = tt / per, rr = tt % per, kt = rr % tk, nt = rr / tk;
;   r.src = jb.src + (size_t)bi * jb.ss + (size_t)(kt * 64) * jb.N + nt * 64;
;   r.dst = jb.dst + (size_t)bi * jb.ds + (size_t)(nt * 64) * jb.K + kt * 64;
;   r.N = jb.N; r.K = jb.K;
;   return r;
; }
;   if (c0 >= c1) return;
;   const int tid = otid(), G = widx < 0 ? ogrid() : wn, b = widx < 0 ? obid() : widx;
;   float* smf = (float*)smraw;
;   const int half = tid >> 8, vt = tid & 255;
;   float* smh = smf + half * (64 * 65);
;   const int kr = vt >> 4, nc = (vt & 15) * 4;
;   int t0 = c0 + b * 2;
;   if (t0 >= c1) { __syncthreads(); return; }
;   CvTile cur = cv_tile(g_jobs, t0 + half, c0, c1);
;   float4 v[4];
; #pragma unroll
;   for (int i = 0; i < 4; ++i) v[i] = *(const float4*)(cur.src + (size_t)(kr + 16 * i) * cur.N + nc);
.LBB0_1114:
	s_or_b64 exec, exec, s[0:1]
	ds_read_b64 v[40:41], v1 offset:16
	ds_read2_b64 v[18:21], v1 offset1:1
	v_lshlrev_b32_e32 v2, 2, v16
	v_and_b32_e32 v26, 60, v2
	v_sub_u32_e32 v6, 0, v0
	s_waitcnt lgkmcnt(0)
	v_ashrrev_i32_e32 v2, 6, v41
	v_ashrrev_i32_e32 v3, 6, v40
	v_mul_lo_u32 v2, v3, v2
	v_sub_u32_e32 v4, 0, v2
	v_max_i32_e32 v4, v2, v4
	v_cvt_f32_u32_e32 v5, v4
	v_sub_u32_e32 v7, 0, v4
	v_max_i32_e32 v6, v0, v6
	ds_read2_b64 v[22:25], v1 offset0:4 offset1:5
	v_rcp_iflag_f32_e32 v5, v5
	v_xor_b32_e32 v1, v0, v2
	v_ashrrev_i32_e32 v1, 31, v1
	v_bfe_u32 v32, v16, 4, 4
	v_mul_f32_e32 v5, 0x4f7ffffe, v5
	v_cvt_u32_f32_e32 v5, v5
	v_or_b32_e32 v34, 16, v32
	v_or_b32_e32 v36, 32, v32
	v_or_b32_e32 v38, 48, v32
	v_mul_lo_u32 v7, v7, v5
	v_mul_hi_u32 v7, v5, v7
	v_add_u32_e32 v5, v5, v7
	v_mul_hi_u32 v5, v6, v5
	v_mul_lo_u32 v7, v5, v4
	v_sub_u32_e32 v6, v6, v7
	v_add_u32_e32 v7, 1, v5
	v_cmp_ge_u32_e64 s[40:41], v6, v4
	v_lshlrev_b32_e32 v192, 2, v26
	v_mad_i64_i32 v[10:11], s[0:1], v41, v34, 0
	v_cndmask_b32_e64 v5, v5, v7, s[40:41]
	v_sub_u32_e32 v7, v6, v4
	v_cndmask_b32_e64 v6, v6, v7, s[40:41]
	v_add_u32_e32 v7, 1, v5
	v_cmp_ge_u32_e64 s[40:41], v6, v4
	v_mad_i64_i32 v[12:13], s[0:1], v41, v32, 0
	s_nop 0
	v_cndmask_b32_e64 v4, v5, v7, s[40:41]
	v_sub_u32_e32 v5, 0, v3
	v_max_i32_e32 v5, v3, v5
	v_cvt_f32_u32_e32 v6, v5
	v_xor_b32_e32 v4, v4, v1
	v_sub_u32_e32 v17, v4, v1
	v_mul_lo_u32 v1, v17, v2
	v_rcp_iflag_f32_e32 v2, v6
	v_sub_u32_e32 v6, 0, v5
	v_sub_u32_e32 v0, v0, v1
	v_sub_u32_e32 v4, 0, v0
	v_mul_f32_e32 v2, 0x4f7ffffe, v2
	v_cvt_u32_f32_e32 v2, v2
	v_max_i32_e32 v4, v0, v4
	v_xor_b32_e32 v1, v0, v3
	v_ashrrev_i32_e32 v1, 31, v1
	v_mul_lo_u32 v6, v6, v2
	v_mul_hi_u32 v6, v2, v6
	v_add_u32_e32 v2, v2, v6
	v_mul_hi_u32 v2, v4, v2
	v_mul_lo_u32 v6, v2, v5
	v_sub_u32_e32 v4, v4, v6
	v_add_u32_e32 v6, 1, v2
	v_cmp_ge_u32_e64 s[40:41], v4, v5
	v_ashrrev_i32_e32 v27, 31, v17
	s_waitcnt lgkmcnt(0)
	v_mul_lo_u32 v25, v25, v17
	v_cndmask_b32_e64 v2, v2, v6, s[40:41]
	v_sub_u32_e32 v6, v4, v5
	v_cndmask_b32_e64 v4, v4, v6, s[40:41]
	v_add_u32_e32 v6, 1, v2
	v_cmp_ge_u32_e64 s[40:41], v4, v5
	v_bfe_u32 v42, v16, 2, 6
	s_lshl_b32 s24, s16, 1
	v_cndmask_b32_e64 v2, v2, v6, s[40:41]
	v_xor_b32_e32 v2, v2, v1
	v_sub_u32_e32 v1, v2, v1
	v_lshlrev_b32_e32 v28, 6, v1
	v_mul_lo_u32 v1, v1, v3
	v_sub_u32_e32 v0, v0, v1
	v_lshlrev_b32_e32 v30, 6, v0
	v_mul_lo_u32 v2, v22, v27
	v_mul_lo_u32 v3, v23, v17
	v_mad_u64_u32 v[0:1], s[0:1], v22, v17, 0
	v_add3_u32 v1, v1, v2, v3
	v_lshl_add_u64 v[0:1], v[0:1], 2, v[18:19]
	v_mad_i64_i32 v[2:3], s[0:1], v30, v41, 0
	v_ashrrev_i32_e32 v29, 31, v28
	v_lshl_add_u64 v[0:1], v[2:3], 2, v[0:1]
	v_lshl_add_u64 v[0:1], v[28:29], 2, v[0:1]
	v_lshl_add_u64 v[8:9], v[0:1], 0, v[192:193]
	v_mad_i64_i32 v[0:1], s[0:1], v41, v38, 0
	v_mad_i64_i32 v[2:3], s[0:1], v41, v36, 0
	v_lshl_add_u64 v[0:1], v[0:1], 2, v[8:9]
	v_lshl_add_u64 v[4:5], v[2:3], 2, v[8:9]
	v_lshl_add_u64 v[10:11], v[10:11], 2, v[8:9]
	v_lshl_add_u64 v[12:13], v[12:13], 2, v[8:9]
	flat_load_dwordx4 v[0:3], v[0:1] nt
	s_nop 0
	flat_load_dwordx4 v[4:7], v[4:5] nt
	s_nop 0
	flat_load_dwordx4 v[8:11], v[10:11] nt
	s_nop 0
	flat_load_dwordx4 v[12:15], v[12:13] nt
	v_mul_lo_u32 v23, v24, v27
	v_mad_u64_u32 v[18:19], s[0:1], v24, v17, 0
	v_add3_u32 v19, v19, v23, v25
	v_lshl_add_u64 v[18:19], v[18:19], 1, v[20:21]
	v_mad_i64_i32 v[20:21], s[0:1], v28, v40, 0
	v_lshl_add_u64 v[18:19], v[20:21], 1, v[18:19]
	v_ashrrev_i32_e32 v31, 31, v30
	v_lshl_add_u64 v[44:45], v[30:31], 1, v[18:19]
	v_lshlrev_b32_e32 v18, 4, v16
	v_and_b32_e32 v18, 48, v18
	v_mul_i32_i24_e32 v22, 0x4100, v33
	v_and_b32_e32 v16, 0xfc, v16
	v_mul_u32_u24_e32 v21, 0x41, v18
	v_cndmask_b32_e64 v41, 0, 1, vcc
	v_or_b32_e32 v17, v22, v192
	v_or_b32_e32 v19, v22, v16
	v_mul_u32_u24_e32 v20, 0x104, v32
	v_lshlrev_b32_e32 v21, 2, v21
	v_add_u32_e32 v35, v19, v21
	v_add3_u32 v37, v22, v21, v16
	v_lshlrev_b32_e32 v192, 2, v26
	v_add_u32_e32 v39, v17, v20
	v_lshlrev_b32_e32 v46, 1, v18
	v_mov_b32_e32 v43, v41
	v_mov_b64_e32 v[50:51], v[44:45]
	s_branch .LBB0_1116

; DI int otid() { int t = threadIdx.x; asm volatile("" : "+v"(t)); return t; }
; DI int obid() { int t = blockIdx.x; asm volatile("" : "+s"(t)); return t; }
; DI int ogrid() { int t = gridDim.x; asm volatile("" : "+s"(t)); return t; }
; DI CvTile cv_tile(const Job* jobs, int t, int c0, int c1) {
;   CvTile r; r.valid = t < c1; r.pad = 0;
;   int j = 0, tt = r.valid ? t : c0;
;   while (tt >= jobs[j].tiles) { tt -= jobs[j].tiles; ++j; }
;   const Job jb = jobs[j];
;   const int tk = jb.K >> 6, tn = jb.N >> 6, per = tk * tn;
;   const int bi = tt / per, rr = tt % per, kt = rr % tk, nt = rr / tk;
;   r.src = jb.src + (size_t)bi * jb.ss + (size_t)(kt * 64) * jb.N + nt * 64;
;   r.dst = jb.dst + (size_t)bi * jb.ds + (size_t)(nt * 64) * jb.K + kt * 64;
;   r.N = jb.N; r.K = jb.K;
;   return r;
; }
;   if (c0 >= c1) return;
;   const int tid = otid(), G = widx < 0 ? ogrid() : wn, b = widx < 0 ? obid() : widx;
;   float* smf = (float*)smraw;
;   const int half = tid >> 8, vt = tid & 255;
;   float* smh = smf + half * (64 * 65);
;   const int kr = vt >> 4, nc = (vt & 15) * 4;
;   int t0 = c0 + b * 2;
;   if (t0 >= c1) { __syncthreads(); return; }
;   CvTile cur = cv_tile(g_jobs, t0 + half, c0, c1);
;   float4 v[4];
; #pragma unroll
;   for (int i = 0; i < 4; ++i) v[i] = *(const float4*)(cur.src + (size_t)(kr + 16 * i) * cur.N + nc);
;   for (; t0 < c1; t0 += 2 * G) {
;     const bool more = t0 + 2 * G < c1;
;     CvTile nx = cur; float4 vn[4];
;     if (more) {
;       nx = cv_tile(g_jobs, t0 + 2 * G + half, c0, c1);
; #pragma unroll
;       for (int i = 0; i < 4; ++i) vn[i] = *(const float4*)(nx.src + (size_t)(kr + 16 * i) * nx.N + nc);
.LBB0_1121:
	s_or_b64 exec, exec, s[14:15]
	ds_read2_b64 v[16:19], v20 offset1:1
	ds_read_b64 v[48:49], v20 offset:16
	ds_read2_b64 v[20:23], v20 offset0:4 offset1:5
	v_sub_u32_e32 v28, 0, v24
	v_max_i32_e32 v28, v24, v28
	v_cndmask_b32_e64 v43, 0, 1, vcc
	s_waitcnt lgkmcnt(0)
	v_ashrrev_i32_e32 v25, 6, v48
	v_ashrrev_i32_e32 v26, 6, v49
	v_mul_lo_u32 v26, v26, v25
	v_sub_u32_e32 v29, 0, v26
	v_max_i32_e32 v29, v26, v29
	v_cvt_f32_u32_e32 v30, v29
	v_sub_u32_e32 v31, 0, v29
	v_xor_b32_e32 v27, v24, v26
	v_ashrrev_i32_e32 v27, 31, v27
	v_rcp_iflag_f32_e32 v30, v30
	s_nop 0
	v_mul_f32_e32 v30, 0x4f7ffffe, v30
	v_cvt_u32_f32_e32 v30, v30
	v_mul_lo_u32 v31, v31, v30
	v_mul_hi_u32 v31, v30, v31
	v_add_u32_e32 v30, v30, v31
	v_mul_hi_u32 v30, v28, v30
	v_mul_lo_u32 v31, v30, v29
	v_sub_u32_e32 v28, v28, v31
	v_cmp_ge_u32_e64 s[40:41], v28, v29
	v_add_u32_e32 v31, 1, v30
	s_nop 0
	v_cndmask_b32_e64 v30, v30, v31, s[40:41]
	v_sub_u32_e32 v31, v28, v29
	v_cndmask_b32_e64 v28, v28, v31, s[40:41]
	v_cmp_ge_u32_e64 s[40:41], v28, v29
	v_sub_u32_e32 v29, 0, v25
	v_add_u32_e32 v28, 1, v30
	v_max_i32_e32 v29, v25, v29
	v_cndmask_b32_e64 v28, v30, v28, s[40:41]
	v_cvt_f32_u32_e32 v30, v29
	v_xor_b32_e32 v28, v28, v27
	v_sub_u32_e32 v27, v28, v27
	v_mul_lo_u32 v26, v27, v26
	v_rcp_iflag_f32_e32 v30, v30
	v_sub_u32_e32 v31, 0, v29
	v_sub_u32_e32 v24, v24, v26
	v_sub_u32_e32 v28, 0, v24
	v_mul_f32_e32 v30, 0x4f7ffffe, v30
	v_cvt_u32_f32_e32 v30, v30
	v_max_i32_e32 v28, v24, v28
	v_xor_b32_e32 v26, v24, v25
	v_ashrrev_i32_e32 v26, 31, v26
	v_mul_lo_u32 v31, v31, v30
	v_mul_hi_u32 v31, v30, v31
	v_add_u32_e32 v30, v30, v31
	v_mul_hi_u32 v30, v28, v30
	v_mul_lo_u32 v31, v30, v29
	v_sub_u32_e32 v28, v28, v31
	v_cmp_ge_u32_e64 s[40:41], v28, v29
	v_add_u32_e32 v31, 1, v30
	s_nop 0
	v_cndmask_b32_e64 v30, v30, v31, s[40:41]
	v_sub_u32_e32 v31, v28, v29
	v_cndmask_b32_e64 v28, v28, v31, s[40:41]
	v_cmp_ge_u32_e64 s[40:41], v28, v29
	v_add_u32_e32 v28, 1, v30
	v_mul_lo_u32 v29, v21, v27
	v_cndmask_b32_e64 v28, v30, v28, s[40:41]
	v_xor_b32_e32 v28, v28, v26
	v_sub_u32_e32 v26, v28, v26
	v_mul_lo_u32 v25, v26, v25
	v_sub_u32_e32 v24, v24, v25
	v_ashrrev_i32_e32 v25, 31, v27
	v_mul_lo_u32 v28, v20, v25
	v_mad_u64_u32 v[20:21], s[14:15], v20, v27, 0
	v_add3_u32 v21, v21, v28, v29
	v_lshlrev_b32_e32 v50, 6, v24
	v_lshl_add_u64 v[16:17], v[20:21], 2, v[16:17]
	v_mad_i64_i32 v[20:21], s[14:15], v50, v49, 0
	v_lshl_add_u64 v[16:17], v[20:21], 2, v[16:17]
	v_lshlrev_b32_e32 v20, 6, v26
	v_ashrrev_i32_e32 v21, 31, v20
	v_lshl_add_u64 v[16:17], v[20:21], 2, v[16:17]
	v_mul_lo_u32 v21, v22, v25
	v_mul_lo_u32 v24, v23, v27
	v_mad_u64_u32 v[22:23], s[14:15], v22, v27, 0
	v_add3_u32 v23, v23, v21, v24
	v_lshl_add_u64 v[18:19], v[22:23], 1, v[18:19]
	v_mad_i64_i32 v[20:21], s[14:15], v20, v48, 0
	v_lshl_add_u64 v[52:53], v[20:21], 1, v[18:19]
	v_lshl_add_u64 v[28:29], v[16:17], 0, v[192:193]
	v_mad_i64_i32 v[16:17], s[14:15], v49, v32, 0
	v_mad_i64_i32 v[20:21], s[14:15], v49, v34, 0
	v_mad_i64_i32 v[24:25], s[14:15], v49, v36, 0
	v_mad_i64_i32 v[30:31], s[14:15], v49, v38, 0
	v_lshl_add_u64 v[16:17], v[16:17], 2, v[28:29]
	v_lshl_add_u64 v[20:21], v[20:21], 2, v[28:29]
	v_lshl_add_u64 v[24:25], v[24:25], 2, v[28:29]
	v_lshl_add_u64 v[28:29], v[30:31], 2, v[28:29]
	flat_load_dwordx4 v[16:19], v[16:17] nt
	v_ashrrev_i32_e32 v51, 31, v50
	flat_load_dwordx4 v[20:23], v[20:21] nt
	v_lshl_add_u64 v[50:51], v[50:51], 1, v[52:53]
	flat_load_dwordx4 v[24:27], v[24:25] nt
	s_nop 0
	flat_load_dwordx4 v[28:31], v[28:29] nt

; DI int otid() { int t = threadIdx.x; asm volatile("" : "+v"(t)); return t; }
; DI int obid() { int t = blockIdx.x; asm volatile("" : "+s"(t)); return t; }
; DI int ogrid() { int t = gridDim.x; asm volatile("" : "+s"(t)); return t; }
; DI CvTile cv_tile(const Job* jobs, int t, int c0, int c1) {
;   CvTile r; r.valid = t < c1; r.pad = 0;
;   int j = 0, tt = r.valid ? t : c0;
;   while (tt >= jobs[j].tiles) { tt -= jobs[j].tiles; ++j; }
;   const Job jb = jobs[j];
;   const int tk = jb.K >> 6, tn = jb.N >> 6, per = tk * tn;
;   const int bi = tt / per, rr = tt % per, kt = rr % tk, nt = rr / tk;
;   r.src = jb.src + (size_t)bi * jb.ss + (size_t)(kt * 64) * jb.N + nt * 64;
;   r.dst = jb.dst + (size_t)bi * jb.ds + (size_t)(nt * 64) * jb.K + kt * 64;
;   r.N = jb.N; r.K = jb.K;
;   return r;
; }
;   if (c0 >= c1) return;
;   const int tid = otid(), G = widx < 0 ? ogrid() : wn, b = widx < 0 ? obid() : widx;
;   float* smf = (float*)smraw;
;   const int half = tid >> 8, vt = tid & 255;
;   float* smh = smf + half * (64 * 65);
;   const int kr = vt >> 4, nc = (vt & 15) * 4;
;   int t0 = c0 + b * 2;
;   if (t0 >= c1) { __syncthreads(); return; }
;   CvTile cur = cv_tile(g_jobs, t0 + half, c0, c1);
;   float4 v[4];
; #pragma unroll
;   for (int i = 0; i < 4; ++i) v[i] = *(const float4*)(cur.src + (size_t)(kr + 16 * i) * cur.N + nc);
.LBB0_1450:
	s_or_b64 exec, exec, s[0:1]
	ds_read_b64 v[40:41], v1 offset:16
	ds_read2_b64 v[18:21], v1 offset1:1
	v_lshlrev_b32_e32 v2, 2, v16
	v_and_b32_e32 v26, 60, v2
	v_sub_u32_e32 v6, 0, v0
	s_waitcnt lgkmcnt(0)
	v_ashrrev_i32_e32 v2, 6, v41
	v_ashrrev_i32_e32 v3, 6, v40
	v_mul_lo_u32 v2, v3, v2
	v_sub_u32_e32 v4, 0, v2
	v_max_i32_e32 v4, v2, v4
	v_cvt_f32_u32_e32 v5, v4
	v_sub_u32_e32 v7, 0, v4
	v_max_i32_e32 v6, v0, v6
	ds_read2_b64 v[22:25], v1 offset0:4 offset1:5
	v_rcp_iflag_f32_e32 v5, v5
	v_xor_b32_e32 v1, v0, v2
	v_ashrrev_i32_e32 v1, 31, v1
	v_bfe_u32 v32, v16, 4, 4
	v_mul_f32_e32 v5, 0x4f7ffffe, v5
	v_cvt_u32_f32_e32 v5, v5
	v_or_b32_e32 v34, 16, v32
	v_or_b32_e32 v36, 32, v32
	v_or_b32_e32 v38, 48, v32
	v_mul_lo_u32 v7, v7, v5
	v_mul_hi_u32 v7, v5, v7
	v_add_u32_e32 v5, v5, v7
	v_mul_hi_u32 v5, v6, v5
	v_mul_lo_u32 v7, v5, v4
	v_sub_u32_e32 v6, v6, v7
	v_add_u32_e32 v7, 1, v5
	v_cmp_ge_u32_e64 s[40:41], v6, v4
	v_lshlrev_b32_e32 v192, 2, v26
	v_mad_i64_i32 v[10:11], s[0:1], v41, v34, 0
	v_cndmask_b32_e64 v5, v5, v7, s[40:41]
	v_sub_u32_e32 v7, v6, v4
	v_cndmask_b32_e64 v6, v6, v7, s[40:41]
	v_add_u32_e32 v7, 1, v5
	v_cmp_ge_u32_e64 s[40:41], v6, v4
	v_mad_i64_i32 v[12:13], s[0:1], v41, v32, 0
	s_nop 0
	v_cndmask_b32_e64 v4, v5, v7, s[40:41]
	v_sub_u32_e32 v5, 0, v3
	v_max_i32_e32 v5, v3, v5
	v_cvt_f32_u32_e32 v6, v5
	v_xor_b32_e32 v4, v4, v1
	v_sub_u32_e32 v17, v4, v1
	v_mul_lo_u32 v1, v17, v2
	v_rcp_iflag_f32_e32 v2, v6
	v_sub_u32_e32 v6, 0, v5
	v_sub_u32_e32 v0, v0, v1
	v_sub_u32_e32 v4, 0, v0
	v_mul_f32_e32 v2, 0x4f7ffffe, v2
	v_cvt_u32_f32_e32 v2, v2
	v_max_i32_e32 v4, v0, v4
	v_xor_b32_e32 v1, v0, v3
	v_ashrrev_i32_e32 v1, 31, v1
	v_mul_lo_u32 v6, v6, v2
	v_mul_hi_u32 v6, v2, v6
	v_add_u32_e32 v2, v2, v6
	v_mul_hi_u32 v2, v4, v2
	v_mul_lo_u32 v6, v2, v5
	v_sub_u32_e32 v4, v4, v6
	v_add_u32_e32 v6, 1, v2
	v_cmp_ge_u32_e64 s[40:41], v4, v5
	v_ashrrev_i32_e32 v27, 31, v17
	s_waitcnt lgkmcnt(0)
	v_mul_lo_u32 v25, v25, v17
	v_cndmask_b32_e64 v2, v2, v6, s[40:41]
	v_sub_u32_e32 v6, v4, v5
	v_cndmask_b32_e64 v4, v4, v6, s[40:41]
	v_add_u32_e32 v6, 1, v2
	v_cmp_ge_u32_e64 s[40:41], v4, v5
	v_bfe_u32 v42, v16, 2, 6
	s_lshl_b32 s25, s16, 1
	v_cndmask_b32_e64 v2, v2, v6, s[40:41]
	v_xor_b32_e32 v2, v2, v1
	v_sub_u32_e32 v1, v2, v1
	v_lshlrev_b32_e32 v28, 6, v1
	v_mul_lo_u32 v1, v1, v3
	v_sub_u32_e32 v0, v0, v1
	v_lshlrev_b32_e32 v30, 6, v0
	v_mul_lo_u32 v2, v22, v27
	v_mul_lo_u32 v3, v23, v17
	v_mad_u64_u32 v[0:1], s[0:1], v22, v17, 0
	v_add3_u32 v1, v1, v2, v3
	v_lshl_add_u64 v[0:1], v[0:1], 2, v[18:19]
	v_mad_i64_i32 v[2:3], s[0:1], v30, v41, 0
	v_ashrrev_i32_e32 v29, 31, v28
	v_lshl_add_u64 v[0:1], v[2:3], 2, v[0:1]
	v_lshl_add_u64 v[0:1], v[28:29], 2, v[0:1]
	v_lshl_add_u64 v[8:9], v[0:1], 0, v[192:193]
	v_mad_i64_i32 v[0:1], s[0:1], v41, v38, 0
	v_mad_i64_i32 v[2:3], s[0:1], v41, v36, 0
	v_lshl_add_u64 v[0:1], v[0:1], 2, v[8:9]
	v_lshl_add_u64 v[4:5], v[2:3], 2, v[8:9]
	v_lshl_add_u64 v[10:11], v[10:11], 2, v[8:9]
	v_lshl_add_u64 v[12:13], v[12:13], 2, v[8:9]
	flat_load_dwordx4 v[0:3], v[0:1] nt
	s_nop 0
	flat_load_dwordx4 v[4:7], v[4:5] nt
	s_nop 0
	flat_load_dwordx4 v[8:11], v[10:11] nt
	s_nop 0
	flat_load_dwordx4 v[12:15], v[12:13] nt
	v_mul_lo_u32 v23, v24, v27
	v_mad_u64_u32 v[18:19], s[0:1], v24, v17, 0
	v_add3_u32 v19, v19, v23, v25
	v_lshl_add_u64 v[18:19], v[18:19], 1, v[20:21]
	v_mad_i64_i32 v[20:21], s[0:1], v28, v40, 0
	v_lshl_add_u64 v[18:19], v[20:21], 1, v[18:19]
	v_ashrrev_i32_e32 v31, 31, v30
	v_lshl_add_u64 v[44:45], v[30:31], 1, v[18:19]
	v_lshlrev_b32_e32 v18, 4, v16
	v_and_b32_e32 v18, 48, v18
	v_mul_i32_i24_e32 v22, 0x4100, v33
	v_and_b32_e32 v16, 0xfc, v16
	v_mul_u32_u24_e32 v21, 0x41, v18
	v_cndmask_b32_e64 v41, 0, 1, vcc
	v_or_b32_e32 v17, v22, v192
	v_or_b32_e32 v19, v22, v16
	v_mul_u32_u24_e32 v20, 0x104, v32
	v_lshlrev_b32_e32 v21, 2, v21
	v_add_u32_e32 v35, v19, v21
	v_add3_u32 v37, v22, v21, v16
	v_lshlrev_b32_e32 v192, 2, v26
	v_add_u32_e32 v39, v17, v20
	v_lshlrev_b32_e32 v46, 1, v18
	v_mov_b32_e32 v43, v41
	v_mov_b64_e32 v[50:51], v[44:45]
	s_branch .LBB0_1452

; DI int otid() { int t = threadIdx.x; asm volatile("" : "+v"(t)); return t; }
; DI int obid() { int t = blockIdx.x; asm volatile("" : "+s"(t)); return t; }
; DI int ogrid() { int t = gridDim.x; asm volatile("" : "+s"(t)); return t; }
; DI CvTile cv_tile(const Job* jobs, int t, int c0, int c1) {
;   CvTile r; r.valid = t < c1; r.pad = 0;
;   int j = 0, tt = r.valid ? t : c0;
;   while (tt >= jobs[j].tiles) { tt -= jobs[j].tiles; ++j; }
;   const Job jb = jobs[j];
;   const int tk = jb.K >> 6, tn = jb.N >> 6, per = tk * tn;
;   const int bi = tt / per, rr = tt % per, kt = rr % tk, nt = rr / tk;
;   r.src = jb.src + (size_t)bi * jb.ss + (size_t)(kt * 64) * jb.N + nt * 64;
;   r.dst = jb.dst + (size_t)bi * jb.ds + (size_t)(nt * 64) * jb.K + kt * 64;
;   r.N = jb.N; r.K = jb.K;
;   return r;
; }
;   if (c0 >= c1) return;
;   const int tid = otid(), G = widx < 0 ? ogrid() : wn, b = widx < 0 ? obid() : widx;
;   float* smf = (float*)smraw;
;   const int half = tid >> 8, vt = tid & 255;
;   float* smh = smf + half * (64 * 65);
;   const int kr = vt >> 4, nc = (vt & 15) * 4;
;   int t0 = c0 + b * 2;
;   if (t0 >= c1) { __syncthreads(); return; }
;   CvTile cur = cv_tile(g_jobs, t0 + half, c0, c1);
;   float4 v[4];
; #pragma unroll
;   for (int i = 0; i < 4; ++i) v[i] = *(const float4*)(cur.src + (size_t)(kr + 16 * i) * cur.N + nc);
.LBB0_1746:
	s_or_b64 exec, exec, s[0:1]
	ds_read_b64 v[40:41], v1 offset:16
	ds_read2_b64 v[18:21], v1 offset1:1
	v_lshlrev_b32_e32 v2, 2, v16
	v_and_b32_e32 v26, 60, v2
	v_sub_u32_e32 v6, 0, v0
	s_waitcnt lgkmcnt(1)
	v_ashrrev_i32_e32 v2, 6, v41
	v_ashrrev_i32_e32 v3, 6, v40
	v_mul_lo_u32 v2, v3, v2
	v_sub_u32_e32 v4, 0, v2
	v_max_i32_e32 v4, v2, v4
	v_cvt_f32_u32_e32 v5, v4
	v_sub_u32_e32 v7, 0, v4
	v_max_i32_e32 v6, v0, v6
	ds_read2_b64 v[22:25], v1 offset0:4 offset1:5
	v_rcp_iflag_f32_e32 v5, v5
	v_xor_b32_e32 v1, v0, v2
	v_ashrrev_i32_e32 v1, 31, v1
	v_bfe_u32 v32, v16, 4, 4
	v_mul_f32_e32 v5, 0x4f7ffffe, v5
	v_cvt_u32_f32_e32 v5, v5
	v_or_b32_e32 v34, 16, v32
	v_or_b32_e32 v36, 32, v32
	v_or_b32_e32 v38, 48, v32
	v_mul_lo_u32 v7, v7, v5
	v_mul_hi_u32 v7, v5, v7
	v_add_u32_e32 v5, v5, v7
	v_mul_hi_u32 v5, v6, v5
	v_mul_lo_u32 v7, v5, v4
	v_sub_u32_e32 v6, v6, v7
	v_add_u32_e32 v7, 1, v5
	v_cmp_ge_u32_e64 s[38:39], v6, v4
	v_lshlrev_b32_e32 v192, 2, v26
	v_mad_i64_i32 v[10:11], s[0:1], v41, v34, 0
	v_cndmask_b32_e64 v5, v5, v7, s[38:39]
	v_sub_u32_e32 v7, v6, v4
	v_cndmask_b32_e64 v6, v6, v7, s[38:39]
	v_add_u32_e32 v7, 1, v5
	v_cmp_ge_u32_e64 s[38:39], v6, v4
	v_mad_i64_i32 v[12:13], s[0:1], v41, v32, 0
	s_nop 0
	v_cndmask_b32_e64 v4, v5, v7, s[38:39]
	v_sub_u32_e32 v5, 0, v3
	v_max_i32_e32 v5, v3, v5
	v_cvt_f32_u32_e32 v6, v5
	v_xor_b32_e32 v4, v4, v1
	v_sub_u32_e32 v17, v4, v1
	v_mul_lo_u32 v1, v17, v2
	v_rcp_iflag_f32_e32 v2, v6
	v_sub_u32_e32 v6, 0, v5
	v_sub_u32_e32 v0, v0, v1
	v_sub_u32_e32 v4, 0, v0
	v_mul_f32_e32 v2, 0x4f7ffffe, v2
	v_cvt_u32_f32_e32 v2, v2
	v_max_i32_e32 v4, v0, v4
	v_xor_b32_e32 v1, v0, v3
	v_ashrrev_i32_e32 v1, 31, v1
	v_mul_lo_u32 v6, v6, v2
	v_mul_hi_u32 v6, v2, v6
	v_add_u32_e32 v2, v2, v6
	v_mul_hi_u32 v2, v4, v2
	v_mul_lo_u32 v6, v2, v5
	v_sub_u32_e32 v4, v4, v6
	v_add_u32_e32 v6, 1, v2
	v_cmp_ge_u32_e64 s[38:39], v4, v5
	v_ashrrev_i32_e32 v27, 31, v17
	s_waitcnt lgkmcnt(0)
	v_mul_lo_u32 v25, v25, v17
	v_cndmask_b32_e64 v2, v2, v6, s[38:39]
	v_sub_u32_e32 v6, v4, v5
	v_cndmask_b32_e64 v4, v4, v6, s[38:39]
	v_add_u32_e32 v6, 1, v2
	v_cmp_ge_u32_e64 s[38:39], v4, v5
	v_bfe_u32 v42, v16, 2, 6
	s_lshl_b32 s25, s30, 1
	v_cndmask_b32_e64 v2, v2, v6, s[38:39]
	v_xor_b32_e32 v2, v2, v1
	v_sub_u32_e32 v1, v2, v1
	v_lshlrev_b32_e32 v28, 6, v1
	v_mul_lo_u32 v1, v1, v3
	v_sub_u32_e32 v0, v0, v1
	v_lshlrev_b32_e32 v30, 6, v0
	v_mul_lo_u32 v2, v22, v27
	v_mul_lo_u32 v3, v23, v17
	v_mad_u64_u32 v[0:1], s[0:1], v22, v17, 0
	v_add3_u32 v1, v1, v2, v3
	v_lshl_add_u64 v[0:1], v[0:1], 2, v[18:19]
	v_mad_i64_i32 v[2:3], s[0:1], v30, v41, 0
	v_ashrrev_i32_e32 v29, 31, v28
	v_lshl_add_u64 v[0:1], v[2:3], 2, v[0:1]
	v_lshl_add_u64 v[0:1], v[28:29], 2, v[0:1]
	v_lshl_add_u64 v[8:9], v[0:1], 0, v[192:193]
	v_mad_i64_i32 v[0:1], s[0:1], v41, v38, 0
	v_mad_i64_i32 v[2:3], s[0:1], v41, v36, 0
	v_lshl_add_u64 v[0:1], v[0:1], 2, v[8:9]
	v_lshl_add_u64 v[4:5], v[2:3], 2, v[8:9]
	v_lshl_add_u64 v[10:11], v[10:11], 2, v[8:9]
	v_lshl_add_u64 v[12:13], v[12:13], 2, v[8:9]
	flat_load_dwordx4 v[0:3], v[0:1] nt
	s_nop 0
	flat_load_dwordx4 v[4:7], v[4:5] nt
	s_nop 0
	flat_load_dwordx4 v[8:11], v[10:11] nt
	s_nop 0
	flat_load_dwordx4 v[12:15], v[12:13] nt
	v_mul_lo_u32 v23, v24, v27
	v_mad_u64_u32 v[18:19], s[0:1], v24, v17, 0
	v_add3_u32 v19, v19, v23, v25
	v_lshl_add_u64 v[18:19], v[18:19], 1, v[20:21]
	v_mad_i64_i32 v[20:21], s[0:1], v28, v40, 0
	v_lshl_add_u64 v[18:19], v[20:21], 1, v[18:19]
	v_ashrrev_i32_e32 v31, 31, v30
	v_lshl_add_u64 v[44:45], v[30:31], 1, v[18:19]
	v_lshlrev_b32_e32 v18, 4, v16
	v_and_b32_e32 v18, 48, v18
	v_mul_i32_i24_e32 v22, 0x4100, v33
	v_and_b32_e32 v16, 0xfc, v16
	v_mul_u32_u24_e32 v21, 0x41, v18
	v_cndmask_b32_e64 v41, 0, 1, vcc
	v_or_b32_e32 v17, v22, v192
	v_or_b32_e32 v19, v22, v16
	v_mul_u32_u24_e32 v20, 0x104, v32
	v_lshlrev_b32_e32 v21, 2, v21
	v_add_u32_e32 v35, v19, v21
	v_add3_u32 v37, v22, v21, v16
	v_lshlrev_b32_e32 v192, 2, v26
	v_add_u32_e32 v39, v17, v20
	v_lshlrev_b32_e32 v46, 1, v18
	v_mov_b32_e32 v43, v41
	v_mov_b64_e32 v[50:51], v[44:45]
	s_branch .LBB0_1748

; DI int otid() { int t = threadIdx.x; asm volatile("" : "+v"(t)); return t; }
; DI int obid() { int t = blockIdx.x; asm volatile("" : "+s"(t)); return t; }
; DI int ogrid() { int t = gridDim.x; asm volatile("" : "+s"(t)); return t; }
; DI CvTile cv_tile(const Job* jobs, int t, int c0, int c1) {
;   CvTile r; r.valid = t < c1; r.pad = 0;
;   int j = 0, tt = r.valid ? t : c0;
;   while (tt >= jobs[j].tiles) { tt -= jobs[j].tiles; ++j; }
;   const Job jb = jobs[j];
;   const int tk = jb.K >> 6, tn = jb.N >> 6, per = tk * tn;
;   const int bi = tt / per, rr = tt % per, kt = rr % tk, nt = rr / tk;
;   r.src = jb.src + (size_t)bi * jb.ss + (size_t)(kt * 64) * jb.N + nt * 64;
;   r.dst = jb.dst + (size_t)bi * jb.ds + (size_t)(nt * 64) * jb.K + kt * 64;
;   r.N = jb.N; r.K = jb.K;
;   return r;
; }
;   if (c0 >= c1) return;
;   const int tid = otid(), G = widx < 0 ? ogrid() : wn, b = widx < 0 ? obid() : widx;
;   float* smf = (float*)smraw;
;   const int half = tid >> 8, vt = tid & 255;
;   float* smh = smf + half * (64 * 65);
;   const int kr = vt >> 4, nc = (vt & 15) * 4;
;   int t0 = c0 + b * 2;
;   if (t0 >= c1) { __syncthreads(); return; }
;   CvTile cur = cv_tile(g_jobs, t0 + half, c0, c1);
;   float4 v[4];
; #pragma unroll
;   for (int i = 0; i < 4; ++i) v[i] = *(const float4*)(cur.src + (size_t)(kr + 16 * i) * cur.N + nc);
.LBB0_1764:
	s_or_b64 exec, exec, s[0:1]
	ds_read_b64 v[40:41], v1 offset:16
	ds_read2_b64 v[18:21], v1 offset1:1
	v_lshlrev_b32_e32 v2, 2, v16
	v_and_b32_e32 v26, 60, v2
	v_sub_u32_e32 v6, 0, v0
	s_waitcnt lgkmcnt(1)
	v_ashrrev_i32_e32 v2, 6, v41
	v_ashrrev_i32_e32 v3, 6, v40
	v_mul_lo_u32 v2, v3, v2
	v_sub_u32_e32 v4, 0, v2
	v_max_i32_e32 v4, v2, v4
	v_cvt_f32_u32_e32 v5, v4
	v_sub_u32_e32 v7, 0, v4
	v_max_i32_e32 v6, v0, v6
	ds_read2_b64 v[22:25], v1 offset0:4 offset1:5
	v_rcp_iflag_f32_e32 v5, v5
	v_xor_b32_e32 v1, v0, v2
	v_ashrrev_i32_e32 v1, 31, v1
	v_bfe_u32 v32, v16, 4, 4
	v_mul_f32_e32 v5, 0x4f7ffffe, v5
	v_cvt_u32_f32_e32 v5, v5
	v_or_b32_e32 v34, 16, v32
	v_or_b32_e32 v36, 32, v32
	v_or_b32_e32 v38, 48, v32
	v_mul_lo_u32 v7, v7, v5
	v_mul_hi_u32 v7, v5, v7
	v_add_u32_e32 v5, v5, v7
	v_mul_hi_u32 v5, v6, v5
	v_mul_lo_u32 v7, v5, v4
	v_sub_u32_e32 v6, v6, v7
	v_add_u32_e32 v7, 1, v5
	v_cmp_ge_u32_e64 s[40:41], v6, v4
	v_lshlrev_b32_e32 v192, 2, v26
	v_mad_i64_i32 v[10:11], s[0:1], v41, v34, 0
	v_cndmask_b32_e64 v5, v5, v7, s[40:41]
	v_sub_u32_e32 v7, v6, v4
	v_cndmask_b32_e64 v6, v6, v7, s[40:41]
	v_add_u32_e32 v7, 1, v5
	v_cmp_ge_u32_e64 s[40:41], v6, v4
	v_mad_i64_i32 v[12:13], s[0:1], v41, v32, 0
	s_nop 0
	v_cndmask_b32_e64 v4, v5, v7, s[40:41]
	v_sub_u32_e32 v5, 0, v3
	v_max_i32_e32 v5, v3, v5
	v_cvt_f32_u32_e32 v6, v5
	v_xor_b32_e32 v4, v4, v1
	v_sub_u32_e32 v17, v4, v1
	v_mul_lo_u32 v1, v17, v2
	v_rcp_iflag_f32_e32 v2, v6
	v_sub_u32_e32 v6, 0, v5
	v_sub_u32_e32 v0, v0, v1
	v_sub_u32_e32 v4, 0, v0
	v_mul_f32_e32 v2, 0x4f7ffffe, v2
	v_cvt_u32_f32_e32 v2, v2
	v_max_i32_e32 v4, v0, v4
	v_xor_b32_e32 v1, v0, v3
	v_ashrrev_i32_e32 v1, 31, v1
	v_mul_lo_u32 v6, v6, v2
	v_mul_hi_u32 v6, v2, v6
	v_add_u32_e32 v2, v2, v6
	v_mul_hi_u32 v2, v4, v2
	v_mul_lo_u32 v6, v2, v5
	v_sub_u32_e32 v4, v4, v6
	v_add_u32_e32 v6, 1, v2
	v_cmp_ge_u32_e64 s[40:41], v4, v5
	v_ashrrev_i32_e32 v27, 31, v17
	s_waitcnt lgkmcnt(0)
	v_mul_lo_u32 v25, v25, v17
	v_cndmask_b32_e64 v2, v2, v6, s[40:41]
	v_sub_u32_e32 v6, v4, v5
	v_cndmask_b32_e64 v4, v4, v6, s[40:41]
	v_add_u32_e32 v6, 1, v2
	v_cmp_ge_u32_e64 s[40:41], v4, v5
	v_bfe_u32 v42, v16, 2, 6
	s_lshl_b32 s42, s24, 1
	v_cndmask_b32_e64 v2, v2, v6, s[40:41]
	v_xor_b32_e32 v2, v2, v1
	v_sub_u32_e32 v1, v2, v1
	v_lshlrev_b32_e32 v28, 6, v1
	v_mul_lo_u32 v1, v1, v3
	v_sub_u32_e32 v0, v0, v1
	v_lshlrev_b32_e32 v30, 6, v0
	v_mul_lo_u32 v2, v22, v27
	v_mul_lo_u32 v3, v23, v17
	v_mad_u64_u32 v[0:1], s[0:1], v22, v17, 0
	v_add3_u32 v1, v1, v2, v3
	v_lshl_add_u64 v[0:1], v[0:1], 2, v[18:19]
	v_mad_i64_i32 v[2:3], s[0:1], v30, v41, 0
	v_ashrrev_i32_e32 v29, 31, v28
	v_lshl_add_u64 v[0:1], v[2:3], 2, v[0:1]
	v_lshl_add_u64 v[0:1], v[28:29], 2, v[0:1]
	v_lshl_add_u64 v[8:9], v[0:1], 0, v[192:193]
	v_mad_i64_i32 v[0:1], s[0:1], v41, v38, 0
	v_mad_i64_i32 v[2:3], s[0:1], v41, v36, 0
	v_lshl_add_u64 v[0:1], v[0:1], 2, v[8:9]
	v_lshl_add_u64 v[4:5], v[2:3], 2, v[8:9]
	v_lshl_add_u64 v[10:11], v[10:11], 2, v[8:9]
	v_lshl_add_u64 v[12:13], v[12:13], 2, v[8:9]
	flat_load_dwordx4 v[0:3], v[0:1] nt
	s_nop 0
	flat_load_dwordx4 v[4:7], v[4:5] nt
	s_nop 0
	flat_load_dwordx4 v[8:11], v[10:11] nt
	s_nop 0
	flat_load_dwordx4 v[12:15], v[12:13] nt
	v_mul_lo_u32 v23, v24, v27
	v_mad_u64_u32 v[18:19], s[0:1], v24, v17, 0
	v_add3_u32 v19, v19, v23, v25
	v_lshl_add_u64 v[18:19], v[18:19], 1, v[20:21]
	v_mad_i64_i32 v[20:21], s[0:1], v28, v40, 0
	v_lshl_add_u64 v[18:19], v[20:21], 1, v[18:19]
	v_ashrrev_i32_e32 v31, 31, v30
	v_lshl_add_u64 v[44:45], v[30:31], 1, v[18:19]
	v_lshlrev_b32_e32 v18, 4, v16
	v_and_b32_e32 v18, 48, v18
	v_mul_i32_i24_e32 v22, 0x4100, v33
	v_and_b32_e32 v16, 0xfc, v16
	v_mul_u32_u24_e32 v21, 0x41, v18
	v_cndmask_b32_e64 v41, 0, 1, vcc
	v_or_b32_e32 v17, v22, v192
	v_or_b32_e32 v19, v22, v16
	v_mul_u32_u24_e32 v20, 0x104, v32
	v_lshlrev_b32_e32 v21, 2, v21
	v_add_u32_e32 v35, v19, v21
	v_add3_u32 v37, v22, v21, v16
	v_lshlrev_b32_e32 v192, 2, v26
	v_add_u32_e32 v39, v17, v20
	v_lshlrev_b32_e32 v46, 1, v18
	v_mov_b32_e32 v43, v41
	v_mov_b64_e32 v[50:51], v[44:45]
	s_branch .LBB0_1766

; DI int otid() { int t = threadIdx.x; asm volatile("" : "+v"(t)); return t; }
; DI int obid() { int t = blockIdx.x; asm volatile("" : "+s"(t)); return t; }
; DI int ogrid() { int t = gridDim.x; asm volatile("" : "+s"(t)); return t; }
; DI CvTile cv_tile(const Job* jobs, int t, int c0, int c1) {
;   CvTile r; r.valid = t < c1; r.pad = 0;
;   int j = 0, tt = r.valid ? t : c0;
;   while (tt >= jobs[j].tiles) { tt -= jobs[j].tiles; ++j; }
;   const Job jb = jobs[j];
;   const int tk = jb.K >> 6, tn = jb.N >> 6, per = tk * tn;
;   const int bi = tt / per, rr = tt % per, kt = rr % tk, nt = rr / tk;
;   r.src = jb.src + (size_t)bi * jb.ss + (size_t)(kt * 64) * jb.N + nt * 64;
;   r.dst = jb.dst + (size_t)bi * jb.ds + (size_t)(nt * 64) * jb.K + kt * 64;
;   r.N = jb.N; r.K = jb.K;
;   return r;
; }
;   if (c0 >= c1) return;
;   const int tid = otid(), G = widx < 0 ? ogrid() : wn, b = widx < 0 ? obid() : widx;
;   float* smf = (float*)smraw;
;   const int half = tid >> 8, vt = tid & 255;
;   float* smh = smf + half * (64 * 65);
;   const int kr = vt >> 4, nc = (vt & 15) * 4;
;   int t0 = c0 + b * 2;
;   if (t0 >= c1) { __syncthreads(); return; }
;   CvTile cur = cv_tile(g_jobs, t0 + half, c0, c1);
;   float4 v[4];
; #pragma unroll
;   for (int i = 0; i < 4; ++i) v[i] = *(const float4*)(cur.src + (size_t)(kr + 16 * i) * cur.N + nc);
.LBB0_1787:
	s_or_b64 exec, exec, s[0:1]
	ds_read_b64 v[40:41], v1 offset:16
	ds_read2_b64 v[18:21], v1 offset1:1
	v_lshlrev_b32_e32 v2, 2, v16
	v_and_b32_e32 v26, 60, v2
	v_sub_u32_e32 v6, 0, v0
	s_waitcnt lgkmcnt(0)
	v_ashrrev_i32_e32 v2, 6, v41
	v_ashrrev_i32_e32 v3, 6, v40
	v_mul_lo_u32 v2, v3, v2
	v_sub_u32_e32 v4, 0, v2
	v_max_i32_e32 v4, v2, v4
	v_cvt_f32_u32_e32 v5, v4
	v_sub_u32_e32 v7, 0, v4
	v_max_i32_e32 v6, v0, v6
	ds_read2_b64 v[22:25], v1 offset0:4 offset1:5
	v_rcp_iflag_f32_e32 v5, v5
	v_xor_b32_e32 v1, v0, v2
	v_ashrrev_i32_e32 v1, 31, v1
	v_bfe_u32 v32, v16, 4, 4
	v_mul_f32_e32 v5, 0x4f7ffffe, v5
	v_cvt_u32_f32_e32 v5, v5
	v_or_b32_e32 v34, 16, v32
	v_or_b32_e32 v36, 32, v32
	v_or_b32_e32 v38, 48, v32
	v_mul_lo_u32 v7, v7, v5
	v_mul_hi_u32 v7, v5, v7
	v_add_u32_e32 v5, v5, v7
	v_mul_hi_u32 v5, v6, v5
	v_mul_lo_u32 v7, v5, v4
	v_sub_u32_e32 v6, v6, v7
	v_add_u32_e32 v7, 1, v5
	v_cmp_ge_u32_e64 s[38:39], v6, v4
	v_lshlrev_b32_e32 v192, 2, v26
	v_mad_i64_i32 v[10:11], s[0:1], v41, v34, 0
	v_cndmask_b32_e64 v5, v5, v7, s[38:39]
	v_sub_u32_e32 v7, v6, v4
	v_cndmask_b32_e64 v6, v6, v7, s[38:39]
	v_add_u32_e32 v7, 1, v5
	v_cmp_ge_u32_e64 s[38:39], v6, v4
	v_mad_i64_i32 v[12:13], s[0:1], v41, v32, 0
	s_nop 0
	v_cndmask_b32_e64 v4, v5, v7, s[38:39]
	v_sub_u32_e32 v5, 0, v3
	v_max_i32_e32 v5, v3, v5
	v_cvt_f32_u32_e32 v6, v5
	v_xor_b32_e32 v4, v4, v1
	v_sub_u32_e32 v17, v4, v1
	v_mul_lo_u32 v1, v17, v2
	v_rcp_iflag_f32_e32 v2, v6
	v_sub_u32_e32 v6, 0, v5
	v_sub_u32_e32 v0, v0, v1
	v_sub_u32_e32 v4, 0, v0
	v_mul_f32_e32 v2, 0x4f7ffffe, v2
	v_cvt_u32_f32_e32 v2, v2
	v_max_i32_e32 v4, v0, v4
	v_xor_b32_e32 v1, v0, v3
	v_ashrrev_i32_e32 v1, 31, v1
	v_mul_lo_u32 v6, v6, v2
	v_mul_hi_u32 v6, v2, v6
	v_add_u32_e32 v2, v2, v6
	v_mul_hi_u32 v2, v4, v2
	v_mul_lo_u32 v6, v2, v5
	v_sub_u32_e32 v4, v4, v6
	v_add_u32_e32 v6, 1, v2
	v_cmp_ge_u32_e64 s[38:39], v4, v5
	v_ashrrev_i32_e32 v27, 31, v17
	s_waitcnt lgkmcnt(0)
	v_mul_lo_u32 v25, v25, v17
	v_cndmask_b32_e64 v2, v2, v6, s[38:39]
	v_sub_u32_e32 v6, v4, v5
	v_cndmask_b32_e64 v4, v4, v6, s[38:39]
	v_add_u32_e32 v6, 1, v2
	v_cmp_ge_u32_e64 s[38:39], v4, v5
	v_bfe_u32 v42, v16, 2, 6
	s_lshl_b32 s25, s16, 1
	v_cndmask_b32_e64 v2, v2, v6, s[38:39]
	v_xor_b32_e32 v2, v2, v1
	v_sub_u32_e32 v1, v2, v1
	v_lshlrev_b32_e32 v28, 6, v1
	v_mul_lo_u32 v1, v1, v3
	v_sub_u32_e32 v0, v0, v1
	v_lshlrev_b32_e32 v30, 6, v0
	v_mul_lo_u32 v2, v22, v27
	v_mul_lo_u32 v3, v23, v17
	v_mad_u64_u32 v[0:1], s[0:1], v22, v17, 0
	v_add3_u32 v1, v1, v2, v3
	v_lshl_add_u64 v[0:1], v[0:1], 2, v[18:19]
	v_mad_i64_i32 v[2:3], s[0:1], v30, v41, 0
	v_ashrrev_i32_e32 v29, 31, v28
	v_lshl_add_u64 v[0:1], v[2:3], 2, v[0:1]
	v_lshl_add_u64 v[0:1], v[28:29], 2, v[0:1]
	v_lshl_add_u64 v[8:9], v[0:1], 0, v[192:193]
	v_mad_i64_i32 v[0:1], s[0:1], v41, v38, 0
	v_mad_i64_i32 v[2:3], s[0:1], v41, v36, 0
	v_lshl_add_u64 v[0:1], v[0:1], 2, v[8:9]
	v_lshl_add_u64 v[4:5], v[2:3], 2, v[8:9]
	v_lshl_add_u64 v[10:11], v[10:11], 2, v[8:9]
	v_lshl_add_u64 v[12:13], v[12:13], 2, v[8:9]
	flat_load_dwordx4 v[0:3], v[0:1] nt
	s_nop 0
	flat_load_dwordx4 v[4:7], v[4:5] nt
	s_nop 0
	flat_load_dwordx4 v[8:11], v[10:11] nt
	s_nop 0
	flat_load_dwordx4 v[12:15], v[12:13] nt
	v_mul_lo_u32 v23, v24, v27
	v_mad_u64_u32 v[18:19], s[0:1], v24, v17, 0
	v_add3_u32 v19, v19, v23, v25
	v_lshl_add_u64 v[18:19], v[18:19], 1, v[20:21]
	v_mad_i64_i32 v[20:21], s[0:1], v28, v40, 0
	v_lshl_add_u64 v[18:19], v[20:21], 1, v[18:19]
	v_ashrrev_i32_e32 v31, 31, v30
	v_lshl_add_u64 v[44:45], v[30:31], 1, v[18:19]
	v_lshlrev_b32_e32 v18, 4, v16
	v_and_b32_e32 v18, 48, v18
	v_mul_i32_i24_e32 v22, 0x4100, v33
	v_and_b32_e32 v16, 0xfc, v16
	v_mul_u32_u24_e32 v21, 0x41, v18
	v_cndmask_b32_e64 v41, 0, 1, vcc
	v_or_b32_e32 v17, v22, v192
	v_or_b32_e32 v19, v22, v16
	v_mul_u32_u24_e32 v20, 0x104, v32
	v_lshlrev_b32_e32 v21, 2, v21
	v_add_u32_e32 v35, v19, v21
	v_add3_u32 v37, v22, v21, v16
	v_lshlrev_b32_e32 v192, 2, v26
	v_add_u32_e32 v39, v17, v20
	v_lshlrev_b32_e32 v46, 1, v18
	v_mov_b32_e32 v43, v41
	v_mov_b64_e32 v[50:51], v[44:45]
	s_branch .LBB0_1789

; DI int otid() { int t = threadIdx.x; asm volatile("" : "+v"(t)); return t; }
; DI int obid() { int t = blockIdx.x; asm volatile("" : "+s"(t)); return t; }
; DI int ogrid() { int t = gridDim.x; asm volatile("" : "+s"(t)); return t; }
; DI CvTile cv_tile(const Job* jobs, int t, int c0, int c1) {
;   CvTile r; r.valid = t < c1; r.pad = 0;
;   int j = 0, tt = r.valid ? t : c0;
;   while (tt >= jobs[j].tiles) { tt -= jobs[j].tiles; ++j; }
;   const Job jb = jobs[j];
;   const int tk = jb.K >> 6, tn = jb.N >> 6, per = tk * tn;
;   const int bi = tt / per, rr = tt % per, kt = rr % tk, nt = rr / tk;
;   r.src = jb.src + (size_t)bi * jb.ss + (size_t)(kt * 64) * jb.N + nt * 64;
;   r.dst = jb.dst + (size_t)bi * jb.ds + (size_t)(nt * 64) * jb.K + kt * 64;
;   r.N = jb.N; r.K = jb.K;
;   return r;
; }
;   if (c0 >= c1) return;
;   const int tid = otid(), G = widx < 0 ? ogrid() : wn, b = widx < 0 ? obid() : widx;
;   float* smf = (float*)smraw;
;   const int half = tid >> 8, vt = tid & 255;
;   float* smh = smf + half * (64 * 65);
;   const int kr = vt >> 4, nc = (vt & 15) * 4;
;   int t0 = c0 + b * 2;
;   if (t0 >= c1) { __syncthreads(); return; }
;   CvTile cur = cv_tile(g_jobs, t0 + half, c0, c1);
;   float4 v[4];
; #pragma unroll
;   for (int i = 0; i < 4; ++i) v[i] = *(const float4*)(cur.src + (size_t)(kr + 16 * i) * cur.N + nc);
.LBB0_2153:
	s_or_b64 exec, exec, s[14:15]
	s_waitcnt vmcnt(2)
	ds_read_b64 v[40:41], v1 offset:16
	s_waitcnt vmcnt(1)
	ds_read2_b64 v[18:21], v1 offset1:1
	v_lshlrev_b32_e32 v2, 2, v16
	s_waitcnt vmcnt(0)
	v_and_b32_e32 v26, 60, v2
	v_sub_u32_e32 v6, 0, v0
	s_waitcnt lgkmcnt(1)
	v_ashrrev_i32_e32 v2, 6, v41
	v_ashrrev_i32_e32 v3, 6, v40
	v_mul_lo_u32 v2, v3, v2
	v_sub_u32_e32 v4, 0, v2
	v_max_i32_e32 v4, v2, v4
	v_cvt_f32_u32_e32 v5, v4
	v_sub_u32_e32 v7, 0, v4
	v_max_i32_e32 v6, v0, v6
	ds_read2_b64 v[22:25], v1 offset0:4 offset1:5
	v_rcp_iflag_f32_e32 v5, v5
	v_xor_b32_e32 v1, v0, v2
	v_ashrrev_i32_e32 v1, 31, v1
	v_bfe_u32 v32, v16, 4, 4
	v_mul_f32_e32 v5, 0x4f7ffffe, v5
	v_cvt_u32_f32_e32 v5, v5
	v_or_b32_e32 v34, 16, v32
	v_or_b32_e32 v36, 32, v32
	v_or_b32_e32 v38, 48, v32
	v_mul_lo_u32 v7, v7, v5
	v_mul_hi_u32 v7, v5, v7
	v_add_u32_e32 v5, v5, v7
	v_mul_hi_u32 v5, v6, v5
	v_mul_lo_u32 v7, v5, v4
	v_sub_u32_e32 v6, v6, v7
	v_add_u32_e32 v7, 1, v5
	v_cmp_ge_u32_e64 s[38:39], v6, v4
	v_lshlrev_b32_e32 v192, 2, v26
	v_mad_i64_i32 v[10:11], s[14:15], v41, v34, 0
	v_cndmask_b32_e64 v5, v5, v7, s[38:39]
	v_sub_u32_e32 v7, v6, v4
	v_cndmask_b32_e64 v6, v6, v7, s[38:39]
	v_add_u32_e32 v7, 1, v5
	v_cmp_ge_u32_e64 s[38:39], v6, v4
	v_mad_i64_i32 v[12:13], s[14:15], v41, v32, 0
	s_nop 0
	v_cndmask_b32_e64 v4, v5, v7, s[38:39]
	v_sub_u32_e32 v5, 0, v3
	v_max_i32_e32 v5, v3, v5
	v_cvt_f32_u32_e32 v6, v5
	v_xor_b32_e32 v4, v4, v1
	v_sub_u32_e32 v17, v4, v1
	v_mul_lo_u32 v1, v17, v2
	v_rcp_iflag_f32_e32 v2, v6
	v_sub_u32_e32 v6, 0, v5
	v_sub_u32_e32 v0, v0, v1
	v_sub_u32_e32 v4, 0, v0
	v_mul_f32_e32 v2, 0x4f7ffffe, v2
	v_cvt_u32_f32_e32 v2, v2
	v_max_i32_e32 v4, v0, v4
	v_xor_b32_e32 v1, v0, v3
	v_ashrrev_i32_e32 v1, 31, v1
	v_mul_lo_u32 v6, v6, v2
	v_mul_hi_u32 v6, v2, v6
	v_add_u32_e32 v2, v2, v6
	v_mul_hi_u32 v2, v4, v2
	v_mul_lo_u32 v6, v2, v5
	v_sub_u32_e32 v4, v4, v6
	v_add_u32_e32 v6, 1, v2
	v_cmp_ge_u32_e64 s[38:39], v4, v5
	v_ashrrev_i32_e32 v27, 31, v17
	s_waitcnt lgkmcnt(0)
	v_mul_lo_u32 v25, v25, v17
	v_cndmask_b32_e64 v2, v2, v6, s[38:39]
	v_sub_u32_e32 v6, v4, v5
	v_cndmask_b32_e64 v4, v4, v6, s[38:39]
	v_add_u32_e32 v6, 1, v2
	v_cmp_ge_u32_e64 s[38:39], v4, v5
	v_bfe_u32 v42, v16, 2, 6
	s_lshl_b32 s18, s18, 1
	v_cndmask_b32_e64 v2, v2, v6, s[38:39]
	v_xor_b32_e32 v2, v2, v1
	v_sub_u32_e32 v1, v2, v1
	v_lshlrev_b32_e32 v28, 6, v1
	v_mul_lo_u32 v1, v1, v3
	v_sub_u32_e32 v0, v0, v1
	v_lshlrev_b32_e32 v30, 6, v0
	v_mul_lo_u32 v2, v22, v27
	v_mul_lo_u32 v3, v23, v17
	v_mad_u64_u32 v[0:1], s[14:15], v22, v17, 0
	v_add3_u32 v1, v1, v2, v3
	v_lshl_add_u64 v[0:1], v[0:1], 2, v[18:19]
	v_mad_i64_i32 v[2:3], s[14:15], v30, v41, 0
	v_ashrrev_i32_e32 v29, 31, v28
	v_lshl_add_u64 v[0:1], v[2:3], 2, v[0:1]
	v_lshl_add_u64 v[0:1], v[28:29], 2, v[0:1]
	v_lshl_add_u64 v[8:9], v[0:1], 0, v[192:193]
	v_mad_i64_i32 v[0:1], s[14:15], v41, v38, 0
	v_mad_i64_i32 v[2:3], s[14:15], v41, v36, 0
	v_lshl_add_u64 v[0:1], v[0:1], 2, v[8:9]
	v_lshl_add_u64 v[4:5], v[2:3], 2, v[8:9]
	v_lshl_add_u64 v[10:11], v[10:11], 2, v[8:9]
	v_lshl_add_u64 v[12:13], v[12:13], 2, v[8:9]
	flat_load_dwordx4 v[0:3], v[0:1] nt
	s_nop 0
	flat_load_dwordx4 v[4:7], v[4:5] nt
	s_nop 0
	flat_load_dwordx4 v[8:11], v[10:11] nt
	s_nop 0
	flat_load_dwordx4 v[12:15], v[12:13] nt
	v_mul_lo_u32 v23, v24, v27
	v_mad_u64_u32 v[18:19], s[14:15], v24, v17, 0
	v_add3_u32 v19, v19, v23, v25
	v_lshl_add_u64 v[18:19], v[18:19], 1, v[20:21]
	v_mad_i64_i32 v[20:21], s[14:15], v28, v40, 0
	v_lshl_add_u64 v[18:19], v[20:21], 1, v[18:19]
	v_ashrrev_i32_e32 v31, 31, v30
	v_lshl_add_u64 v[44:45], v[30:31], 1, v[18:19]
	v_lshlrev_b32_e32 v18, 4, v16
	v_and_b32_e32 v18, 48, v18
	v_mul_i32_i24_e32 v22, 0x4100, v33
	v_and_b32_e32 v16, 0xfc, v16
	v_mul_u32_u24_e32 v21, 0x41, v18
	v_cndmask_b32_e64 v41, 0, 1, vcc
	v_or_b32_e32 v17, v22, v192
	v_or_b32_e32 v19, v22, v16
	v_mul_u32_u24_e32 v20, 0x104, v32
	v_lshlrev_b32_e32 v21, 2, v21
	v_add_u32_e32 v35, v19, v21
	v_add3_u32 v37, v22, v21, v16
	v_lshlrev_b32_e32 v192, 2, v26
	v_add_u32_e32 v39, v17, v20
	v_lshlrev_b32_e32 v46, 1, v18
	v_mov_b32_e32 v43, v41
	v_mov_b64_e32 v[50:51], v[44:45]
	s_branch .LBB0_2155

; DI int otid() { int t = threadIdx.x; asm volatile("" : "+v"(t)); return t; }
; DI int obid() { int t = blockIdx.x; asm volatile("" : "+s"(t)); return t; }
; DI int ogrid() { int t = gridDim.x; asm volatile("" : "+s"(t)); return t; }
; DI CvTile cv_tile(const Job* jobs, int t, int c0, int c1) {
;   CvTile r; r.valid = t < c1; r.pad = 0;
;   int j = 0, tt = r.valid ? t : c0;
;   while (tt >= jobs[j].tiles) { tt -= jobs[j].tiles; ++j; }
;   const Job jb = jobs[j];
;   const int tk = jb.K >> 6, tn = jb.N >> 6, per = tk * tn;
;   const int bi = tt / per, rr = tt % per, kt = rr % tk, nt = rr / tk;
;   r.src = jb.src + (size_t)bi * jb.ss + (size_t)(kt * 64) * jb.N + nt * 64;
;   r.dst = jb.dst + (size_t)bi * jb.ds + (size_t)(nt * 64) * jb.K + kt * 64;
;   r.N = jb.N; r.K = jb.K;
;   return r;
; }
;   if (c0 >= c1) return;
;   const int tid = otid(), G = widx < 0 ? ogrid() : wn, b = widx < 0 ? obid() : widx;
;   float* smf = (float*)smraw;
;   const int half = tid >> 8, vt = tid & 255;
;   float* smh = smf + half * (64 * 65);
;   const int kr = vt >> 4, nc = (vt & 15) * 4;
;   int t0 = c0 + b * 2;
;   if (t0 >= c1) { __syncthreads(); return; }
;   CvTile cur = cv_tile(g_jobs, t0 + half, c0, c1);
;   float4 v[4];
; #pragma unroll
;   for (int i = 0; i < 4; ++i) v[i] = *(const float4*)(cur.src + (size_t)(kr + 16 * i) * cur.N + nc);
.LBB0_2172:
	s_or_b64 exec, exec, s[0:1]
	ds_read_b64 v[40:41], v1 offset:16
	ds_read2_b64 v[18:21], v1 offset1:1
	v_lshlrev_b32_e32 v2, 2, v16
	v_and_b32_e32 v26, 60, v2
	v_sub_u32_e32 v6, 0, v0
	s_waitcnt lgkmcnt(1)
	v_ashrrev_i32_e32 v2, 6, v41
	v_ashrrev_i32_e32 v3, 6, v40
	v_mul_lo_u32 v2, v3, v2
	v_sub_u32_e32 v4, 0, v2
	v_max_i32_e32 v4, v2, v4
	v_cvt_f32_u32_e32 v5, v4
	v_sub_u32_e32 v7, 0, v4
	v_max_i32_e32 v6, v0, v6
	ds_read2_b64 v[22:25], v1 offset0:4 offset1:5
	v_rcp_iflag_f32_e32 v5, v5
	v_xor_b32_e32 v1, v0, v2
	v_ashrrev_i32_e32 v1, 31, v1
	v_bfe_u32 v32, v16, 4, 4
	v_mul_f32_e32 v5, 0x4f7ffffe, v5
	v_cvt_u32_f32_e32 v5, v5
	v_or_b32_e32 v34, 16, v32
	v_or_b32_e32 v36, 32, v32
	v_or_b32_e32 v38, 48, v32
	v_mul_lo_u32 v7, v7, v5
	v_mul_hi_u32 v7, v5, v7
	v_add_u32_e32 v5, v5, v7
	v_mul_hi_u32 v5, v6, v5
	v_mul_lo_u32 v7, v5, v4
	v_sub_u32_e32 v6, v6, v7
	v_add_u32_e32 v7, 1, v5
	v_cmp_ge_u32_e64 s[38:39], v6, v4
	v_lshlrev_b32_e32 v192, 2, v26
	v_mad_i64_i32 v[10:11], s[0:1], v41, v34, 0
	v_cndmask_b32_e64 v5, v5, v7, s[38:39]
	v_sub_u32_e32 v7, v6, v4
	v_cndmask_b32_e64 v6, v6, v7, s[38:39]
	v_add_u32_e32 v7, 1, v5
	v_cmp_ge_u32_e64 s[38:39], v6, v4
	v_mad_i64_i32 v[12:13], s[0:1], v41, v32, 0
	s_nop 0
	v_cndmask_b32_e64 v4, v5, v7, s[38:39]
	v_sub_u32_e32 v5, 0, v3
	v_max_i32_e32 v5, v3, v5
	v_cvt_f32_u32_e32 v6, v5
	v_xor_b32_e32 v4, v4, v1
	v_sub_u32_e32 v17, v4, v1
	v_mul_lo_u32 v1, v17, v2
	v_rcp_iflag_f32_e32 v2, v6
	v_sub_u32_e32 v6, 0, v5
	v_sub_u32_e32 v0, v0, v1
	v_sub_u32_e32 v4, 0, v0
	v_mul_f32_e32 v2, 0x4f7ffffe, v2
	v_cvt_u32_f32_e32 v2, v2
	v_max_i32_e32 v4, v0, v4
	v_xor_b32_e32 v1, v0, v3
	v_ashrrev_i32_e32 v1, 31, v1
	v_mul_lo_u32 v6, v6, v2
	v_mul_hi_u32 v6, v2, v6
	v_add_u32_e32 v2, v2, v6
	v_mul_hi_u32 v2, v4, v2
	v_mul_lo_u32 v6, v2, v5
	v_sub_u32_e32 v4, v4, v6
	v_add_u32_e32 v6, 1, v2
	v_cmp_ge_u32_e64 s[38:39], v4, v5
	v_ashrrev_i32_e32 v27, 31, v17
	s_waitcnt lgkmcnt(0)
	v_mul_lo_u32 v25, v25, v17
	v_cndmask_b32_e64 v2, v2, v6, s[38:39]
	v_sub_u32_e32 v6, v4, v5
	v_cndmask_b32_e64 v4, v4, v6, s[38:39]
	v_add_u32_e32 v6, 1, v2
	v_cmp_ge_u32_e64 s[38:39], v4, v5
	v_bfe_u32 v42, v16, 2, 6
	s_lshl_b32 s18, s16, 1
	v_cndmask_b32_e64 v2, v2, v6, s[38:39]
	v_xor_b32_e32 v2, v2, v1
	v_sub_u32_e32 v1, v2, v1
	v_lshlrev_b32_e32 v28, 6, v1
	v_mul_lo_u32 v1, v1, v3
	v_sub_u32_e32 v0, v0, v1
	v_lshlrev_b32_e32 v30, 6, v0
	v_mul_lo_u32 v2, v22, v27
	v_mul_lo_u32 v3, v23, v17
	v_mad_u64_u32 v[0:1], s[0:1], v22, v17, 0
	v_add3_u32 v1, v1, v2, v3
	v_lshl_add_u64 v[0:1], v[0:1], 2, v[18:19]
	v_mad_i64_i32 v[2:3], s[0:1], v30, v41, 0
	v_ashrrev_i32_e32 v29, 31, v28
	v_lshl_add_u64 v[0:1], v[2:3], 2, v[0:1]
	v_lshl_add_u64 v[0:1], v[28:29], 2, v[0:1]
	v_lshl_add_u64 v[8:9], v[0:1], 0, v[192:193]
	v_mad_i64_i32 v[0:1], s[0:1], v41, v38, 0
	v_mad_i64_i32 v[2:3], s[0:1], v41, v36, 0
	v_lshl_add_u64 v[0:1], v[0:1], 2, v[8:9]
	v_lshl_add_u64 v[4:5], v[2:3], 2, v[8:9]
	v_lshl_add_u64 v[10:11], v[10:11], 2, v[8:9]
	v_lshl_add_u64 v[12:13], v[12:13], 2, v[8:9]
	flat_load_dwordx4 v[0:3], v[0:1] nt
	s_nop 0
	flat_load_dwordx4 v[4:7], v[4:5] nt
	s_nop 0
	flat_load_dwordx4 v[8:11], v[10:11] nt
	s_nop 0
	flat_load_dwordx4 v[12:15], v[12:13] nt
	v_mul_lo_u32 v23, v24, v27
	v_mad_u64_u32 v[18:19], s[0:1], v24, v17, 0
	v_add3_u32 v19, v19, v23, v25
	v_lshl_add_u64 v[18:19], v[18:19], 1, v[20:21]
	v_mad_i64_i32 v[20:21], s[0:1], v28, v40, 0
	v_lshl_add_u64 v[18:19], v[20:21], 1, v[18:19]
	v_ashrrev_i32_e32 v31, 31, v30
	v_lshl_add_u64 v[44:45], v[30:31], 1, v[18:19]
	v_lshlrev_b32_e32 v18, 4, v16
	v_and_b32_e32 v18, 48, v18
	v_mul_i32_i24_e32 v22, 0x4100, v33
	v_and_b32_e32 v16, 0xfc, v16
	v_mul_u32_u24_e32 v21, 0x41, v18
	v_cndmask_b32_e64 v41, 0, 1, vcc
	v_or_b32_e32 v17, v22, v192
	v_or_b32_e32 v19, v22, v16
	v_mul_u32_u24_e32 v20, 0x104, v32
	v_lshlrev_b32_e32 v21, 2, v21
	v_add_u32_e32 v35, v19, v21
	v_add3_u32 v37, v22, v21, v16
	v_lshlrev_b32_e32 v192, 2, v26
	v_add_u32_e32 v39, v17, v20
	v_lshlrev_b32_e32 v46, 1, v18
	v_mov_b32_e32 v43, v41
	v_mov_b64_e32 v[50:51], v[44:45]
	s_branch .LBB0_2174

; DI int otid() { int t = threadIdx.x; asm volatile("" : "+v"(t)); return t; }
; DI int obid() { int t = blockIdx.x; asm volatile("" : "+s"(t)); return t; }
; DI int ogrid() { int t = gridDim.x; asm volatile("" : "+s"(t)); return t; }
; DI CvTile cv_tile(const Job* jobs, int t, int c0, int c1) {
;   CvTile r; r.valid = t < c1; r.pad = 0;
;   int j = 0, tt = r.valid ? t : c0;
;   while (tt >= jobs[j].tiles) { tt -= jobs[j].tiles; ++j; }
;   const Job jb = jobs[j];
;   const int tk = jb.K >> 6, tn = jb.N >> 6, per = tk * tn;
;   const int bi = tt / per, rr = tt % per, kt = rr % tk, nt = rr / tk;
;   r.src = jb.src + (size_t)bi * jb.ss + (size_t)(kt * 64) * jb.N + nt * 64;
;   r.dst = jb.dst + (size_t)bi * jb.ds + (size_t)(nt * 64) * jb.K + kt * 64;
;   r.N = jb.N; r.K = jb.K;
;   return r;
; }
;   if (c0 >= c1) return;
;   const int tid = otid(), G = widx < 0 ? ogrid() : wn, b = widx < 0 ? obid() : widx;
;   float* smf = (float*)smraw;
;   const int half = tid >> 8, vt = tid & 255;
;   float* smh = smf + half * (64 * 65);
;   const int kr = vt >> 4, nc = (vt & 15) * 4;
;   int t0 = c0 + b * 2;
;   if (t0 >= c1) { __syncthreads(); return; }
;   CvTile cur = cv_tile(g_jobs, t0 + half, c0, c1);
;   float4 v[4];
; #pragma unroll
;   for (int i = 0; i < 4; ++i) v[i] = *(const float4*)(cur.src + (size_t)(kr + 16 * i) * cur.N + nc);
.LBB0_2390:
	s_or_b64 exec, exec, s[14:15]
	ds_read_b64 v[40:41], v1 offset:16
	ds_read2_b64 v[18:21], v1 offset1:1
	v_lshlrev_b32_e32 v2, 2, v16
	s_waitcnt vmcnt(1)
	v_and_b32_e32 v26, 60, v2
	v_sub_u32_e32 v6, 0, v0
	s_waitcnt lgkmcnt(1)
	v_ashrrev_i32_e32 v2, 6, v41
	v_ashrrev_i32_e32 v3, 6, v40
	v_mul_lo_u32 v2, v3, v2
	v_sub_u32_e32 v4, 0, v2
	v_max_i32_e32 v4, v2, v4
	v_cvt_f32_u32_e32 v5, v4
	v_sub_u32_e32 v7, 0, v4
	v_max_i32_e32 v6, v0, v6
	ds_read2_b64 v[22:25], v1 offset0:4 offset1:5
	v_rcp_iflag_f32_e32 v5, v5
	v_xor_b32_e32 v1, v0, v2
	v_ashrrev_i32_e32 v1, 31, v1
	v_bfe_u32 v32, v16, 4, 4
	v_mul_f32_e32 v5, 0x4f7ffffe, v5
	v_cvt_u32_f32_e32 v5, v5
	v_or_b32_e32 v34, 16, v32
	v_or_b32_e32 v36, 32, v32
	v_or_b32_e32 v38, 48, v32
	v_mul_lo_u32 v7, v7, v5
	v_mul_hi_u32 v7, v5, v7
	v_add_u32_e32 v5, v5, v7
	v_mul_hi_u32 v5, v6, v5
	v_mul_lo_u32 v7, v5, v4
	v_sub_u32_e32 v6, v6, v7
	v_add_u32_e32 v7, 1, v5
	v_cmp_ge_u32_e64 s[38:39], v6, v4
	v_lshlrev_b32_e32 v192, 2, v26
	s_waitcnt vmcnt(0)
	v_mad_i64_i32 v[10:11], s[14:15], v41, v34, 0
	v_cndmask_b32_e64 v5, v5, v7, s[38:39]
	v_sub_u32_e32 v7, v6, v4
	v_cndmask_b32_e64 v6, v6, v7, s[38:39]
	v_add_u32_e32 v7, 1, v5
	v_cmp_ge_u32_e64 s[38:39], v6, v4
	v_mad_i64_i32 v[12:13], s[14:15], v41, v32, 0
	s_nop 0
	v_cndmask_b32_e64 v4, v5, v7, s[38:39]
	v_sub_u32_e32 v5, 0, v3
	v_max_i32_e32 v5, v3, v5
	v_cvt_f32_u32_e32 v6, v5
	v_xor_b32_e32 v4, v4, v1
	v_sub_u32_e32 v17, v4, v1
	v_mul_lo_u32 v1, v17, v2
	v_rcp_iflag_f32_e32 v2, v6
	v_sub_u32_e32 v6, 0, v5
	v_sub_u32_e32 v0, v0, v1
	v_sub_u32_e32 v4, 0, v0
	v_mul_f32_e32 v2, 0x4f7ffffe, v2
	v_cvt_u32_f32_e32 v2, v2
	v_max_i32_e32 v4, v0, v4
	v_xor_b32_e32 v1, v0, v3
	v_ashrrev_i32_e32 v1, 31, v1
	v_mul_lo_u32 v6, v6, v2
	v_mul_hi_u32 v6, v2, v6
	v_add_u32_e32 v2, v2, v6
	v_mul_hi_u32 v2, v4, v2
	v_mul_lo_u32 v6, v2, v5
	v_sub_u32_e32 v4, v4, v6
	v_add_u32_e32 v6, 1, v2
	v_cmp_ge_u32_e64 s[38:39], v4, v5
	v_ashrrev_i32_e32 v27, 31, v17
	s_waitcnt lgkmcnt(0)
	v_mul_lo_u32 v25, v25, v17
	v_cndmask_b32_e64 v2, v2, v6, s[38:39]
	v_sub_u32_e32 v6, v4, v5
	v_cndmask_b32_e64 v4, v4, v6, s[38:39]
	v_add_u32_e32 v6, 1, v2
	v_cmp_ge_u32_e64 s[38:39], v4, v5
	v_bfe_u32 v42, v16, 2, 6
	s_lshl_b32 s18, s18, 1
	v_cndmask_b32_e64 v2, v2, v6, s[38:39]
	v_xor_b32_e32 v2, v2, v1
	v_sub_u32_e32 v1, v2, v1
	v_lshlrev_b32_e32 v28, 6, v1
	v_mul_lo_u32 v1, v1, v3
	v_sub_u32_e32 v0, v0, v1
	v_lshlrev_b32_e32 v30, 6, v0
	v_mul_lo_u32 v2, v22, v27
	v_mul_lo_u32 v3, v23, v17
	v_mad_u64_u32 v[0:1], s[14:15], v22, v17, 0
	v_add3_u32 v1, v1, v2, v3
	v_lshl_add_u64 v[0:1], v[0:1], 2, v[18:19]
	v_mad_i64_i32 v[2:3], s[14:15], v30, v41, 0
	v_ashrrev_i32_e32 v29, 31, v28
	v_lshl_add_u64 v[0:1], v[2:3], 2, v[0:1]
	v_lshl_add_u64 v[0:1], v[28:29], 2, v[0:1]
	v_lshl_add_u64 v[8:9], v[0:1], 0, v[192:193]
	v_mad_i64_i32 v[0:1], s[14:15], v41, v38, 0
	v_mad_i64_i32 v[2:3], s[14:15], v41, v36, 0
	v_lshl_add_u64 v[0:1], v[0:1], 2, v[8:9]
	v_lshl_add_u64 v[4:5], v[2:3], 2, v[8:9]
	v_lshl_add_u64 v[10:11], v[10:11], 2, v[8:9]
	v_lshl_add_u64 v[12:13], v[12:13], 2, v[8:9]
	flat_load_dwordx4 v[0:3], v[0:1] nt
	s_nop 0
	flat_load_dwordx4 v[4:7], v[4:5] nt
	s_nop 0
	flat_load_dwordx4 v[8:11], v[10:11] nt
	s_nop 0
	flat_load_dwordx4 v[12:15], v[12:13] nt
	v_mul_lo_u32 v23, v24, v27
	v_mad_u64_u32 v[18:19], s[14:15], v24, v17, 0
	v_add3_u32 v19, v19, v23, v25
	v_lshl_add_u64 v[18:19], v[18:19], 1, v[20:21]
	v_mad_i64_i32 v[20:21], s[14:15], v28, v40, 0
	v_lshl_add_u64 v[18:19], v[20:21], 1, v[18:19]
	v_ashrrev_i32_e32 v31, 31, v30
	v_lshl_add_u64 v[44:45], v[30:31], 1, v[18:19]
	v_lshlrev_b32_e32 v18, 4, v16
	v_and_b32_e32 v18, 48, v18
	v_mul_i32_i24_e32 v22, 0x4100, v33
	v_and_b32_e32 v16, 0xfc, v16
	v_mul_u32_u24_e32 v21, 0x41, v18
	v_cndmask_b32_e64 v41, 0, 1, vcc
	v_or_b32_e32 v17, v22, v192
	v_or_b32_e32 v19, v22, v16
	v_mul_u32_u24_e32 v20, 0x104, v32
	v_lshlrev_b32_e32 v21, 2, v21
	v_add_u32_e32 v35, v19, v21
	v_add3_u32 v37, v22, v21, v16
	v_lshlrev_b32_e32 v192, 2, v26
	v_add_u32_e32 v39, v17, v20
	v_lshlrev_b32_e32 v46, 1, v18
	v_mov_b32_e32 v43, v41
	v_mov_b64_e32 v[50:51], v[44:45]
	s_branch .LBB0_2392

; DI int otid() { int t = threadIdx.x; asm volatile("" : "+v"(t)); return t; }
; DI int obid() { int t = blockIdx.x; asm volatile("" : "+s"(t)); return t; }
; DI int ogrid() { int t = gridDim.x; asm volatile("" : "+s"(t)); return t; }
; DI CvTile cv_tile(const Job* jobs, int t, int c0, int c1) {
;   CvTile r; r.valid = t < c1; r.pad = 0;
;   int j = 0, tt = r.valid ? t : c0;
;   while (tt >= jobs[j].tiles) { tt -= jobs[j].tiles; ++j; }
;   const Job jb = jobs[j];
;   const int tk = jb.K >> 6, tn = jb.N >> 6, per = tk * tn;
;   const int bi = tt / per, rr = tt % per, kt = rr % tk, nt = rr / tk;
;   r.src = jb.src + (size_t)bi * jb.ss + (size_t)(kt * 64) * jb.N + nt * 64;
;   r.dst = jb.dst + (size_t)bi * jb.ds + (size_t)(nt * 64) * jb.K + kt * 64;
;   r.N = jb.N; r.K = jb.K;
;   return r;
; }
;   if (c0 >= c1) return;
;   const int tid = otid(), G = widx < 0 ? ogrid() : wn, b = widx < 0 ? obid() : widx;
;   float* smf = (float*)smraw;
;   const int half = tid >> 8, vt = tid & 255;
;   float* smh = smf + half * (64 * 65);
;   const int kr = vt >> 4, nc = (vt & 15) * 4;
;   int t0 = c0 + b * 2;
;   if (t0 >= c1) { __syncthreads(); return; }
;   CvTile cur = cv_tile(g_jobs, t0 + half, c0, c1);
;   float4 v[4];
; #pragma unroll
;   for (int i = 0; i < 4; ++i) v[i] = *(const float4*)(cur.src + (size_t)(kr + 16 * i) * cur.N + nc);
.LBB0_2409:
	s_or_b64 exec, exec, s[0:1]
	ds_read_b64 v[40:41], v1 offset:16
	ds_read2_b64 v[18:21], v1 offset1:1
	v_lshlrev_b32_e32 v2, 2, v16
	s_waitcnt vmcnt(0)
	v_and_b32_e32 v26, 60, v2
	v_sub_u32_e32 v6, 0, v0
	s_waitcnt lgkmcnt(1)
	v_ashrrev_i32_e32 v2, 6, v41
	v_ashrrev_i32_e32 v3, 6, v40
	v_mul_lo_u32 v2, v3, v2
	v_sub_u32_e32 v4, 0, v2
	v_max_i32_e32 v4, v2, v4
	v_cvt_f32_u32_e32 v5, v4
	v_sub_u32_e32 v7, 0, v4
	v_max_i32_e32 v6, v0, v6
	ds_read2_b64 v[22:25], v1 offset0:4 offset1:5
	v_rcp_iflag_f32_e32 v5, v5
	v_xor_b32_e32 v1, v0, v2
	v_ashrrev_i32_e32 v1, 31, v1
	v_bfe_u32 v32, v16, 4, 4
	v_mul_f32_e32 v5, 0x4f7ffffe, v5
	v_cvt_u32_f32_e32 v5, v5
	v_or_b32_e32 v34, 16, v32
	v_or_b32_e32 v36, 32, v32
	v_or_b32_e32 v38, 48, v32
	v_mul_lo_u32 v7, v7, v5
	v_mul_hi_u32 v7, v5, v7
	v_add_u32_e32 v5, v5, v7
	v_mul_hi_u32 v5, v6, v5
	v_mul_lo_u32 v7, v5, v4
	v_sub_u32_e32 v6, v6, v7
	v_add_u32_e32 v7, 1, v5
	v_cmp_ge_u32_e64 s[38:39], v6, v4
	v_lshlrev_b32_e32 v192, 2, v26
	v_mad_i64_i32 v[10:11], s[0:1], v41, v34, 0
	v_cndmask_b32_e64 v5, v5, v7, s[38:39]
	v_sub_u32_e32 v7, v6, v4
	v_cndmask_b32_e64 v6, v6, v7, s[38:39]
	v_add_u32_e32 v7, 1, v5
	v_cmp_ge_u32_e64 s[38:39], v6, v4
	v_mad_i64_i32 v[12:13], s[0:1], v41, v32, 0
	s_nop 0
	v_cndmask_b32_e64 v4, v5, v7, s[38:39]
	v_sub_u32_e32 v5, 0, v3
	v_max_i32_e32 v5, v3, v5
	v_cvt_f32_u32_e32 v6, v5
	v_xor_b32_e32 v4, v4, v1
	v_sub_u32_e32 v17, v4, v1
	v_mul_lo_u32 v1, v17, v2
	v_rcp_iflag_f32_e32 v2, v6
	v_sub_u32_e32 v6, 0, v5
	v_sub_u32_e32 v0, v0, v1
	v_sub_u32_e32 v4, 0, v0
	v_mul_f32_e32 v2, 0x4f7ffffe, v2
	v_cvt_u32_f32_e32 v2, v2
	v_max_i32_e32 v4, v0, v4
	v_xor_b32_e32 v1, v0, v3
	v_ashrrev_i32_e32 v1, 31, v1
	v_mul_lo_u32 v6, v6, v2
	v_mul_hi_u32 v6, v2, v6
	v_add_u32_e32 v2, v2, v6
	v_mul_hi_u32 v2, v4, v2
	v_mul_lo_u32 v6, v2, v5
	v_sub_u32_e32 v4, v4, v6
	v_add_u32_e32 v6, 1, v2
	v_cmp_ge_u32_e64 s[38:39], v4, v5
	v_ashrrev_i32_e32 v27, 31, v17
	s_waitcnt lgkmcnt(0)
	v_mul_lo_u32 v25, v25, v17
	v_cndmask_b32_e64 v2, v2, v6, s[38:39]
	v_sub_u32_e32 v6, v4, v5
	v_cndmask_b32_e64 v4, v4, v6, s[38:39]
	v_add_u32_e32 v6, 1, v2
	v_cmp_ge_u32_e64 s[38:39], v4, v5
	v_bfe_u32 v42, v16, 2, 6
	s_lshl_b32 s18, s16, 1
	v_cndmask_b32_e64 v2, v2, v6, s[38:39]
	v_xor_b32_e32 v2, v2, v1
	v_sub_u32_e32 v1, v2, v1
	v_lshlrev_b32_e32 v28, 6, v1
	v_mul_lo_u32 v1, v1, v3
	v_sub_u32_e32 v0, v0, v1
	v_lshlrev_b32_e32 v30, 6, v0
	v_mul_lo_u32 v2, v22, v27
	v_mul_lo_u32 v3, v23, v17
	v_mad_u64_u32 v[0:1], s[0:1], v22, v17, 0
	v_add3_u32 v1, v1, v2, v3
	v_lshl_add_u64 v[0:1], v[0:1], 2, v[18:19]
	v_mad_i64_i32 v[2:3], s[0:1], v30, v41, 0
	v_ashrrev_i32_e32 v29, 31, v28
	v_lshl_add_u64 v[0:1], v[2:3], 2, v[0:1]
	v_lshl_add_u64 v[0:1], v[28:29], 2, v[0:1]
	v_lshl_add_u64 v[8:9], v[0:1], 0, v[192:193]
	v_mad_i64_i32 v[0:1], s[0:1], v41, v38, 0
	v_mad_i64_i32 v[2:3], s[0:1], v41, v36, 0
	v_lshl_add_u64 v[0:1], v[0:1], 2, v[8:9]
	v_lshl_add_u64 v[4:5], v[2:3], 2, v[8:9]
	v_lshl_add_u64 v[10:11], v[10:11], 2, v[8:9]
	v_lshl_add_u64 v[12:13], v[12:13], 2, v[8:9]
	flat_load_dwordx4 v[0:3], v[0:1] nt
	s_nop 0
	flat_load_dwordx4 v[4:7], v[4:5] nt
	s_nop 0
	flat_load_dwordx4 v[8:11], v[10:11] nt
	s_nop 0
	flat_load_dwordx4 v[12:15], v[12:13] nt
	v_mul_lo_u32 v23, v24, v27
	v_mad_u64_u32 v[18:19], s[0:1], v24, v17, 0
	v_add3_u32 v19, v19, v23, v25
	v_lshl_add_u64 v[18:19], v[18:19], 1, v[20:21]
	v_mad_i64_i32 v[20:21], s[0:1], v28, v40, 0
	v_lshl_add_u64 v[18:19], v[20:21], 1, v[18:19]
	v_ashrrev_i32_e32 v31, 31, v30
	v_lshl_add_u64 v[44:45], v[30:31], 1, v[18:19]
	v_lshlrev_b32_e32 v18, 4, v16
	v_and_b32_e32 v18, 48, v18
	v_mul_i32_i24_e32 v22, 0x4100, v33
	v_and_b32_e32 v16, 0xfc, v16
	v_mul_u32_u24_e32 v21, 0x41, v18
	v_cndmask_b32_e64 v41, 0, 1, vcc
	v_or_b32_e32 v17, v22, v192
	v_or_b32_e32 v19, v22, v16
	v_mul_u32_u24_e32 v20, 0x104, v32
	v_lshlrev_b32_e32 v21, 2, v21
	v_add_u32_e32 v35, v19, v21
	v_add3_u32 v37, v22, v21, v16
	v_lshlrev_b32_e32 v192, 2, v26
	v_add_u32_e32 v39, v17, v20
	v_lshlrev_b32_e32 v46, 1, v18
	v_mov_b32_e32 v43, v41
	v_mov_b64_e32 v[50:51], v[44:45]
	s_branch .LBB0_2411

; DI int otid() { int t = threadIdx.x; asm volatile("" : "+v"(t)); return t; }
; DI int obid() { int t = blockIdx.x; asm volatile("" : "+s"(t)); return t; }
; DI int ogrid() { int t = gridDim.x; asm volatile("" : "+s"(t)); return t; }
; DI CvTile cv_tile(const Job* jobs, int t, int c0, int c1) {
;   CvTile r; r.valid = t < c1; r.pad = 0;
;   int j = 0, tt = r.valid ? t : c0;
;   while (tt >= jobs[j].tiles) { tt -= jobs[j].tiles; ++j; }
;   const Job jb = jobs[j];
;   const int tk = jb.K >> 6, tn = jb.N >> 6, per = tk * tn;
;   const int bi = tt / per, rr = tt % per, kt = rr % tk, nt = rr / tk;
;   r.src = jb.src + (size_t)bi * jb.ss + (size_t)(kt * 64) * jb.N + nt * 64;
;   r.dst = jb.dst + (size_t)bi * jb.ds + (size_t)(nt * 64) * jb.K + kt * 64;
;   r.N = jb.N; r.K = jb.K;
;   return r;
; }
;   if (c0 >= c1) return;
;   const int tid = otid(), G = widx < 0 ? ogrid() : wn, b = widx < 0 ? obid() : widx;
;   float* smf = (float*)smraw;
;   const int half = tid >> 8, vt = tid & 255;
;   float* smh = smf + half * (64 * 65);
;   const int kr = vt >> 4, nc = (vt & 15) * 4;
;   int t0 = c0 + b * 2;
;   if (t0 >= c1) { __syncthreads(); return; }
;   CvTile cur = cv_tile(g_jobs, t0 + half, c0, c1);
;   float4 v[4];
; #pragma unroll
;   for (int i = 0; i < 4; ++i) v[i] = *(const float4*)(cur.src + (size_t)(kr + 16 * i) * cur.N + nc);
.LBB0_2532:
	s_or_b64 exec, exec, s[14:15]
	ds_read_b64 v[40:41], v1 offset:16
	ds_read2_b64 v[18:21], v1 offset1:1
	v_lshlrev_b32_e32 v2, 2, v16
	v_and_b32_e32 v26, 60, v2
	v_sub_u32_e32 v6, 0, v0
	s_waitcnt lgkmcnt(1)
	v_ashrrev_i32_e32 v2, 6, v41
	v_ashrrev_i32_e32 v3, 6, v40
	v_mul_lo_u32 v2, v3, v2
	v_sub_u32_e32 v4, 0, v2
	v_max_i32_e32 v4, v2, v4
	v_cvt_f32_u32_e32 v5, v4
	v_sub_u32_e32 v7, 0, v4
	v_max_i32_e32 v6, v0, v6
	ds_read2_b64 v[22:25], v1 offset0:4 offset1:5
	v_rcp_iflag_f32_e32 v5, v5
	v_xor_b32_e32 v1, v0, v2
	v_ashrrev_i32_e32 v1, 31, v1
	v_bfe_u32 v32, v16, 4, 4
	v_mul_f32_e32 v5, 0x4f7ffffe, v5
	v_cvt_u32_f32_e32 v5, v5
	v_or_b32_e32 v34, 16, v32
	v_or_b32_e32 v36, 32, v32
	v_or_b32_e32 v38, 48, v32
	v_mul_lo_u32 v7, v7, v5
	v_mul_hi_u32 v7, v5, v7
	v_add_u32_e32 v5, v5, v7
	v_mul_hi_u32 v5, v6, v5
	v_mul_lo_u32 v7, v5, v4
	v_sub_u32_e32 v6, v6, v7
	v_add_u32_e32 v7, 1, v5
	v_cmp_ge_u32_e64 s[38:39], v6, v4
	v_lshlrev_b32_e32 v192, 2, v26
	v_mad_i64_i32 v[10:11], s[14:15], v41, v34, 0
	v_cndmask_b32_e64 v5, v5, v7, s[38:39]
	v_sub_u32_e32 v7, v6, v4
	v_cndmask_b32_e64 v6, v6, v7, s[38:39]
	v_add_u32_e32 v7, 1, v5
	v_cmp_ge_u32_e64 s[38:39], v6, v4
	v_mad_i64_i32 v[12:13], s[14:15], v41, v32, 0
	s_nop 0
	v_cndmask_b32_e64 v4, v5, v7, s[38:39]
	v_sub_u32_e32 v5, 0, v3
	v_max_i32_e32 v5, v3, v5
	v_cvt_f32_u32_e32 v6, v5
	v_xor_b32_e32 v4, v4, v1
	v_sub_u32_e32 v17, v4, v1
	v_mul_lo_u32 v1, v17, v2
	v_rcp_iflag_f32_e32 v2, v6
	v_sub_u32_e32 v6, 0, v5
	v_sub_u32_e32 v0, v0, v1
	v_sub_u32_e32 v4, 0, v0
	v_mul_f32_e32 v2, 0x4f7ffffe, v2
	v_cvt_u32_f32_e32 v2, v2
	v_max_i32_e32 v4, v0, v4
	v_xor_b32_e32 v1, v0, v3
	v_ashrrev_i32_e32 v1, 31, v1
	v_mul_lo_u32 v6, v6, v2
	v_mul_hi_u32 v6, v2, v6
	v_add_u32_e32 v2, v2, v6
	v_mul_hi_u32 v2, v4, v2
	v_mul_lo_u32 v6, v2, v5
	v_sub_u32_e32 v4, v4, v6
	v_add_u32_e32 v6, 1, v2
	v_cmp_ge_u32_e64 s[38:39], v4, v5
	v_ashrrev_i32_e32 v27, 31, v17
	s_waitcnt lgkmcnt(0)
	v_mul_lo_u32 v25, v25, v17
	v_cndmask_b32_e64 v2, v2, v6, s[38:39]
	v_sub_u32_e32 v6, v4, v5
	v_cndmask_b32_e64 v4, v4, v6, s[38:39]
	v_add_u32_e32 v6, 1, v2
	v_cmp_ge_u32_e64 s[38:39], v4, v5
	v_bfe_u32 v42, v16, 2, 6
	s_lshl_b32 s31, s25, 1
	v_cndmask_b32_e64 v2, v2, v6, s[38:39]
	v_xor_b32_e32 v2, v2, v1
	v_sub_u32_e32 v1, v2, v1
	v_lshlrev_b32_e32 v28, 6, v1
	v_mul_lo_u32 v1, v1, v3
	v_sub_u32_e32 v0, v0, v1
	v_lshlrev_b32_e32 v30, 6, v0
	v_mul_lo_u32 v2, v22, v27
	v_mul_lo_u32 v3, v23, v17
	v_mad_u64_u32 v[0:1], s[14:15], v22, v17, 0
	v_add3_u32 v1, v1, v2, v3
	v_lshl_add_u64 v[0:1], v[0:1], 2, v[18:19]
	v_mad_i64_i32 v[2:3], s[14:15], v30, v41, 0
	v_ashrrev_i32_e32 v29, 31, v28
	v_lshl_add_u64 v[0:1], v[2:3], 2, v[0:1]
	v_lshl_add_u64 v[0:1], v[28:29], 2, v[0:1]
	v_lshl_add_u64 v[8:9], v[0:1], 0, v[192:193]
	v_mad_i64_i32 v[0:1], s[14:15], v41, v38, 0
	v_mad_i64_i32 v[2:3], s[14:15], v41, v36, 0
	v_lshl_add_u64 v[0:1], v[0:1], 2, v[8:9]
	v_lshl_add_u64 v[4:5], v[2:3], 2, v[8:9]
	v_lshl_add_u64 v[10:11], v[10:11], 2, v[8:9]
	v_lshl_add_u64 v[12:13], v[12:13], 2, v[8:9]
	flat_load_dwordx4 v[0:3], v[0:1] nt
	s_nop 0
	flat_load_dwordx4 v[4:7], v[4:5] nt
	s_nop 0
	flat_load_dwordx4 v[8:11], v[10:11] nt
	s_nop 0
	flat_load_dwordx4 v[12:15], v[12:13] nt
	v_mul_lo_u32 v23, v24, v27
	v_mad_u64_u32 v[18:19], s[14:15], v24, v17, 0
	v_add3_u32 v19, v19, v23, v25
	v_lshl_add_u64 v[18:19], v[18:19], 1, v[20:21]
	v_mad_i64_i32 v[20:21], s[14:15], v28, v40, 0
	v_lshl_add_u64 v[18:19], v[20:21], 1, v[18:19]
	v_ashrrev_i32_e32 v31, 31, v30
	v_lshl_add_u64 v[44:45], v[30:31], 1, v[18:19]
	v_lshlrev_b32_e32 v18, 4, v16
	v_and_b32_e32 v18, 48, v18
	v_mul_i32_i24_e32 v22, 0x4100, v33
	v_and_b32_e32 v16, 0xfc, v16
	v_mul_u32_u24_e32 v21, 0x41, v18
	v_cndmask_b32_e64 v41, 0, 1, vcc
	v_or_b32_e32 v17, v22, v192
	v_or_b32_e32 v19, v22, v16
	v_mul_u32_u24_e32 v20, 0x104, v32
	v_lshlrev_b32_e32 v21, 2, v21
	v_add_u32_e32 v35, v19, v21
	v_add3_u32 v37, v22, v21, v16
	v_lshlrev_b32_e32 v192, 2, v26
	v_add_u32_e32 v39, v17, v20
	v_lshlrev_b32_e32 v46, 1, v18
	v_mov_b32_e32 v43, v41
	v_mov_b64_e32 v[50:51], v[44:45]
	s_branch .LBB0_2534

; DI int otid() { int t = threadIdx.x; asm volatile("" : "+v"(t)); return t; }
; DI int obid() { int t = blockIdx.x; asm volatile("" : "+s"(t)); return t; }
; DI int ogrid() { int t = gridDim.x; asm volatile("" : "+s"(t)); return t; }
; DI CvTile cv_tile(const Job* jobs, int t, int c0, int c1) {
;   CvTile r; r.valid = t < c1; r.pad = 0;
;   int j = 0, tt = r.valid ? t : c0;
;   while (tt >= jobs[j].tiles) { tt -= jobs[j].tiles; ++j; }
;   const Job jb = jobs[j];
;   const int tk = jb.K >> 6, tn = jb.N >> 6, per = tk * tn;
;   const int bi = tt / per, rr = tt % per, kt = rr % tk, nt = rr / tk;
;   r.src = jb.src + (size_t)bi * jb.ss + (size_t)(kt * 64) * jb.N + nt * 64;
;   r.dst = jb.dst + (size_t)bi * jb.ds + (size_t)(nt * 64) * jb.K + kt * 64;
;   r.N = jb.N; r.K = jb.K;
;   return r;
; }
;   if (c0 >= c1) return;
;   const int tid = otid(), G = widx < 0 ? ogrid() : wn, b = widx < 0 ? obid() : widx;
;   float* smf = (float*)smraw;
;   const int half = tid >> 8, vt = tid & 255;
;   float* smh = smf + half * (64 * 65);
;   const int kr = vt >> 4, nc = (vt & 15) * 4;
;   int t0 = c0 + b * 2;
;   if (t0 >= c1) { __syncthreads(); return; }
;   CvTile cur = cv_tile(g_jobs, t0 + half, c0, c1);
;   float4 v[4];
; #pragma unroll
;   for (int i = 0; i < 4; ++i) v[i] = *(const float4*)(cur.src + (size_t)(kr + 16 * i) * cur.N + nc);
.LBB0_2705:
	s_or_b64 exec, exec, s[0:1]
	ds_read_b64 v[40:41], v1 offset:16
	ds_read2_b64 v[18:21], v1 offset1:1
	v_lshlrev_b32_e32 v2, 2, v16
	v_and_b32_e32 v26, 60, v2
	v_sub_u32_e32 v6, 0, v0
	s_waitcnt lgkmcnt(1)
	v_ashrrev_i32_e32 v2, 6, v41
	v_ashrrev_i32_e32 v3, 6, v40
	v_mul_lo_u32 v2, v3, v2
	v_sub_u32_e32 v4, 0, v2
	v_max_i32_e32 v4, v2, v4
	v_cvt_f32_u32_e32 v5, v4
	v_sub_u32_e32 v7, 0, v4
	v_max_i32_e32 v6, v0, v6
	ds_read2_b64 v[22:25], v1 offset0:4 offset1:5
	v_rcp_iflag_f32_e32 v5, v5
	v_xor_b32_e32 v1, v0, v2
	v_ashrrev_i32_e32 v1, 31, v1
	v_bfe_u32 v32, v16, 4, 4
	v_mul_f32_e32 v5, 0x4f7ffffe, v5
	v_cvt_u32_f32_e32 v5, v5
	v_or_b32_e32 v34, 16, v32
	v_or_b32_e32 v36, 32, v32
	v_or_b32_e32 v38, 48, v32
	v_mul_lo_u32 v7, v7, v5
	v_mul_hi_u32 v7, v5, v7
	v_add_u32_e32 v5, v5, v7
	v_mul_hi_u32 v5, v6, v5
	v_mul_lo_u32 v7, v5, v4
	v_sub_u32_e32 v6, v6, v7
	v_add_u32_e32 v7, 1, v5
	v_cmp_ge_u32_e64 s[38:39], v6, v4
	v_lshlrev_b32_e32 v192, 2, v26
	v_mad_i64_i32 v[10:11], s[0:1], v41, v34, 0
	v_cndmask_b32_e64 v5, v5, v7, s[38:39]
	v_sub_u32_e32 v7, v6, v4
	v_cndmask_b32_e64 v6, v6, v7, s[38:39]
	v_add_u32_e32 v7, 1, v5
	v_cmp_ge_u32_e64 s[38:39], v6, v4
	v_mad_i64_i32 v[12:13], s[0:1], v41, v32, 0
	s_nop 0
	v_cndmask_b32_e64 v4, v5, v7, s[38:39]
	v_sub_u32_e32 v5, 0, v3
	v_max_i32_e32 v5, v3, v5
	v_cvt_f32_u32_e32 v6, v5
	v_xor_b32_e32 v4, v4, v1
	v_sub_u32_e32 v17, v4, v1
	v_mul_lo_u32 v1, v17, v2
	v_rcp_iflag_f32_e32 v2, v6
	v_sub_u32_e32 v6, 0, v5
	v_sub_u32_e32 v0, v0, v1
	v_sub_u32_e32 v4, 0, v0
	v_mul_f32_e32 v2, 0x4f7ffffe, v2
	v_cvt_u32_f32_e32 v2, v2
	v_max_i32_e32 v4, v0, v4
	v_xor_b32_e32 v1, v0, v3
	v_ashrrev_i32_e32 v1, 31, v1
	v_mul_lo_u32 v6, v6, v2
	v_mul_hi_u32 v6, v2, v6
	v_add_u32_e32 v2, v2, v6
	v_mul_hi_u32 v2, v4, v2
	v_mul_lo_u32 v6, v2, v5
	v_sub_u32_e32 v4, v4, v6
	v_add_u32_e32 v6, 1, v2
	v_cmp_ge_u32_e64 s[38:39], v4, v5
	v_ashrrev_i32_e32 v27, 31, v17
	s_waitcnt lgkmcnt(0)
	v_mul_lo_u32 v25, v25, v17
	v_cndmask_b32_e64 v2, v2, v6, s[38:39]
	v_sub_u32_e32 v6, v4, v5
	v_cndmask_b32_e64 v4, v4, v6, s[38:39]
	v_add_u32_e32 v6, 1, v2
	v_cmp_ge_u32_e64 s[38:39], v4, v5
	v_bfe_u32 v42, v16, 2, 6
	s_lshl_b32 s17, s14, 1
	v_cndmask_b32_e64 v2, v2, v6, s[38:39]
	v_xor_b32_e32 v2, v2, v1
	v_sub_u32_e32 v1, v2, v1
	v_lshlrev_b32_e32 v28, 6, v1
	v_mul_lo_u32 v1, v1, v3
	v_sub_u32_e32 v0, v0, v1
	v_lshlrev_b32_e32 v30, 6, v0
	v_mul_lo_u32 v2, v22, v27
	v_mul_lo_u32 v3, v23, v17
	v_mad_u64_u32 v[0:1], s[0:1], v22, v17, 0
	v_add3_u32 v1, v1, v2, v3
	v_lshl_add_u64 v[0:1], v[0:1], 2, v[18:19]
	v_mad_i64_i32 v[2:3], s[0:1], v30, v41, 0
	v_ashrrev_i32_e32 v29, 31, v28
	v_lshl_add_u64 v[0:1], v[2:3], 2, v[0:1]
	v_lshl_add_u64 v[0:1], v[28:29], 2, v[0:1]
	v_lshl_add_u64 v[8:9], v[0:1], 0, v[192:193]
	v_mad_i64_i32 v[0:1], s[0:1], v41, v38, 0
	v_mad_i64_i32 v[2:3], s[0:1], v41, v36, 0
	v_lshl_add_u64 v[0:1], v[0:1], 2, v[8:9]
	v_lshl_add_u64 v[4:5], v[2:3], 2, v[8:9]
	v_lshl_add_u64 v[10:11], v[10:11], 2, v[8:9]
	v_lshl_add_u64 v[12:13], v[12:13], 2, v[8:9]
	flat_load_dwordx4 v[0:3], v[0:1] nt
	s_nop 0
	flat_load_dwordx4 v[4:7], v[4:5] nt
	s_nop 0
	flat_load_dwordx4 v[8:11], v[10:11] nt
	s_nop 0
	flat_load_dwordx4 v[12:15], v[12:13] nt
	v_mul_lo_u32 v23, v24, v27
	v_mad_u64_u32 v[18:19], s[0:1], v24, v17, 0
	v_add3_u32 v19, v19, v23, v25
	v_lshl_add_u64 v[18:19], v[18:19], 1, v[20:21]
	v_mad_i64_i32 v[20:21], s[0:1], v28, v40, 0
	v_lshl_add_u64 v[18:19], v[20:21], 1, v[18:19]
	v_ashrrev_i32_e32 v31, 31, v30
	v_lshl_add_u64 v[44:45], v[30:31], 1, v[18:19]
	v_lshlrev_b32_e32 v18, 4, v16
	v_and_b32_e32 v18, 48, v18
	v_mul_i32_i24_e32 v22, 0x4100, v33
	v_and_b32_e32 v16, 0xfc, v16
	v_mul_u32_u24_e32 v21, 0x41, v18
	v_cndmask_b32_e64 v41, 0, 1, vcc
	v_or_b32_e32 v17, v22, v192
	v_or_b32_e32 v19, v22, v16
	v_mul_u32_u24_e32 v20, 0x104, v32
	v_lshlrev_b32_e32 v21, 2, v21
	v_add_u32_e32 v35, v19, v21
	v_add3_u32 v37, v22, v21, v16
	v_lshlrev_b32_e32 v192, 2, v26
	v_add_u32_e32 v39, v17, v20
	v_lshlrev_b32_e32 v46, 1, v18
	v_mov_b32_e32 v43, v41
	v_mov_b64_e32 v[50:51], v[44:45]
	s_branch .LBB0_2707

; DI int otid() { int t = threadIdx.x; asm volatile("" : "+v"(t)); return t; }
; DI int obid() { int t = blockIdx.x; asm volatile("" : "+s"(t)); return t; }
; DI int ogrid() { int t = gridDim.x; asm volatile("" : "+s"(t)); return t; }
; DI unsigned pack2(float a, float b) { unsigned r; asm("v_cvt_pk_bf16_f32 %0, %1, %2" : "=v"(r) : "v"(a), "v"(b)); return r; }
; DI CvTile cv_tile(const Job* jobs, int t, int c0, int c1) {
;     ...
;   while (tt >= jobs[j].tiles) { tt -= jobs[j].tiles; ++j; }
;   const Job jb = jobs[j];
;   const int tk = jb.K >> 6, tn = jb.N >> 6, per = tk * tn;
;   const int bi = tt / per, rr = tt % per, kt = rr % tk, nt = rr / tk;
;   r.src = jb.src + (size_t)bi * jb.ss + (size_t)(kt * 64) * jb.N + nt * 64;
;   r.dst = jb.dst + (size_t)bi * jb.ds + (size_t)(nt * 64) * jb.K + kt * 64;
;   r.N = jb.N; r.K = jb.K;
;   return r;
; }
;   if (c0 >= c1) return;
;   const int tid = otid(), G = widx < 0 ? ogrid() : wn, b = widx < 0 ? obid() : widx;
;   float* smf = (float*)smraw;
;   const int half = tid >> 8, vt = tid & 255;
;   float* smh = smf + half * (64 * 65);
;   const int kr = vt >> 4, nc = (vt & 15) * 4;
;   int t0 = c0 + b * 2;
;   if (t0 >= c1) { __syncthreads(); return; }
;   CvTile cur = cv_tile(g_jobs, t0 + half, c0, c1);
;   float4 v[4];
; #pragma unroll
;   for (int i = 0; i < 4; ++i) v[i] = *(const float4*)(cur.src + (size_t)(kr + 16 * i) * cur.N + nc);
;   for (; t0 < c1; t0 += 2 * G) {
;     const bool more = t0 + 2 * G < c1;
;     CvTile nx = cur; float4 vn[4];
;     if (more) {
;       nx = cv_tile(g_jobs, t0 + 2 * G + half, c0, c1);
; #pragma unroll
;       for (int i = 0; i < 4; ++i) vn[i] = *(const float4*)(nx.src + (size_t)(kr + 16 * i) * nx.N + nc);
;     }
;     __syncthreads();
; #pragma unroll
;     for (int i = 0; i < 4; ++i) { float* d = smh + (kr + 16 * i) * 65 + nc; d[0] = v[i].x; d[1] = v[i].y; d[2] = v[i].z; d[3] = v[i].w; }
;     __syncthreads();
;     if (cur.valid) {
;       const int n = vt >> 2, kp = (vt & 3) * 16;
;       unsigned o[8];
; #pragma unroll
;       for (int q = 0; q < 8; ++q) o[q] = pack2(smh[(kp + 2 * q) * 65 + n], smh[(kp + 2 * q + 1) * 65 + n]);
;       uint4* d4 = (uint4*)(cur.dst + (size_t)n * cur.K + kp);
;       d4[0] = make_uint4(o[0], o[1], o[2], o[3]); d4[1] = make_uint4(o[4], o[5], o[6], o[7]);
;     }
.LBB0_2712:
	s_or_b64 exec, exec, s[2:3]
	ds_read2_b64 v[16:19], v20 offset1:1
	ds_read_b64 v[48:49], v20 offset:16
	ds_read2_b64 v[20:23], v20 offset0:4 offset1:5
	v_sub_u32_e32 v28, 0, v24
	v_max_i32_e32 v28, v24, v28
	v_cndmask_b32_e64 v43, 0, 1, vcc
	s_waitcnt lgkmcnt(0)
	v_ashrrev_i32_e32 v25, 6, v48
	v_ashrrev_i32_e32 v26, 6, v49
	v_mul_lo_u32 v26, v26, v25
	v_sub_u32_e32 v29, 0, v26
	v_max_i32_e32 v29, v26, v29
	v_cvt_f32_u32_e32 v30, v29
	v_sub_u32_e32 v31, 0, v29
	v_xor_b32_e32 v27, v24, v26
	v_ashrrev_i32_e32 v27, 31, v27
	v_rcp_iflag_f32_e32 v30, v30
	s_nop 0
	v_mul_f32_e32 v30, 0x4f7ffffe, v30
	v_cvt_u32_f32_e32 v30, v30
	v_mul_lo_u32 v31, v31, v30
	v_mul_hi_u32 v31, v30, v31
	v_add_u32_e32 v30, v30, v31
	v_mul_hi_u32 v30, v28, v30
	v_mul_lo_u32 v31, v30, v29
	v_sub_u32_e32 v28, v28, v31
	v_cmp_ge_u32_e64 s[38:39], v28, v29
	v_add_u32_e32 v31, 1, v30
	s_nop 0
	v_cndmask_b32_e64 v30, v30, v31, s[38:39]
	v_sub_u32_e32 v31, v28, v29
	v_cndmask_b32_e64 v28, v28, v31, s[38:39]
	v_cmp_ge_u32_e64 s[38:39], v28, v29
	v_sub_u32_e32 v29, 0, v25
	v_add_u32_e32 v28, 1, v30
	v_max_i32_e32 v29, v25, v29
	v_cndmask_b32_e64 v28, v30, v28, s[38:39]
	v_cvt_f32_u32_e32 v30, v29
	v_xor_b32_e32 v28, v28, v27
	v_sub_u32_e32 v27, v28, v27
	v_mul_lo_u32 v26, v27, v26
	v_rcp_iflag_f32_e32 v30, v30
	v_sub_u32_e32 v31, 0, v29
	v_sub_u32_e32 v24, v24, v26
	v_sub_u32_e32 v28, 0, v24
	v_mul_f32_e32 v30, 0x4f7ffffe, v30
	v_cvt_u32_f32_e32 v30, v30
	v_max_i32_e32 v28, v24, v28
	v_xor_b32_e32 v26, v24, v25
	v_ashrrev_i32_e32 v26, 31, v26
	v_mul_lo_u32 v31, v31, v30
	v_mul_hi_u32 v31, v30, v31
	v_add_u32_e32 v30, v30, v31
	v_mul_hi_u32 v30, v28, v30
	v_mul_lo_u32 v31, v30, v29
	v_sub_u32_e32 v28, v28, v31
	v_cmp_ge_u32_e64 s[38:39], v28, v29
	v_add_u32_e32 v31, 1, v30
	s_nop 0
	v_cndmask_b32_e64 v30, v30, v31, s[38:39]
	v_sub_u32_e32 v31, v28, v29
	v_cndmask_b32_e64 v28, v28, v31, s[38:39]
	v_cmp_ge_u32_e64 s[38:39], v28, v29
	v_add_u32_e32 v28, 1, v30
	v_mul_lo_u32 v29, v21, v27
	v_cndmask_b32_e64 v28, v30, v28, s[38:39]
	v_xor_b32_e32 v28, v28, v26
	v_sub_u32_e32 v26, v28, v26
	v_mul_lo_u32 v25, v26, v25
	v_sub_u32_e32 v24, v24, v25
	v_ashrrev_i32_e32 v25, 31, v27
	v_mul_lo_u32 v28, v20, v25
	v_mad_u64_u32 v[20:21], s[2:3], v20, v27, 0
	v_add3_u32 v21, v21, v28, v29
	v_lshlrev_b32_e32 v50, 6, v24
	v_lshl_add_u64 v[16:17], v[20:21], 2, v[16:17]
	v_mad_i64_i32 v[20:21], s[2:3], v50, v49, 0
	v_lshl_add_u64 v[16:17], v[20:21], 2, v[16:17]
	v_lshlrev_b32_e32 v20, 6, v26
	v_ashrrev_i32_e32 v21, 31, v20
	v_lshl_add_u64 v[16:17], v[20:21], 2, v[16:17]
	v_mul_lo_u32 v21, v22, v25
	v_mul_lo_u32 v24, v23, v27
	v_mad_u64_u32 v[22:23], s[2:3], v22, v27, 0
	v_add3_u32 v23, v23, v21, v24
	v_lshl_add_u64 v[18:19], v[22:23], 1, v[18:19]
	v_mad_i64_i32 v[20:21], s[2:3], v20, v48, 0
	v_lshl_add_u64 v[52:53], v[20:21], 1, v[18:19]
	v_lshl_add_u64 v[28:29], v[16:17], 0, v[192:193]
	v_mad_i64_i32 v[16:17], s[2:3], v49, v32, 0
	v_mad_i64_i32 v[20:21], s[2:3], v49, v34, 0
	v_mad_i64_i32 v[24:25], s[2:3], v49, v36, 0
	v_mad_i64_i32 v[30:31], s[2:3], v49, v38, 0
	v_lshl_add_u64 v[16:17], v[16:17], 2, v[28:29]
	v_lshl_add_u64 v[20:21], v[20:21], 2, v[28:29]
	v_lshl_add_u64 v[24:25], v[24:25], 2, v[28:29]
	v_lshl_add_u64 v[28:29], v[30:31], 2, v[28:29]
	flat_load_dwordx4 v[16:19], v[16:17] nt
	v_ashrrev_i32_e32 v51, 31, v50
	flat_load_dwordx4 v[20:23], v[20:21] nt
	v_lshl_add_u64 v[50:51], v[50:51], 1, v[52:53]
	flat_load_dwordx4 v[24:27], v[24:25] nt
	s_nop 0
	flat_load_dwordx4 v[28:31], v[28:29] nt
.LBB0_2713:
	s_waitcnt lgkmcnt(0)
	s_barrier
	s_waitcnt vmcnt(0)
	ds_write2_b32 v39, v12, v13 offset1:1
	ds_write2_b32 v39, v14, v15 offset0:2 offset1:3
	v_add_u32_e32 v12, 0x1040, v39
	ds_write2_b32 v12, v8, v9 offset1:1
	v_add_u32_e32 v8, 0x1048, v39
	ds_write2_b32 v8, v10, v11 offset1:1
	v_add_u32_e32 v8, 0x2080, v39
	ds_write2_b32 v8, v4, v5 offset1:1
	v_add_u32_e32 v4, 0x2088, v39
	ds_write2_b32 v4, v6, v7 offset1:1
	v_add_u32_e32 v4, 0x30c0, v39
	ds_write2_b32 v4, v0, v1 offset1:1
	v_add_u32_e32 v0, 0x30c8, v39
	v_cmp_ne_u32_e32 vcc, 0, v41
	ds_write2_b32 v0, v2, v3 offset1:1
	s_waitcnt lgkmcnt(0)
	s_barrier
	s_and_saveexec_b64 s[2:3], vcc
	s_cbranch_execz .LBB0_2706
	ds_read2_b32 v[0:1], v35 offset1:130
	ds_read2_b32 v[2:3], v37 offset0:65 offset1:195
	v_add_u32_e32 v4, 0x400, v37
	ds_read2_b32 v[4:5], v4 offset0:69 offset1:199
	v_add_u32_e32 v6, 0x800, v37
	ds_read2_b32 v[6:7], v6 offset0:73 offset1:203
	s_waitcnt lgkmcnt(2)
	v_cvt_pk_bf16_f32 v0, v0, v2
	v_add_u32_e32 v2, 0x400, v35
	v_cvt_pk_bf16_f32 v1, v1, v3
	ds_read2_b32 v[2:3], v2 offset0:4 offset1:134
	s_waitcnt lgkmcnt(0)
	v_cvt_pk_bf16_f32 v2, v2, v4
	v_add_u32_e32 v4, 0x800, v35
	v_cvt_pk_bf16_f32 v3, v3, v5
	ds_read2_b32 v[4:5], v4 offset0:8 offset1:138
	s_waitcnt lgkmcnt(0)
	v_cvt_pk_bf16_f32 v4, v4, v6
	v_add_u32_e32 v6, 0xc00, v35
	v_add_u32_e32 v8, 0xc00, v37
	v_cvt_pk_bf16_f32 v5, v5, v7
	ds_read2_b32 v[6:7], v6 offset0:12 offset1:142
	ds_read2_b32 v[8:9], v8 offset0:77 offset1:207
	s_waitcnt lgkmcnt(0)
	v_cvt_pk_bf16_f32 v6, v6, v8
	v_cvt_pk_bf16_f32 v7, v7, v9
	v_mad_i64_i32 v[8:9], s[14:15], v40, v42, 0
	v_lshl_add_u64 v[8:9], v[8:9], 1, v[44:45]
	v_mov_b32_e32 v47, v193
	v_lshl_add_u64 v[8:9], v[8:9], 0, v[46:47]
	flat_store_dwordx4 v[8:9], v[0:3] nt
	flat_store_dwordx4 v[8:9], v[4:7] offset:16 nt
	s_branch .LBB0_2706

; DI int otid() { int t = threadIdx.x; asm volatile("" : "+v"(t)); return t; }
; DI int obid() { int t = blockIdx.x; asm volatile("" : "+s"(t)); return t; }
; DI int ogrid() { int t = gridDim.x; asm volatile("" : "+s"(t)); return t; }
; DI CvTile cv_tile(const Job* jobs, int t, int c0, int c1) {
;   CvTile r; r.valid = t < c1; r.pad = 0;
;   int j = 0, tt = r.valid ? t : c0;
;   while (tt >= jobs[j].tiles) { tt -= jobs[j].tiles; ++j; }
;   const Job jb = jobs[j];
;   const int tk = jb.K >> 6, tn = jb.N >> 6, per = tk * tn;
;   const int bi = tt / per, rr = tt % per, kt = rr % tk, nt = rr / tk;
;   r.src = jb.src + (size_t)bi * jb.ss + (size_t)(kt * 64) * jb.N + nt * 64;
;   r.dst = jb.dst + (size_t)bi * jb.ds + (size_t)(nt * 64) * jb.K + kt * 64;
;   r.N = jb.N; r.K = jb.K;
;   return r;
; }
;   if (c0 >= c1) return;
;   const int tid = otid(), G = widx < 0 ? ogrid() : wn, b = widx < 0 ? obid() : widx;
;   float* smf = (float*)smraw;
;   const int half = tid >> 8, vt = tid & 255;
;   float* smh = smf + half * (64 * 65);
;   const int kr = vt >> 4, nc = (vt & 15) * 4;
;   int t0 = c0 + b * 2;
;   if (t0 >= c1) { __syncthreads(); return; }
;   CvTile cur = cv_tile(g_jobs, t0 + half, c0, c1);
;   float4 v[4];
; #pragma unroll
;   for (int i = 0; i < 4; ++i) v[i] = *(const float4*)(cur.src + (size_t)(kr + 16 * i) * cur.N + nc);
.LBB0_2722:
	s_or_b64 exec, exec, s[0:1]
	ds_read_b64 v[40:41], v1 offset:16
	ds_read2_b64 v[18:21], v1 offset1:1
	v_lshlrev_b32_e32 v2, 2, v16
	v_and_b32_e32 v26, 60, v2
	v_sub_u32_e32 v6, 0, v0
	s_waitcnt lgkmcnt(1)
	v_ashrrev_i32_e32 v2, 6, v41
	v_ashrrev_i32_e32 v3, 6, v40
	v_mul_lo_u32 v2, v3, v2
	v_sub_u32_e32 v4, 0, v2
	v_max_i32_e32 v4, v2, v4
	v_cvt_f32_u32_e32 v5, v4
	v_sub_u32_e32 v7, 0, v4
	v_max_i32_e32 v6, v0, v6
	ds_read2_b64 v[22:25], v1 offset0:4 offset1:5
	v_rcp_iflag_f32_e32 v5, v5
	v_xor_b32_e32 v1, v0, v2
	v_ashrrev_i32_e32 v1, 31, v1
	v_bfe_u32 v32, v16, 4, 4
	v_mul_f32_e32 v5, 0x4f7ffffe, v5
	v_cvt_u32_f32_e32 v5, v5
	v_or_b32_e32 v34, 16, v32
	v_or_b32_e32 v36, 32, v32
	v_or_b32_e32 v38, 48, v32
	v_mul_lo_u32 v7, v7, v5
	v_mul_hi_u32 v7, v5, v7
	v_add_u32_e32 v5, v5, v7
	v_mul_hi_u32 v5, v6, v5
	v_mul_lo_u32 v7, v5, v4
	v_sub_u32_e32 v6, v6, v7
	v_add_u32_e32 v7, 1, v5
	v_cmp_ge_u32_e64 s[38:39], v6, v4
	v_lshlrev_b32_e32 v192, 2, v26
	v_mad_i64_i32 v[10:11], s[0:1], v41, v34, 0
	v_cndmask_b32_e64 v5, v5, v7, s[38:39]
	v_sub_u32_e32 v7, v6, v4
	v_cndmask_b32_e64 v6, v6, v7, s[38:39]
	v_add_u32_e32 v7, 1, v5
	v_cmp_ge_u32_e64 s[38:39], v6, v4
	v_mad_i64_i32 v[12:13], s[0:1], v41, v32, 0
	s_nop 0
	v_cndmask_b32_e64 v4, v5, v7, s[38:39]
	v_sub_u32_e32 v5, 0, v3
	v_max_i32_e32 v5, v3, v5
	v_cvt_f32_u32_e32 v6, v5
	v_xor_b32_e32 v4, v4, v1
	v_sub_u32_e32 v17, v4, v1
	v_mul_lo_u32 v1, v17, v2
	v_rcp_iflag_f32_e32 v2, v6
	v_sub_u32_e32 v6, 0, v5
	v_sub_u32_e32 v0, v0, v1
	v_sub_u32_e32 v4, 0, v0
	v_mul_f32_e32 v2, 0x4f7ffffe, v2
	v_cvt_u32_f32_e32 v2, v2
	v_max_i32_e32 v4, v0, v4
	v_xor_b32_e32 v1, v0, v3
	v_ashrrev_i32_e32 v1, 31, v1
	v_mul_lo_u32 v6, v6, v2
	v_mul_hi_u32 v6, v2, v6
	v_add_u32_e32 v2, v2, v6
	v_mul_hi_u32 v2, v4, v2
	v_mul_lo_u32 v6, v2, v5
	v_sub_u32_e32 v4, v4, v6
	v_add_u32_e32 v6, 1, v2
	v_cmp_ge_u32_e64 s[38:39], v4, v5
	v_ashrrev_i32_e32 v27, 31, v17
	s_waitcnt lgkmcnt(0)
	v_mul_lo_u32 v25, v25, v17
	v_cndmask_b32_e64 v2, v2, v6, s[38:39]
	v_sub_u32_e32 v6, v4, v5
	v_cndmask_b32_e64 v4, v4, v6, s[38:39]
	v_add_u32_e32 v6, 1, v2
	v_cmp_ge_u32_e64 s[38:39], v4, v5
	v_bfe_u32 v42, v16, 2, 6
	s_lshl_b32 s31, s16, 1
	v_cndmask_b32_e64 v2, v2, v6, s[38:39]
	v_xor_b32_e32 v2, v2, v1
	v_sub_u32_e32 v1, v2, v1
	v_lshlrev_b32_e32 v28, 6, v1
	v_mul_lo_u32 v1, v1, v3
	v_sub_u32_e32 v0, v0, v1
	v_lshlrev_b32_e32 v30, 6, v0
	v_mul_lo_u32 v2, v22, v27
	v_mul_lo_u32 v3, v23, v17
	v_mad_u64_u32 v[0:1], s[0:1], v22, v17, 0
	v_add3_u32 v1, v1, v2, v3
	v_lshl_add_u64 v[0:1], v[0:1], 2, v[18:19]
	v_mad_i64_i32 v[2:3], s[0:1], v30, v41, 0
	v_ashrrev_i32_e32 v29, 31, v28
	v_lshl_add_u64 v[0:1], v[2:3], 2, v[0:1]
	v_lshl_add_u64 v[0:1], v[28:29], 2, v[0:1]
	v_lshl_add_u64 v[8:9], v[0:1], 0, v[192:193]
	v_mad_i64_i32 v[0:1], s[0:1], v41, v38, 0
	v_mad_i64_i32 v[2:3], s[0:1], v41, v36, 0
	v_lshl_add_u64 v[0:1], v[0:1], 2, v[8:9]
	v_lshl_add_u64 v[4:5], v[2:3], 2, v[8:9]
	v_lshl_add_u64 v[10:11], v[10:11], 2, v[8:9]
	v_lshl_add_u64 v[12:13], v[12:13], 2, v[8:9]
	flat_load_dwordx4 v[0:3], v[0:1] nt
	s_nop 0
	flat_load_dwordx4 v[4:7], v[4:5] nt
	s_nop 0
	flat_load_dwordx4 v[8:11], v[10:11] nt
	s_nop 0
	flat_load_dwordx4 v[12:15], v[12:13] nt
	v_mul_lo_u32 v23, v24, v27
	v_mad_u64_u32 v[18:19], s[0:1], v24, v17, 0
	v_add3_u32 v19, v19, v23, v25
	v_lshl_add_u64 v[18:19], v[18:19], 1, v[20:21]
	v_mad_i64_i32 v[20:21], s[0:1], v28, v40, 0
	v_lshl_add_u64 v[18:19], v[20:21], 1, v[18:19]
	v_ashrrev_i32_e32 v31, 31, v30
	v_lshl_add_u64 v[44:45], v[30:31], 1, v[18:19]
	v_lshlrev_b32_e32 v18, 4, v16
	v_and_b32_e32 v18, 48, v18
	v_mul_i32_i24_e32 v22, 0x4100, v33
	v_and_b32_e32 v16, 0xfc, v16
	v_mul_u32_u24_e32 v21, 0x41, v18
	v_cndmask_b32_e64 v41, 0, 1, vcc
	v_or_b32_e32 v17, v22, v192
	v_or_b32_e32 v19, v22, v16
	v_mul_u32_u24_e32 v20, 0x104, v32
	v_lshlrev_b32_e32 v21, 2, v21
	v_add_u32_e32 v35, v19, v21
	v_add3_u32 v37, v22, v21, v16
	v_lshlrev_b32_e32 v192, 2, v26
	v_add_u32_e32 v39, v17, v20
	v_lshlrev_b32_e32 v46, 1, v18
	v_mov_b32_e32 v43, v41
	v_mov_b64_e32 v[50:51], v[44:45]
	s_branch .LBB0_2724

; DI int otid() { int t = threadIdx.x; asm volatile("" : "+v"(t)); return t; }
; DI int obid() { int t = blockIdx.x; asm volatile("" : "+s"(t)); return t; }
; DI int ogrid() { int t = gridDim.x; asm volatile("" : "+s"(t)); return t; }
; DI CvTile cv_tile(const Job* jobs, int t, int c0, int c1) {
;   CvTile r; r.valid = t < c1; r.pad = 0;
;   int j = 0, tt = r.valid ? t : c0;
;   while (tt >= jobs[j].tiles) { tt -= jobs[j].tiles; ++j; }
;   const Job jb = jobs[j];
;   const int tk = jb.K >> 6, tn = jb.N >> 6, per = tk * tn;
;   const int bi = tt / per, rr = tt % per, kt = rr % tk, nt = rr / tk;
;   r.src = jb.src + (size_t)bi * jb.ss + (size_t)(kt * 64) * jb.N + nt * 64;
;   r.dst = jb.dst + (size_t)bi * jb.ds + (size_t)(nt * 64) * jb.K + kt * 64;
;   r.N = jb.N; r.K = jb.K;
;   return r;
; }
;   if (c0 >= c1) return;
;   const int tid = otid(), G = widx < 0 ? ogrid() : wn, b = widx < 0 ? obid() : widx;
;   float* smf = (float*)smraw;
;   const int half = tid >> 8, vt = tid & 255;
;   float* smh = smf + half * (64 * 65);
;   const int kr = vt >> 4, nc = (vt & 15) * 4;
;   int t0 = c0 + b * 2;
;   if (t0 >= c1) { __syncthreads(); return; }
;   CvTile cur = cv_tile(g_jobs, t0 + half, c0, c1);
;   float4 v[4];
; #pragma unroll
;   for (int i = 0; i < 4; ++i) v[i] = *(const float4*)(cur.src + (size_t)(kr + 16 * i) * cur.N + nc);
.LBB0_2745:
	s_or_b64 exec, exec, s[0:1]
	ds_read_b64 v[40:41], v1 offset:16
	ds_read2_b64 v[18:21], v1 offset1:1
	v_lshlrev_b32_e32 v2, 2, v16
	v_and_b32_e32 v26, 60, v2
	v_sub_u32_e32 v6, 0, v0
	s_waitcnt lgkmcnt(0)
	v_ashrrev_i32_e32 v2, 6, v41
	v_ashrrev_i32_e32 v3, 6, v40
	v_mul_lo_u32 v2, v3, v2
	v_sub_u32_e32 v4, 0, v2
	v_max_i32_e32 v4, v2, v4
	v_cvt_f32_u32_e32 v5, v4
	v_sub_u32_e32 v7, 0, v4
	v_max_i32_e32 v6, v0, v6
	ds_read2_b64 v[22:25], v1 offset0:4 offset1:5
	v_rcp_iflag_f32_e32 v5, v5
	v_xor_b32_e32 v1, v0, v2
	v_ashrrev_i32_e32 v1, 31, v1
	v_bfe_u32 v32, v16, 4, 4
	v_mul_f32_e32 v5, 0x4f7ffffe, v5
	v_cvt_u32_f32_e32 v5, v5
	v_or_b32_e32 v34, 16, v32
	v_or_b32_e32 v36, 32, v32
	v_or_b32_e32 v38, 48, v32
	v_mul_lo_u32 v7, v7, v5
	v_mul_hi_u32 v7, v5, v7
	v_add_u32_e32 v5, v5, v7
	v_mul_hi_u32 v5, v6, v5
	v_mul_lo_u32 v7, v5, v4
	v_sub_u32_e32 v6, v6, v7
	v_add_u32_e32 v7, 1, v5
	v_cmp_ge_u32_e64 s[38:39], v6, v4
	v_lshlrev_b32_e32 v192, 2, v26
	v_mad_i64_i32 v[10:11], s[0:1], v41, v34, 0
	v_cndmask_b32_e64 v5, v5, v7, s[38:39]
	v_sub_u32_e32 v7, v6, v4
	v_cndmask_b32_e64 v6, v6, v7, s[38:39]
	v_add_u32_e32 v7, 1, v5
	v_cmp_ge_u32_e64 s[38:39], v6, v4
	v_mad_i64_i32 v[12:13], s[0:1], v41, v32, 0
	s_nop 0
	v_cndmask_b32_e64 v4, v5, v7, s[38:39]
	v_sub_u32_e32 v5, 0, v3
	v_max_i32_e32 v5, v3, v5
	v_cvt_f32_u32_e32 v6, v5
	v_xor_b32_e32 v4, v4, v1
	v_sub_u32_e32 v17, v4, v1
	v_mul_lo_u32 v1, v17, v2
	v_rcp_iflag_f32_e32 v2, v6
	v_sub_u32_e32 v6, 0, v5
	v_sub_u32_e32 v0, v0, v1
	v_sub_u32_e32 v4, 0, v0
	v_mul_f32_e32 v2, 0x4f7ffffe, v2
	v_cvt_u32_f32_e32 v2, v2
	v_max_i32_e32 v4, v0, v4
	v_xor_b32_e32 v1, v0, v3
	v_ashrrev_i32_e32 v1, 31, v1
	v_mul_lo_u32 v6, v6, v2
	v_mul_hi_u32 v6, v2, v6
	v_add_u32_e32 v2, v2, v6
	v_mul_hi_u32 v2, v4, v2
	v_mul_lo_u32 v6, v2, v5
	v_sub_u32_e32 v4, v4, v6
	v_add_u32_e32 v6, 1, v2
	v_cmp_ge_u32_e64 s[38:39], v4, v5
	v_ashrrev_i32_e32 v27, 31, v17
	s_waitcnt lgkmcnt(0)
	v_mul_lo_u32 v25, v25, v17
	v_cndmask_b32_e64 v2, v2, v6, s[38:39]
	v_sub_u32_e32 v6, v4, v5
	v_cndmask_b32_e64 v4, v4, v6, s[38:39]
	v_add_u32_e32 v6, 1, v2
	v_cmp_ge_u32_e64 s[38:39], v4, v5
	v_bfe_u32 v42, v16, 2, 6
	s_lshl_b32 s17, s14, 1
	v_cndmask_b32_e64 v2, v2, v6, s[38:39]
	v_xor_b32_e32 v2, v2, v1
	v_sub_u32_e32 v1, v2, v1
	v_lshlrev_b32_e32 v28, 6, v1
	v_mul_lo_u32 v1, v1, v3
	v_sub_u32_e32 v0, v0, v1
	v_lshlrev_b32_e32 v30, 6, v0
	v_mul_lo_u32 v2, v22, v27
	v_mul_lo_u32 v3, v23, v17
	v_mad_u64_u32 v[0:1], s[0:1], v22, v17, 0
	v_add3_u32 v1, v1, v2, v3
	v_lshl_add_u64 v[0:1], v[0:1], 2, v[18:19]
	v_mad_i64_i32 v[2:3], s[0:1], v30, v41, 0
	v_ashrrev_i32_e32 v29, 31, v28
	v_lshl_add_u64 v[0:1], v[2:3], 2, v[0:1]
	v_lshl_add_u64 v[0:1], v[28:29], 2, v[0:1]
	v_lshl_add_u64 v[8:9], v[0:1], 0, v[192:193]
	v_mad_i64_i32 v[0:1], s[0:1], v41, v38, 0
	v_mad_i64_i32 v[2:3], s[0:1], v41, v36, 0
	v_lshl_add_u64 v[0:1], v[0:1], 2, v[8:9]
	v_lshl_add_u64 v[4:5], v[2:3], 2, v[8:9]
	v_lshl_add_u64 v[10:11], v[10:11], 2, v[8:9]
	v_lshl_add_u64 v[12:13], v[12:13], 2, v[8:9]
	flat_load_dwordx4 v[0:3], v[0:1] nt
	s_nop 0
	flat_load_dwordx4 v[4:7], v[4:5] nt
	s_nop 0
	flat_load_dwordx4 v[8:11], v[10:11] nt
	s_nop 0
	flat_load_dwordx4 v[12:15], v[12:13] nt
	v_mul_lo_u32 v23, v24, v27
	v_mad_u64_u32 v[18:19], s[0:1], v24, v17, 0
	v_add3_u32 v19, v19, v23, v25
	v_lshl_add_u64 v[18:19], v[18:19], 1, v[20:21]
	v_mad_i64_i32 v[20:21], s[0:1], v28, v40, 0
	v_lshl_add_u64 v[18:19], v[20:21], 1, v[18:19]
	v_ashrrev_i32_e32 v31, 31, v30
	v_lshl_add_u64 v[44:45], v[30:31], 1, v[18:19]
	v_lshlrev_b32_e32 v18, 4, v16
	v_and_b32_e32 v18, 48, v18
	v_mul_i32_i24_e32 v22, 0x4100, v33
	v_and_b32_e32 v16, 0xfc, v16
	v_mul_u32_u24_e32 v21, 0x41, v18
	v_cndmask_b32_e64 v41, 0, 1, vcc
	v_or_b32_e32 v17, v22, v192
	v_or_b32_e32 v19, v22, v16
	v_mul_u32_u24_e32 v20, 0x104, v32
	v_lshlrev_b32_e32 v21, 2, v21
	v_add_u32_e32 v35, v19, v21
	v_add3_u32 v37, v22, v21, v16
	v_lshlrev_b32_e32 v192, 2, v26
	v_add_u32_e32 v39, v17, v20
	v_lshlrev_b32_e32 v46, 1, v18
	v_mov_b32_e32 v43, v41
	v_mov_b64_e32 v[50:51], v[44:45]
	s_branch .LBB0_2747
